# first k-tile's LDS-DMA pieces issued before the tile prologue's accumulator zeroing (overlaps their latency with it)
# speedup vs baseline: 1.0009x; 1.0009x over previous
; template <bool SWAP>
; DI void gemm_mainloop(f32x16 (&acc)[4][2], const u16* __restrict__ A, int lda, int rlo, int rhi,
;                       const u16* __restrict__ B, int ldb, int K, char* lds, const u16* zero_line) {
;   const int tid = opaque_tid(), lane = tid & 63, w = tid >> 6;
;   const int wm = w >> 2, wn = w & 3;
;   const int h = lane >> 5, r = lane & 31;
;   const int lr = tid >> 3, lc = tid & 7;
; #pragma unroll
;   for (int mi = 0; mi < 4; ++mi)
; #pragma unroll
;     for (int ni = 0; ni < 2; ++ni)
; #pragma unroll
;       for (int i = 0; i < 16; ++i) acc[mi][ni][i] = 0.f;
;   const int gch = (lc ^ ((lr >> 1) & 7)) * 8;
;   const u16* ap = A + (ptrdiff_t)lr * lda + gch;
;   const u16* bp = B + (ptrdiff_t)lr * ldb + gch;
;   const int nk = K >> 6;
;   typedef __attribute__((address_space(3))) unsigned lds_u32;
;   auto glds = [&](int kt, int st) {
;     char* as_ = lds + st * 65536 + tid * 16;
; #pragma unroll
;     for (int i = 0; i < 4; ++i) {
;       const int rr = lr + 64 * i;
;       const u16* srca = (rr >= rlo && rr < rhi) ? (ap + (ptrdiff_t)(64 * i) * lda + kt * 64) : (zero_line + lc * 8);
;       __builtin_amdgcn_global_load_lds((const unsigned*)srca, (lds_u32*)(as_ + i * 8192), 16, 0, 0);
;       __builtin_amdgcn_global_load_lds((const unsigned*)(bp + (ptrdiff_t)(64 * i) * ldb + kt * 64), (lds_u32*)(as_ + 32768 + i * 8192), 16, 0, 0);
;     }
;   };
;   const int sw = (r >> 1) & 7;
;   const int arow_off = (wm * 128 + r) * 128;
;   const int brow_off = 32768 + (wn * 64 + r) * 128;
;   __syncthreads();
;   glds(0, 0);
;   asm volatile("s_waitcnt vmcnt(0)" ::: "memory");
;   __syncthreads();
; template <int EPI>
; DI void phase_gemm(const Params& p, const GemmArgs& ga, char* lds) {
;     ...
;   for (int it = 0; it * (int)gridDim.x < total; ++it) {
;     const int lt = logical_index(it);
;     if (lt >= total) continue;
;     int mt, nt;
;     tile_mn(lt, Mt, ga.Nt, mt, nt);
;     int bb, tokbase, S, pos0, rlo = 0, rhi = 256;
;     if (EPI == EPI_UP) {
;       bb = 0; tokbase = 0; S = NTOK;
;       pos0 = 254 * mt - 1;
;       rlo = (mt == 0) ? 1 : 0;
;       rhi = NTOK - pos0; if (rhi > 256) rhi = 256;
;     } else {
;       seq_of_token(mt * 256, bb, tokbase, S);
;       pos0 = mt * 256 - tokbase;
;     }
;     const u16* A = ga.A + (ptrdiff_t)(tokbase + pos0) * ga.lda;
;     const u16* B = ga.Bt + (size_t)(nt * 256) * ga.K;
.LBB0_56:
	s_add_i32 s30, s10, s25
	s_cmpk_gt_i32 s30, 0x10ab
	s_cbranch_scc1 .LBB0_55
	s_mul_hi_i32 s10, s30, 0x2e8ba2e9
	s_lshr_b32 s11, s10, 31
	s_ashr_i32 s10, s10, 5
	s_add_i32 s31, s10, s11
	s_lshl_b32 s10, s31, 3
	s_sub_i32 s11, 0xc2, s10
	s_min_u32 s11, s11, 8
	v_cvt_f32_ubyte0_e32 v0, s11
	v_rcp_iflag_f32_e32 v0, v0
	s_sub_i32 s15, 0, s11
	s_mul_i32 s12, s31, 0xffffff50
	s_add_i32 s12, s12, s30
	v_mul_f32_e32 v0, 0x4f7ffffe, v0
	v_cvt_u32_f32_e32 v0, v0
	s_abs_i32 s14, s12
	s_ashr_i32 s13, s12, 31
	s_waitcnt vmcnt(5)
	v_mov_b32_e32 v13, v204
	v_readfirstlane_b32 s16, v0
	s_mul_i32 s15, s15, s16
	s_mul_hi_u32 s15, s16, s15
	s_add_i32 s16, s16, s15
	s_mul_hi_u32 s15, s14, s16
	s_mul_i32 s16, s15, s11
	s_sub_i32 s14, s14, s16
	s_add_i32 s16, s15, 1
	s_sub_i32 s17, s14, s11
	s_cmp_ge_u32 s14, s11
	s_cselect_b32 s15, s16, s15
	s_cselect_b32 s14, s17, s14
	s_add_i32 s16, s15, 1
	s_cmp_ge_u32 s14, s11
	s_cselect_b32 s14, s16, s15
	s_xor_b32 s14, s14, s13
	s_sub_i32 s28, s14, s13
	s_mul_i32 s34, s28, s11
	s_add_i32 s14, s12, s10
	s_sub_i32 s27, s14, s34
	s_mulk_i32 s27, 0xfe
	s_lshl_b32 s10, s28, 8
	s_add_i32 s20, s27, -1
	s_ashr_i32 s11, s10, 31
	s_ashr_i32 s21, s20, 31
	s_lshl_b64 s[22:23], s[10:11], 11
	v_readlane_b32 s10, v253, 17
	v_readlane_b32 s11, v253, 18
	s_add_u32 s10, s10, s22
	s_addc_u32 s11, s11, s23
	s_lshl_b64 s[12:13], s[20:21], 11
	s_add_u32 s12, s90, s12
	v_ashrrev_i32_e32 v2, 3, v13
	s_waitcnt vmcnt(4)
	v_lshrrev_b32_e32 v15, 1, v2
	s_addc_u32 s13, s91, s13
	s_sub_i32 s15, 0xc001, s27
	v_xor_b32_e32 v0, v15, v13
	v_ashrrev_i32_e32 v3, 31, v2
	s_min_i32 s18, s15, 0x100
	v_lshlrev_b64 v[4:5], 11, v[2:3]
	v_lshlrev_b32_e32 v0, 4, v0
	s_cmp_eq_u32 s14, s34
	v_and_b32_e32 v10, 31, v13
	v_lshl_add_u64 v[6:7], s[12:13], 0, v[4:5]
	v_and_b32_e32 v0, 0x70, v0
	v_lshl_add_u64 v[8:9], s[10:11], 0, v[4:5]
	v_lshrrev_b32_e32 v16, 1, v13
	s_cselect_b64 s[14:15], -1, 0
	v_lshl_add_u64 v[6:7], v[6:7], 0, v[0:1]
	v_lshl_add_u64 v[8:9], v[8:9], 0, v[0:1]
	v_and_or_b32 v0, v16, s51, v10
	v_cndmask_b32_e64 v12, 0, 1, s[14:15]
	v_lshlrev_b32_e32 v175, 7, v0
	v_lshlrev_b32_e32 v0, 7, v13
	v_lshlrev_b32_e32 v177, 4, v13
	v_and_b32_e32 v176, 0x6f80, v0
	v_cmp_ge_i32_e64 s[10:11], v2, v12
	v_cmp_gt_i32_e64 s[12:13], s18, v2
	v_and_b32_e32 v0, 0x70, v177
	v_add_u32_e32 v178, 0x8000, v177
	v_lshl_add_u64 v[158:159], s[80:81], 0, v[0:1]
	s_and_b64 s[10:11], s[10:11], s[12:13]
	v_readfirstlane_b32 s12, v177
	v_cndmask_b32_e64 v11, v159, v7, s[10:11]
	v_cndmask_b32_e64 v10, v158, v6, s[10:11]
	s_mov_b32 m0, s12
	v_readfirstlane_b32 s12, v178
	v_add_u32_e32 v0, 64, v2
	s_barrier
	s_mov_b32 m0, s12
	v_cmp_ge_i32_e64 s[12:13], v0, v12
	v_cmp_gt_i32_e64 s[14:15], s18, v0
	s_mov_b64 s[16:17], 0x20000
	v_add_u32_e32 v0, 0x2000, v177
	v_lshl_add_u64 v[10:11], v[6:7], 0, s[16:17]
	s_and_b64 s[12:13], s[12:13], s[14:15]
	v_readfirstlane_b32 s14, v0
	v_add_u32_e32 v179, 0xa000, v177
	v_cndmask_b32_e64 v11, v159, v11, s[12:13]
	v_cndmask_b32_e64 v10, v158, v10, s[12:13]
	s_mov_b32 m0, s14
	v_readfirstlane_b32 s14, v179
	v_add_u32_e32 v3, 0x80, v2
	v_lshl_add_u64 v[10:11], v[8:9], 0, s[16:17]
	s_mov_b32 m0, s14
	v_cmp_ge_i32_e64 s[14:15], v3, v12
	v_cmp_gt_i32_e64 s[16:17], s18, v3
	s_mov_b64 s[38:39], 0x40000
	v_add_u32_e32 v180, 0x4000, v177
	v_lshl_add_u64 v[10:11], v[6:7], 0, s[38:39]
	s_and_b64 s[14:15], s[14:15], s[16:17]
	v_readfirstlane_b32 s16, v180
	v_add_u32_e32 v181, 0xc000, v177
	v_cndmask_b32_e64 v11, v159, v11, s[14:15]
	v_cndmask_b32_e64 v10, v158, v10, s[14:15]
	s_mov_b32 m0, s16
	v_readfirstlane_b32 s16, v181
	v_add_u32_e32 v2, 0xc0, v2
	v_lshl_add_u64 v[10:11], v[8:9], 0, s[38:39]
	s_mov_b32 m0, s16
	v_cmp_ge_i32_e64 s[16:17], v2, v12
	v_cmp_gt_i32_e64 s[18:19], s18, v2
	s_mov_b64 s[38:39], 0x60000
	v_add_u32_e32 v182, 0x6000, v177
	v_lshl_add_u64 v[2:3], v[6:7], 0, s[38:39]
	s_and_b64 s[16:17], s[16:17], s[18:19]
	v_readfirstlane_b32 s18, v182
	v_add_u32_e32 v183, 0xe000, v177
	v_cndmask_b32_e64 v3, v159, v3, s[16:17]
	v_cndmask_b32_e64 v2, v158, v2, s[16:17]
	s_mov_b32 m0, s18
	v_readfirstlane_b32 s18, v183
	v_lshl_add_u64 v[2:3], v[8:9], 0, s[38:39]
	s_mov_b32 m0, s18
	s_sub_i32 s18, s30, s34
	s_mulk_i32 s31, 0xa8
	v_bfe_u32 v14, v13, 5, 1
	s_sub_i32 s18, s18, s31
	v_bfe_u32 v17, v13, 1, 3
	v_bitop3_b32 v2, v16, v14, 7 bitop3:0x6c
	s_mulk_i32 s18, 0xfe
	v_lshlrev_b32_e32 v185, 4, v2
	v_bitop3_b32 v2, v14, v17, 2 bitop3:0x36
	s_add_i32 s18, s18, -2
	v_lshlrev_b32_e32 v186, 4, v2
	v_bitop3_b32 v2, v14, v17, 4 bitop3:0x36
	s_ashr_i32 s19, s18, 31
	v_lshlrev_b32_e32 v187, 4, v2
	v_bitop3_b32 v2, v14, v17, 6 bitop3:0x36
	s_lshl_b64 s[18:19], s[18:19], 11
	v_bitop3_b32 v6, v15, 7, v13 bitop3:0x48
	v_lshlrev_b32_e32 v188, 4, v2
	v_lshl_add_u64 v[2:3], v[4:5], 0, s[18:19]
	v_lshlrev_b32_e32 v6, 4, v6
	v_or_b32_e32 v2, v2, v6
	v_lshl_add_u64 v[160:161], s[70:71], 0, v[2:3]
	v_lshl_add_u64 v[2:3], v[4:5], 0, s[22:23]
	s_waitcnt vmcnt(0)
	v_or_b32_e32 v2, v2, v6
	v_lshl_add_u64 v[162:163], s[70:71], 0, v[2:3]
	v_mov_b32_e32 v130, 0
	v_mov_b32_e32 v2, 0
	s_mov_b32 s29, 1
	s_mov_b64 s[38:39], 0x3858900
	v_add_u32_e32 v189, 0x10000, v177
	v_add_u32_e32 v190, 0x18000, v177
	v_add_u32_e32 v191, 0x12000, v177
	v_add_u32_e32 v192, 0x1a000, v177
	v_add_u32_e32 v193, 0x14000, v177
	v_add_u32_e32 v194, 0x1c000, v177
	v_add_u32_e32 v195, 0x16000, v177
	v_add_u32_e32 v196, 0x1e000, v177
	v_add_u32_e32 v197, 0x10000, v175
	v_or_b32_e32 v198, 0x10000, v176
	s_mov_b64 s[18:19], 0
	v_mov_b32_e32 v3, v2
	v_mov_b32_e32 v4, v2
	v_mov_b32_e32 v5, v2
	v_mov_b32_e32 v6, v2
	v_mov_b32_e32 v7, v2
	v_mov_b32_e32 v8, v2
	v_mov_b32_e32 v9, v2
	v_mov_b32_e32 v10, v2
	v_mov_b32_e32 v11, v2
	v_mov_b32_e32 v12, v2
	v_mov_b32_e32 v13, v2
	v_mov_b32_e32 v14, v2
	v_mov_b32_e32 v15, v2
	v_mov_b32_e32 v16, v2
	v_mov_b32_e32 v17, v2
	s_waitcnt vmcnt(0)
; template <bool SWAP>
; DI void gemm_mainloop(f32x16 (&acc)[4][2], const u16* __restrict__ A, int lda, int rlo, int rhi,
;                       const u16* __restrict__ B, int ldb, int K, char* lds, const u16* zero_line) {
;     ...
; #pragma unroll
;   for (int mi = 0; mi < 4; ++mi)
; #pragma unroll
;     for (int ni = 0; ni < 2; ++ni)
; #pragma unroll
;       for (int i = 0; i < 16; ++i) acc[mi][ni][i] = 0.f;
;     ...
;   auto glds = [&](int kt, int st) {
;     char* as_ = lds + st * 65536 + tid * 16;
; #pragma unroll
;     for (int i = 0; i < 4; ++i) {
;       const int rr = lr + 64 * i;
;       const u16* srca = (rr >= rlo && rr < rhi) ? (ap + (ptrdiff_t)(64 * i) * lda + kt * 64) : (zero_line + lc * 8);
;       __builtin_amdgcn_global_load_lds((const unsigned*)srca, (lds_u32*)(as_ + i * 8192), 16, 0, 0);
;       __builtin_amdgcn_global_load_lds((const unsigned*)(bp + (ptrdiff_t)(64 * i) * ldb + kt * 64), (lds_u32*)(as_ + 32768 + i * 8192), 16, 0, 0);
;     }
;   };
;   const int sw = (r >> 1) & 7;
;   const int arow_off = (wm * 128 + r) * 128;
;   const int brow_off = 32768 + (wn * 64 + r) * 128;
;   __syncthreads();
;   glds(0, 0);
;   asm volatile("s_waitcnt vmcnt(0)" ::: "memory");
;   __syncthreads();
	s_add_i32 s18, s27, -1
	s_ashr_i32 s19, s18, 31
	s_lshl_b64 s[18:19], s[18:19], 11
	s_add_u32 s18, s90, s18
	s_addc_u32 s19, s91, s19
	v_readlane_b32 s22, v253, 17
	v_readlane_b32 s23, v253, 18
	s_lshl_b32 s21, s28, 19
	s_add_u32 s22, s22, s21
	s_addc_u32 s23, s23, 0
	v_and_b32_e32 v130, 63, v204
	v_lshrrev_b32_e32 v131, 6, v204
	v_lshrrev_b32_e32 v132, 3, v204
	v_lshrrev_b32_e32 v0, 4, v130
	v_lshl_add_u32 v0, v131, 2, v0
	v_xor_b32_e32 v0, v0, v130
	v_and_b32_e32 v0, 7, v0
	v_lshlrev_b32_e32 v133, 4, v0
	v_lshl_add_u32 v236, v132, 11, v133
	v_add_u32_e32 v237, 0x20000, v236
	v_add_u32_e32 v238, 0x40000, v236
	v_add_u32_e32 v239, 0x60000, v236
	v_and_b32_e32 v0, 31, v132
	v_lshrrev_b32_e32 v130, 5, v132
	v_lshl_add_u32 v0, v130, 6, v0
	v_lshl_add_u32 v240, v0, 11, v133
	v_add_u32_e32 v241, 0x10000, v240
	v_add_u32_e32 v242, 0x40000, v240
	v_add_u32_e32 v243, 0x50000, v240
	v_and_b32_e32 v132, 31, v204
	v_lshrrev_b32_e32 v0, 2, v131
	v_lshl_add_u32 v0, v0, 6, v132
	v_lshlrev_b32_e32 v248, 7, v0
	v_and_b32_e32 v0, 3, v131
	v_lshl_add_u32 v0, v0, 5, v132
	v_lshlrev_b32_e32 v249, 7, v0
	v_bfe_u32 v0, v204, 5, 1
	v_bfe_u32 v130, v132, 1, 3
	v_or_b32_e32 v133, 0, v0
	v_xor_b32_e32 v133, v133, v130
	v_lshlrev_b32_e32 v244, 4, v133
	v_or_b32_e32 v133, 2, v0
	v_xor_b32_e32 v133, v133, v130
	v_lshlrev_b32_e32 v245, 4, v133
	v_or_b32_e32 v133, 4, v0
	v_xor_b32_e32 v133, v133, v130
	v_lshlrev_b32_e32 v246, 4, v133
	v_or_b32_e32 v133, 6, v0
	v_xor_b32_e32 v133, v133, v130
	v_lshlrev_b32_e32 v247, 4, v133
	v_lshlrev_b32_e32 v131, 10, v131
	s_nop 0
	v_readfirstlane_b32 s100, v131
	v_mov_b32_e32 v146, 0
	v_mov_b32_e32 v147, 0
	v_mov_b32_e32 v148, 0
	v_mov_b32_e32 v149, 0
	v_lshlrev_b32_e32 v130, 4, v204
	v_add_u32_e32 v132, 0x10000, v130
	s_not_b64 exec, s[10:11]
	ds_write_b128 v130, v[146:149]
	ds_write_b128 v132, v[146:149]
	s_not_b64 exec, s[12:13]
	ds_write_b128 v130, v[146:149] offset:16384
	ds_write_b128 v132, v[146:149] offset:16384
	s_not_b64 exec, s[14:15]
	ds_write_b128 v130, v[146:149] offset:8192
	ds_write_b128 v132, v[146:149] offset:8192
	s_not_b64 exec, s[16:17]
	ds_write_b128 v130, v[146:149] offset:24576
	ds_write_b128 v132, v[146:149] offset:24576
	s_mov_b64 exec, -1
	s_mov_b32 s29, 0
	s_mov_b32 s21, 0x10000
	s_waitcnt lgkmcnt(0)
	s_add_u32 m0, s100, 0x8000
	s_nop 0
	global_load_lds_dwordx4 v240, s[22:23]
	v_add_u32_e32 v240, 0x80, v240
	s_add_u32 m0, s100, 0xa000
	s_nop 0
	global_load_lds_dwordx4 v242, s[22:23]
	v_add_u32_e32 v242, 0x80, v242
	s_add_u32 m0, s100, 0x0
	s_mov_b64 exec, s[10:11]
	global_load_lds_dwordx4 v236, s[18:19]
	s_mov_b64 exec, -1
	v_add_u32_e32 v236, 0x80, v236
	s_add_u32 m0, s100, 0x2000
	s_mov_b64 exec, s[14:15]
	global_load_lds_dwordx4 v238, s[18:19]
	s_mov_b64 exec, -1
	v_add_u32_e32 v238, 0x80, v238
	s_add_u32 m0, s100, 0xc000
	s_nop 0
	global_load_lds_dwordx4 v241, s[22:23]
	v_add_u32_e32 v241, 0x80, v241
	s_add_u32 m0, s100, 0xe000
	s_nop 0
	global_load_lds_dwordx4 v243, s[22:23]
	v_add_u32_e32 v243, 0x80, v243
	s_add_u32 m0, s100, 0x4000
	s_mov_b64 exec, s[12:13]
	global_load_lds_dwordx4 v237, s[18:19]
	s_mov_b64 exec, -1
	v_add_u32_e32 v237, 0x80, v237
	s_add_u32 m0, s100, 0x6000
	s_mov_b64 exec, s[16:17]
	global_load_lds_dwordx4 v239, s[18:19]
	s_mov_b64 exec, -1
	v_add_u32_e32 v239, 0x80, v239
	v_mov_b32_e32 v18, v2
	v_mov_b32_e32 v19, v2
	v_mov_b32_e32 v20, v2
	v_mov_b32_e32 v21, v2
	v_mov_b32_e32 v22, v2
	v_mov_b32_e32 v23, v2
	v_mov_b32_e32 v24, v2
	v_mov_b32_e32 v25, v2
	v_mov_b32_e32 v26, v2
	v_mov_b32_e32 v27, v2
	v_mov_b32_e32 v28, v2
	v_mov_b32_e32 v29, v2
	v_mov_b32_e32 v30, v2
	v_mov_b32_e32 v31, v2
	v_mov_b32_e32 v32, v2
	v_mov_b32_e32 v33, v2
	v_mov_b32_e32 v34, v2
	v_mov_b32_e32 v35, v2
	v_mov_b32_e32 v36, v2
	v_mov_b32_e32 v37, v2
	v_mov_b32_e32 v38, v2
	v_mov_b32_e32 v39, v2
	v_mov_b32_e32 v40, v2
	v_mov_b32_e32 v41, v2
	v_mov_b32_e32 v42, v2
	v_mov_b32_e32 v43, v2
	v_mov_b32_e32 v44, v2
	v_mov_b32_e32 v45, v2
	v_mov_b32_e32 v46, v2
	v_mov_b32_e32 v47, v2
	v_mov_b32_e32 v48, v2
	v_mov_b32_e32 v49, v2
	v_mov_b32_e32 v50, v2
	v_mov_b32_e32 v51, v2
	v_mov_b32_e32 v52, v2
	v_mov_b32_e32 v53, v2
	v_mov_b32_e32 v54, v2
	v_mov_b32_e32 v55, v2
	v_mov_b32_e32 v56, v2
	v_mov_b32_e32 v57, v2
	v_mov_b32_e32 v58, v2
	v_mov_b32_e32 v59, v2
	v_mov_b32_e32 v60, v2
	v_mov_b32_e32 v61, v2
	v_mov_b32_e32 v62, v2
	v_mov_b32_e32 v63, v2
	v_mov_b32_e32 v64, v2
	v_mov_b32_e32 v65, v2
	v_mov_b32_e32 v66, v2
	v_mov_b32_e32 v67, v2
	v_mov_b32_e32 v68, v2
	v_mov_b32_e32 v69, v2
	v_mov_b32_e32 v70, v2
	v_mov_b32_e32 v71, v2
	v_mov_b32_e32 v72, v2
	v_mov_b32_e32 v73, v2
	v_mov_b32_e32 v74, v2
	v_mov_b32_e32 v75, v2
	v_mov_b32_e32 v76, v2
	v_mov_b32_e32 v77, v2
	v_mov_b32_e32 v78, v2
	v_mov_b32_e32 v79, v2
	v_mov_b32_e32 v80, v2
	v_mov_b32_e32 v81, v2
	v_mov_b32_e32 v82, v2
	v_mov_b32_e32 v83, v2
	v_mov_b32_e32 v84, v2
	v_mov_b32_e32 v85, v2
	v_mov_b32_e32 v86, v2
	v_mov_b32_e32 v87, v2
	v_mov_b32_e32 v88, v2
	v_mov_b32_e32 v89, v2
	v_mov_b32_e32 v90, v2
	v_mov_b32_e32 v91, v2
	v_mov_b32_e32 v92, v2
	v_mov_b32_e32 v93, v2
	v_mov_b32_e32 v94, v2
	v_mov_b32_e32 v95, v2
	v_mov_b32_e32 v96, v2
	v_mov_b32_e32 v97, v2
	v_mov_b32_e32 v98, v2
	v_mov_b32_e32 v99, v2
	v_mov_b32_e32 v100, v2
	v_mov_b32_e32 v101, v2
	v_mov_b32_e32 v102, v2
	v_mov_b32_e32 v103, v2
	v_mov_b32_e32 v104, v2
	v_mov_b32_e32 v105, v2
	v_mov_b32_e32 v106, v2
	v_mov_b32_e32 v107, v2
	v_mov_b32_e32 v108, v2
	v_mov_b32_e32 v109, v2
	v_mov_b32_e32 v110, v2
	v_mov_b32_e32 v111, v2
	v_mov_b32_e32 v112, v2
	v_mov_b32_e32 v113, v2
	v_mov_b32_e32 v114, v2
	v_mov_b32_e32 v115, v2
	v_mov_b32_e32 v116, v2
	v_mov_b32_e32 v117, v2
	v_mov_b32_e32 v118, v2
	v_mov_b32_e32 v119, v2
	v_mov_b32_e32 v120, v2
	v_mov_b32_e32 v121, v2
	v_mov_b32_e32 v122, v2
	v_mov_b32_e32 v123, v2
	v_mov_b32_e32 v124, v2
	v_mov_b32_e32 v125, v2
	v_mov_b32_e32 v126, v2
	v_mov_b32_e32 v127, v2
	v_mov_b32_e32 v128, v2
	v_mov_b32_e32 v129, v2
	v_mov_b32_e32 v131, v130
	v_mov_b32_e32 v132, v130
	v_mov_b32_e32 v133, v130
	v_mov_b32_e32 v134, v130
	v_mov_b32_e32 v135, v130
	v_mov_b32_e32 v136, v130
	v_mov_b32_e32 v137, v130
	v_mov_b32_e32 v138, v130
	v_mov_b32_e32 v139, v130
	v_mov_b32_e32 v140, v130
	v_mov_b32_e32 v141, v130
	v_mov_b32_e32 v142, v130
	v_mov_b32_e32 v143, v130
	v_mov_b32_e32 v144, v130
	v_mov_b32_e32 v145, v130
	v_mov_b32_e32 v146, v130
	v_mov_b32_e32 v147, v130
	v_mov_b32_e32 v148, v130
	v_mov_b32_e32 v149, v130
	v_mov_b32_e32 v150, v130
	v_mov_b32_e32 v151, v130
	v_mov_b32_e32 v152, v130
	v_mov_b32_e32 v153, v130
	s_mov_b64 s[30:31], 0x37f8900
	s_waitcnt vmcnt(0) lgkmcnt(0)
	s_barrier
	s_add_i32 s18, s27, -1
	s_ashr_i32 s19, s18, 31
	s_lshl_b64 s[18:19], s[18:19], 11
	s_add_u32 s18, s90, s18
	s_addc_u32 s19, s91, s19
	v_readlane_b32 s22, v253, 17
	v_readlane_b32 s23, v253, 18
	s_lshl_b32 s21, s28, 19
	s_add_u32 s22, s22, s21
	s_addc_u32 s23, s23, 0
	s_mov_b32 s29, 0
	s_mov_b32 s21, 0x10000
	s_cmp_eq_u32 s27, 0
	s_cbranch_scc1 .Lg8_u0_msk
	s_cmp_gt_i32 s20, 0xbf00
	s_cbranch_scc1 .Lg8_u0_msk
	s_cmp_eq_u32 s101, 1
	s_cbranch_scc0 .Lg8_u0u_p0
	s_barrier

; template <bool SWAP>
; DI void gemm_mainloop(f32x16 (&acc)[4][2], const u16* __restrict__ A, int lda, int rlo, int rhi,
;                       const u16* __restrict__ B, int ldb, int K, char* lds, const u16* zero_line) {
;     ...
;   auto glds = [&](int kt, int st) {
;     char* as_ = lds + st * 65536 + tid * 16;
; #pragma unroll
;     for (int i = 0; i < 4; ++i) {
;       const int rr = lr + 64 * i;
;       const u16* srca = (rr >= rlo && rr < rhi) ? (ap + (ptrdiff_t)(64 * i) * lda + kt * 64) : (zero_line + lc * 8);
;       __builtin_amdgcn_global_load_lds((const unsigned*)srca, (lds_u32*)(as_ + i * 8192), 16, 0, 0);
;       __builtin_amdgcn_global_load_lds((const unsigned*)(bp + (ptrdiff_t)(64 * i) * ldb + kt * 64), (lds_u32*)(as_ + 32768 + i * 8192), 16, 0, 0);
;     }
;   };
.Lg8_u0_msk:
	s_cmp_eq_u32 s101, 1
	s_cbranch_scc0 .Lg8_u0m_p0
	s_barrier

; template <bool SWAP>
; DI void gemm_mainloop(f32x16 (&acc)[4][2], const u16* __restrict__ A, int lda, int rlo, int rhi,
;                       const u16* __restrict__ B, int ldb, int K, char* lds, const u16* zero_line) {
;   const int tid = opaque_tid(), lane = tid & 63, w = tid >> 6;
;   const int wm = w >> 2, wn = w & 3;
;   const int h = lane >> 5, r = lane & 31;
;   const int lr = tid >> 3, lc = tid & 7;
; #pragma unroll
;   for (int mi = 0; mi < 4; ++mi)
; #pragma unroll
;     for (int ni = 0; ni < 2; ++ni)
; #pragma unroll
;       for (int i = 0; i < 16; ++i) acc[mi][ni][i] = 0.f;
;   const int gch = (lc ^ ((lr >> 1) & 7)) * 8;
;   const u16* ap = A + (ptrdiff_t)lr * lda + gch;
;   const u16* bp = B + (ptrdiff_t)lr * ldb + gch;
;   const int nk = K >> 6;
;   typedef __attribute__((address_space(3))) unsigned lds_u32;
;   auto glds = [&](int kt, int st) {
;     char* as_ = lds + st * 65536 + tid * 16;
; #pragma unroll
;     for (int i = 0; i < 4; ++i) {
;       const int rr = lr + 64 * i;
;       const u16* srca = (rr >= rlo && rr < rhi) ? (ap + (ptrdiff_t)(64 * i) * lda + kt * 64) : (zero_line + lc * 8);
;       __builtin_amdgcn_global_load_lds((const unsigned*)srca, (lds_u32*)(as_ + i * 8192), 16, 0, 0);
;       __builtin_amdgcn_global_load_lds((const unsigned*)(bp + (ptrdiff_t)(64 * i) * ldb + kt * 64), (lds_u32*)(as_ + 32768 + i * 8192), 16, 0, 0);
;     }
;   };
;   const int sw = (r >> 1) & 7;
;   const int arow_off = (wm * 128 + r) * 128;
;   const int brow_off = 32768 + (wn * 64 + r) * 128;
;   __syncthreads();
;   glds(0, 0);
;   asm volatile("s_waitcnt vmcnt(0)" ::: "memory");
;   __syncthreads();
; template <int EPI>
; DI void phase_gemm(const Params& p, const GemmArgs& ga, char* lds) {
;     ...
;   for (int it = 0; it * (int)gridDim.x < total; ++it) {
;     const int lt = logical_index(it);
;     if (lt >= total) continue;
;     int mt, nt;
;     tile_mn(lt, Mt, ga.Nt, mt, nt);
;     int bb, tokbase, S, pos0, rlo = 0, rhi = 256;
;     if (EPI == EPI_UP) {
;       bb = 0; tokbase = 0; S = NTOK;
;       pos0 = 254 * mt - 1;
;       rlo = (mt == 0) ? 1 : 0;
;       rhi = NTOK - pos0; if (rhi > 256) rhi = 256;
;     } else {
;       seq_of_token(mt * 256, bb, tokbase, S);
;       pos0 = mt * 256 - tokbase;
;     }
;     const u16* A = ga.A + (ptrdiff_t)(tokbase + pos0) * ga.lda;
;     const u16* B = ga.Bt + (size_t)(nt * 256) * ga.K;
.LBB0_167:
	s_add_i32 s30, s10, s25
	s_cmpk_gt_i32 s30, 0x10ab
	s_cbranch_scc1 .LBB0_166
	s_mul_hi_i32 s10, s30, 0x2e8ba2e9
	s_lshr_b32 s11, s10, 31
	s_ashr_i32 s10, s10, 5
	s_add_i32 s31, s10, s11
	s_lshl_b32 s10, s31, 3
	s_sub_i32 s11, 0xc2, s10
	s_min_u32 s11, s11, 8
	v_cvt_f32_ubyte0_e32 v0, s11
	v_rcp_iflag_f32_e32 v0, v0
	s_sub_i32 s15, 0, s11
	s_mul_i32 s12, s31, 0xffffff50
	s_add_i32 s12, s12, s30
	v_mul_f32_e32 v0, 0x4f7ffffe, v0
	v_cvt_u32_f32_e32 v0, v0
	s_abs_i32 s14, s12
	s_ashr_i32 s13, s12, 31
	s_waitcnt vmcnt(5)
	v_mov_b32_e32 v13, v204
	v_readfirstlane_b32 s16, v0
	s_mul_i32 s15, s15, s16
	s_mul_hi_u32 s15, s16, s15
	s_add_i32 s16, s16, s15
	s_mul_hi_u32 s15, s14, s16
	s_mul_i32 s16, s15, s11
	s_sub_i32 s14, s14, s16
	s_add_i32 s16, s15, 1
	s_sub_i32 s17, s14, s11
	s_cmp_ge_u32 s14, s11
	s_cselect_b32 s15, s16, s15
	s_cselect_b32 s14, s17, s14
	s_add_i32 s16, s15, 1
	s_cmp_ge_u32 s14, s11
	s_cselect_b32 s14, s16, s15
	s_xor_b32 s14, s14, s13
	s_sub_i32 s28, s14, s13
	s_mul_i32 s34, s28, s11
	s_add_i32 s14, s12, s10
	s_sub_i32 s27, s14, s34
	s_mulk_i32 s27, 0xfe
	s_lshl_b32 s10, s28, 8
	s_add_i32 s20, s27, -1
	s_ashr_i32 s11, s10, 31
	s_ashr_i32 s21, s20, 31
	s_lshl_b64 s[22:23], s[10:11], 11
	v_readlane_b32 s10, v253, 47
	v_readlane_b32 s11, v253, 48
	s_add_u32 s10, s10, s22
	s_addc_u32 s11, s11, s23
	s_lshl_b64 s[12:13], s[20:21], 11
	s_add_u32 s12, s90, s12
	v_ashrrev_i32_e32 v2, 3, v13
	s_waitcnt vmcnt(4)
	v_lshrrev_b32_e32 v15, 1, v2
	s_addc_u32 s13, s91, s13
	s_sub_i32 s15, 0xc001, s27
	v_xor_b32_e32 v0, v15, v13
	v_ashrrev_i32_e32 v3, 31, v2
	s_min_i32 s18, s15, 0x100
	v_lshlrev_b64 v[4:5], 11, v[2:3]
	v_lshlrev_b32_e32 v0, 4, v0
	s_cmp_eq_u32 s14, s34
	v_and_b32_e32 v10, 31, v13
	v_lshl_add_u64 v[6:7], s[12:13], 0, v[4:5]
	v_and_b32_e32 v0, 0x70, v0
	v_lshl_add_u64 v[8:9], s[10:11], 0, v[4:5]
	v_lshrrev_b32_e32 v16, 1, v13
	s_cselect_b64 s[14:15], -1, 0
	v_lshl_add_u64 v[6:7], v[6:7], 0, v[0:1]
	v_lshl_add_u64 v[8:9], v[8:9], 0, v[0:1]
	v_and_or_b32 v0, v16, s51, v10
	v_cndmask_b32_e64 v12, 0, 1, s[14:15]
	v_lshlrev_b32_e32 v175, 7, v0
	v_lshlrev_b32_e32 v0, 7, v13
	v_lshlrev_b32_e32 v177, 4, v13
	v_and_b32_e32 v176, 0x6f80, v0
	v_cmp_ge_i32_e64 s[10:11], v2, v12
	v_cmp_gt_i32_e64 s[12:13], s18, v2
	v_and_b32_e32 v0, 0x70, v177
	v_add_u32_e32 v178, 0x8000, v177
	v_lshl_add_u64 v[158:159], s[80:81], 0, v[0:1]
	s_and_b64 s[10:11], s[10:11], s[12:13]
	v_readfirstlane_b32 s12, v177
	v_cndmask_b32_e64 v11, v159, v7, s[10:11]
	v_cndmask_b32_e64 v10, v158, v6, s[10:11]
	s_mov_b32 m0, s12
	v_readfirstlane_b32 s12, v178
	v_add_u32_e32 v0, 64, v2
	s_barrier
	s_mov_b32 m0, s12
	v_cmp_ge_i32_e64 s[12:13], v0, v12
	v_cmp_gt_i32_e64 s[14:15], s18, v0
	s_mov_b64 s[16:17], 0x20000
	v_add_u32_e32 v0, 0x2000, v177
	v_lshl_add_u64 v[10:11], v[6:7], 0, s[16:17]
	s_and_b64 s[12:13], s[12:13], s[14:15]
	v_readfirstlane_b32 s14, v0
	v_add_u32_e32 v179, 0xa000, v177
	v_cndmask_b32_e64 v11, v159, v11, s[12:13]
	v_cndmask_b32_e64 v10, v158, v10, s[12:13]
	s_mov_b32 m0, s14
	v_readfirstlane_b32 s14, v179
	v_add_u32_e32 v3, 0x80, v2
	v_lshl_add_u64 v[10:11], v[8:9], 0, s[16:17]
	s_mov_b32 m0, s14
	v_cmp_ge_i32_e64 s[14:15], v3, v12
	v_cmp_gt_i32_e64 s[16:17], s18, v3
	s_mov_b64 s[36:37], 0x40000
	v_add_u32_e32 v180, 0x4000, v177
	v_lshl_add_u64 v[10:11], v[6:7], 0, s[36:37]
	s_and_b64 s[14:15], s[14:15], s[16:17]
	v_readfirstlane_b32 s16, v180
	v_add_u32_e32 v181, 0xc000, v177
	v_cndmask_b32_e64 v11, v159, v11, s[14:15]
	v_cndmask_b32_e64 v10, v158, v10, s[14:15]
	s_mov_b32 m0, s16
	v_readfirstlane_b32 s16, v181
	v_add_u32_e32 v2, 0xc0, v2
	v_lshl_add_u64 v[10:11], v[8:9], 0, s[36:37]
	s_mov_b32 m0, s16
	v_cmp_ge_i32_e64 s[16:17], v2, v12
	v_cmp_gt_i32_e64 s[18:19], s18, v2
	s_mov_b64 s[36:37], 0x60000
	v_add_u32_e32 v182, 0x6000, v177
	v_lshl_add_u64 v[2:3], v[6:7], 0, s[36:37]
	s_and_b64 s[16:17], s[16:17], s[18:19]
	v_readfirstlane_b32 s18, v182
	v_add_u32_e32 v183, 0xe000, v177
	v_cndmask_b32_e64 v3, v159, v3, s[16:17]
	v_cndmask_b32_e64 v2, v158, v2, s[16:17]
	s_mov_b32 m0, s18
	v_readfirstlane_b32 s18, v183
	v_lshl_add_u64 v[2:3], v[8:9], 0, s[36:37]
	s_mov_b32 m0, s18
	s_sub_i32 s18, s30, s34
	s_mulk_i32 s31, 0xa8
	v_bfe_u32 v14, v13, 5, 1
	s_sub_i32 s18, s18, s31
	v_bfe_u32 v17, v13, 1, 3
	v_bitop3_b32 v2, v16, v14, 7 bitop3:0x6c
	s_mulk_i32 s18, 0xfe
	v_lshlrev_b32_e32 v185, 4, v2
	v_bitop3_b32 v2, v14, v17, 2 bitop3:0x36
	s_add_i32 s18, s18, -2
	v_lshlrev_b32_e32 v186, 4, v2
	v_bitop3_b32 v2, v14, v17, 4 bitop3:0x36
	s_ashr_i32 s19, s18, 31
	v_lshlrev_b32_e32 v187, 4, v2
	v_bitop3_b32 v2, v14, v17, 6 bitop3:0x36
	s_lshl_b64 s[18:19], s[18:19], 11
	v_bitop3_b32 v6, v15, 7, v13 bitop3:0x48
	v_lshlrev_b32_e32 v188, 4, v2
	v_lshl_add_u64 v[2:3], v[4:5], 0, s[18:19]
	v_lshlrev_b32_e32 v6, 4, v6
	v_or_b32_e32 v2, v2, v6
	v_lshl_add_u64 v[160:161], s[70:71], 0, v[2:3]
	v_lshl_add_u64 v[2:3], v[4:5], 0, s[22:23]
	s_waitcnt vmcnt(0)
	v_or_b32_e32 v2, v2, v6
	v_lshl_add_u64 v[162:163], s[70:71], 0, v[2:3]
	v_mov_b32_e32 v130, 0
	v_mov_b32_e32 v2, 0
	s_mov_b32 s29, 1
	v_add_u32_e32 v189, 0x10000, v177
	v_add_u32_e32 v190, 0x18000, v177
	v_add_u32_e32 v191, 0x12000, v177
	v_add_u32_e32 v192, 0x1a000, v177
	v_add_u32_e32 v193, 0x14000, v177
	v_add_u32_e32 v194, 0x1c000, v177
	v_add_u32_e32 v195, 0x16000, v177
	v_add_u32_e32 v196, 0x1e000, v177
	v_add_u32_e32 v197, 0x10000, v175
	v_or_b32_e32 v198, 0x10000, v176
	s_mov_b64 s[18:19], 0
	v_mov_b32_e32 v3, v2
	v_mov_b32_e32 v4, v2
	v_mov_b32_e32 v5, v2
	v_mov_b32_e32 v6, v2
	v_mov_b32_e32 v7, v2
	v_mov_b32_e32 v8, v2
	v_mov_b32_e32 v9, v2
	v_mov_b32_e32 v10, v2
	v_mov_b32_e32 v11, v2
	v_mov_b32_e32 v12, v2
	v_mov_b32_e32 v13, v2
	v_mov_b32_e32 v14, v2
	v_mov_b32_e32 v15, v2
	v_mov_b32_e32 v16, v2
	v_mov_b32_e32 v17, v2
	s_waitcnt vmcnt(0)
; template <bool SWAP>
; DI void gemm_mainloop(f32x16 (&acc)[4][2], const u16* __restrict__ A, int lda, int rlo, int rhi,
;                       const u16* __restrict__ B, int ldb, int K, char* lds, const u16* zero_line) {
;     ...
; #pragma unroll
;   for (int mi = 0; mi < 4; ++mi)
; #pragma unroll
;     for (int ni = 0; ni < 2; ++ni)
; #pragma unroll
;       for (int i = 0; i < 16; ++i) acc[mi][ni][i] = 0.f;
;     ...
;   auto glds = [&](int kt, int st) {
;     char* as_ = lds + st * 65536 + tid * 16;
; #pragma unroll
;     for (int i = 0; i < 4; ++i) {
;       const int rr = lr + 64 * i;
;       const u16* srca = (rr >= rlo && rr < rhi) ? (ap + (ptrdiff_t)(64 * i) * lda + kt * 64) : (zero_line + lc * 8);
;       __builtin_amdgcn_global_load_lds((const unsigned*)srca, (lds_u32*)(as_ + i * 8192), 16, 0, 0);
;       __builtin_amdgcn_global_load_lds((const unsigned*)(bp + (ptrdiff_t)(64 * i) * ldb + kt * 64), (lds_u32*)(as_ + 32768 + i * 8192), 16, 0, 0);
;     }
;   };
;   const int sw = (r >> 1) & 7;
;   const int arow_off = (wm * 128 + r) * 128;
;   const int brow_off = 32768 + (wn * 64 + r) * 128;
;   __syncthreads();
;   glds(0, 0);
;   asm volatile("s_waitcnt vmcnt(0)" ::: "memory");
;   __syncthreads();
	s_add_i32 s18, s27, -1
	s_ashr_i32 s19, s18, 31
	s_lshl_b64 s[18:19], s[18:19], 11
	s_add_u32 s18, s90, s18
	s_addc_u32 s19, s91, s19
	v_readlane_b32 s22, v253, 47
	v_readlane_b32 s23, v253, 48
	s_lshl_b32 s21, s28, 19
	s_add_u32 s22, s22, s21
	s_addc_u32 s23, s23, 0
	v_and_b32_e32 v130, 63, v204
	v_lshrrev_b32_e32 v131, 6, v204
	v_lshrrev_b32_e32 v132, 3, v204
	v_lshrrev_b32_e32 v0, 4, v130
	v_lshl_add_u32 v0, v131, 2, v0
	v_xor_b32_e32 v0, v0, v130
	v_and_b32_e32 v0, 7, v0
	v_lshlrev_b32_e32 v133, 4, v0
	v_lshl_add_u32 v236, v132, 11, v133
	v_add_u32_e32 v237, 0x20000, v236
	v_add_u32_e32 v238, 0x40000, v236
	v_add_u32_e32 v239, 0x60000, v236
	v_and_b32_e32 v0, 31, v132
	v_lshrrev_b32_e32 v130, 5, v132
	v_lshl_add_u32 v0, v130, 6, v0
	v_lshl_add_u32 v240, v0, 11, v133
	v_add_u32_e32 v241, 0x10000, v240
	v_add_u32_e32 v242, 0x40000, v240
	v_add_u32_e32 v243, 0x50000, v240
	v_and_b32_e32 v132, 31, v204
	v_lshrrev_b32_e32 v0, 2, v131
	v_lshl_add_u32 v0, v0, 6, v132
	v_lshlrev_b32_e32 v248, 7, v0
	v_and_b32_e32 v0, 3, v131
	v_lshl_add_u32 v0, v0, 5, v132
	v_lshlrev_b32_e32 v249, 7, v0
	v_bfe_u32 v0, v204, 5, 1
	v_bfe_u32 v130, v132, 1, 3
	v_or_b32_e32 v133, 0, v0
	v_xor_b32_e32 v133, v133, v130
	v_lshlrev_b32_e32 v244, 4, v133
	v_or_b32_e32 v133, 2, v0
	v_xor_b32_e32 v133, v133, v130
	v_lshlrev_b32_e32 v245, 4, v133
	v_or_b32_e32 v133, 4, v0
	v_xor_b32_e32 v133, v133, v130
	v_lshlrev_b32_e32 v246, 4, v133
	v_or_b32_e32 v133, 6, v0
	v_xor_b32_e32 v133, v133, v130
	v_lshlrev_b32_e32 v247, 4, v133
	v_lshlrev_b32_e32 v131, 10, v131
	s_nop 0
	v_readfirstlane_b32 s100, v131
	v_mov_b32_e32 v146, 0
	v_mov_b32_e32 v147, 0
	v_mov_b32_e32 v148, 0
	v_mov_b32_e32 v149, 0
	v_lshlrev_b32_e32 v130, 4, v204
	v_add_u32_e32 v132, 0x10000, v130
	s_not_b64 exec, s[10:11]
	ds_write_b128 v130, v[146:149]
	ds_write_b128 v132, v[146:149]
	s_not_b64 exec, s[12:13]
	ds_write_b128 v130, v[146:149] offset:16384
	ds_write_b128 v132, v[146:149] offset:16384
	s_not_b64 exec, s[14:15]
	ds_write_b128 v130, v[146:149] offset:8192
	ds_write_b128 v132, v[146:149] offset:8192
	s_not_b64 exec, s[16:17]
	ds_write_b128 v130, v[146:149] offset:24576
	ds_write_b128 v132, v[146:149] offset:24576
	s_mov_b64 exec, -1
	s_mov_b32 s29, 0
	s_mov_b32 s21, 0x10000
	s_waitcnt lgkmcnt(0)
	s_add_u32 m0, s100, 0x8000
	s_nop 0
	global_load_lds_dwordx4 v240, s[22:23]
	v_add_u32_e32 v240, 0x80, v240
	s_add_u32 m0, s100, 0xa000
	s_nop 0
	global_load_lds_dwordx4 v242, s[22:23]
	v_add_u32_e32 v242, 0x80, v242
	s_add_u32 m0, s100, 0x0
	s_mov_b64 exec, s[10:11]
	global_load_lds_dwordx4 v236, s[18:19]
	s_mov_b64 exec, -1
	v_add_u32_e32 v236, 0x80, v236
	s_add_u32 m0, s100, 0x2000
	s_mov_b64 exec, s[14:15]
	global_load_lds_dwordx4 v238, s[18:19]
	s_mov_b64 exec, -1
	v_add_u32_e32 v238, 0x80, v238
	s_add_u32 m0, s100, 0xc000
	s_nop 0
	global_load_lds_dwordx4 v241, s[22:23]
	v_add_u32_e32 v241, 0x80, v241
	s_add_u32 m0, s100, 0xe000
	s_nop 0
	global_load_lds_dwordx4 v243, s[22:23]
	v_add_u32_e32 v243, 0x80, v243
	s_add_u32 m0, s100, 0x4000
	s_mov_b64 exec, s[12:13]
	global_load_lds_dwordx4 v237, s[18:19]
	s_mov_b64 exec, -1
	v_add_u32_e32 v237, 0x80, v237
	s_add_u32 m0, s100, 0x6000
	s_mov_b64 exec, s[16:17]
	global_load_lds_dwordx4 v239, s[18:19]
	s_mov_b64 exec, -1
	v_add_u32_e32 v239, 0x80, v239
	v_mov_b32_e32 v18, v2
	v_mov_b32_e32 v19, v2
	v_mov_b32_e32 v20, v2
	v_mov_b32_e32 v21, v2
	v_mov_b32_e32 v22, v2
	v_mov_b32_e32 v23, v2
	v_mov_b32_e32 v24, v2
	v_mov_b32_e32 v25, v2
	v_mov_b32_e32 v26, v2
	v_mov_b32_e32 v27, v2
	v_mov_b32_e32 v28, v2
	v_mov_b32_e32 v29, v2
	v_mov_b32_e32 v30, v2
	v_mov_b32_e32 v31, v2
	v_mov_b32_e32 v32, v2
	v_mov_b32_e32 v33, v2
	v_mov_b32_e32 v34, v2
	v_mov_b32_e32 v35, v2
	v_mov_b32_e32 v36, v2
	v_mov_b32_e32 v37, v2
	v_mov_b32_e32 v38, v2
	v_mov_b32_e32 v39, v2
	v_mov_b32_e32 v40, v2
	v_mov_b32_e32 v41, v2
	v_mov_b32_e32 v42, v2
	v_mov_b32_e32 v43, v2
	v_mov_b32_e32 v44, v2
	v_mov_b32_e32 v45, v2
	v_mov_b32_e32 v46, v2
	v_mov_b32_e32 v47, v2
	v_mov_b32_e32 v48, v2
	v_mov_b32_e32 v49, v2
	v_mov_b32_e32 v50, v2
	v_mov_b32_e32 v51, v2
	v_mov_b32_e32 v52, v2
	v_mov_b32_e32 v53, v2
	v_mov_b32_e32 v54, v2
	v_mov_b32_e32 v55, v2
	v_mov_b32_e32 v56, v2
	v_mov_b32_e32 v57, v2
	v_mov_b32_e32 v58, v2
	v_mov_b32_e32 v59, v2
	v_mov_b32_e32 v60, v2
	v_mov_b32_e32 v61, v2
	v_mov_b32_e32 v62, v2
	v_mov_b32_e32 v63, v2
	v_mov_b32_e32 v64, v2
	v_mov_b32_e32 v65, v2
	v_mov_b32_e32 v66, v2
	v_mov_b32_e32 v67, v2
	v_mov_b32_e32 v68, v2
	v_mov_b32_e32 v69, v2
	v_mov_b32_e32 v70, v2
	v_mov_b32_e32 v71, v2
	v_mov_b32_e32 v72, v2
	v_mov_b32_e32 v73, v2
	v_mov_b32_e32 v74, v2
	v_mov_b32_e32 v75, v2
	v_mov_b32_e32 v76, v2
	v_mov_b32_e32 v77, v2
	v_mov_b32_e32 v78, v2
	v_mov_b32_e32 v79, v2
	v_mov_b32_e32 v80, v2
	v_mov_b32_e32 v81, v2
	v_mov_b32_e32 v82, v2
	v_mov_b32_e32 v83, v2
	v_mov_b32_e32 v84, v2
	v_mov_b32_e32 v85, v2
	v_mov_b32_e32 v86, v2
	v_mov_b32_e32 v87, v2
	v_mov_b32_e32 v88, v2
	v_mov_b32_e32 v89, v2
	v_mov_b32_e32 v90, v2
	v_mov_b32_e32 v91, v2
	v_mov_b32_e32 v92, v2
	v_mov_b32_e32 v93, v2
	v_mov_b32_e32 v94, v2
	v_mov_b32_e32 v95, v2
	v_mov_b32_e32 v96, v2
	v_mov_b32_e32 v97, v2
	v_mov_b32_e32 v98, v2
	v_mov_b32_e32 v99, v2
	v_mov_b32_e32 v100, v2
	v_mov_b32_e32 v101, v2
	v_mov_b32_e32 v102, v2
	v_mov_b32_e32 v103, v2
	v_mov_b32_e32 v104, v2
	v_mov_b32_e32 v105, v2
	v_mov_b32_e32 v106, v2
	v_mov_b32_e32 v107, v2
	v_mov_b32_e32 v108, v2
	v_mov_b32_e32 v109, v2
	v_mov_b32_e32 v110, v2
	v_mov_b32_e32 v111, v2
	v_mov_b32_e32 v112, v2
	v_mov_b32_e32 v113, v2
	v_mov_b32_e32 v114, v2
	v_mov_b32_e32 v115, v2
	v_mov_b32_e32 v116, v2
	v_mov_b32_e32 v117, v2
	v_mov_b32_e32 v118, v2
	v_mov_b32_e32 v119, v2
	v_mov_b32_e32 v120, v2
	v_mov_b32_e32 v121, v2
	v_mov_b32_e32 v122, v2
	v_mov_b32_e32 v123, v2
	v_mov_b32_e32 v124, v2
	v_mov_b32_e32 v125, v2
	v_mov_b32_e32 v126, v2
	v_mov_b32_e32 v127, v2
	v_mov_b32_e32 v128, v2
	v_mov_b32_e32 v129, v2
	v_mov_b32_e32 v131, v130
	v_mov_b32_e32 v132, v130
	v_mov_b32_e32 v133, v130
	v_mov_b32_e32 v134, v130
	v_mov_b32_e32 v135, v130
	v_mov_b32_e32 v136, v130
	v_mov_b32_e32 v137, v130
	v_mov_b32_e32 v138, v130
	v_mov_b32_e32 v139, v130
	v_mov_b32_e32 v140, v130
	v_mov_b32_e32 v141, v130
	v_mov_b32_e32 v142, v130
	v_mov_b32_e32 v143, v130
	v_mov_b32_e32 v144, v130
	v_mov_b32_e32 v145, v130
	v_mov_b32_e32 v146, v130
	v_mov_b32_e32 v147, v130
	v_mov_b32_e32 v148, v130
	v_mov_b32_e32 v149, v130
	v_mov_b32_e32 v150, v130
	v_mov_b32_e32 v151, v130
	v_mov_b32_e32 v152, v130
	v_mov_b32_e32 v153, v130
	s_mov_b64 s[30:31], 0x37f8900
	s_waitcnt lgkmcnt(0)
	s_barrier
	s_add_i32 s18, s27, -1
	s_ashr_i32 s19, s18, 31
	s_lshl_b64 s[18:19], s[18:19], 11
	s_add_u32 s18, s90, s18
	s_addc_u32 s19, s91, s19
	v_readlane_b32 s22, v253, 47
	v_readlane_b32 s23, v253, 48
	s_lshl_b32 s21, s28, 19
	s_add_u32 s22, s22, s21
	s_addc_u32 s23, s23, 0
	s_mov_b32 s29, 0
	s_mov_b32 s21, 0x10000
	s_cmp_eq_u32 s27, 0
	s_cbranch_scc1 .Lg8_u1_msk
	s_cmp_gt_i32 s20, 0xbf00
	s_cbranch_scc1 .Lg8_u1_msk
	s_cmp_eq_u32 s101, 1
	s_cbranch_scc0 .Lg8_u1u_p0
	s_barrier

; template <bool SWAP>
; DI void gemm_mainloop(f32x16 (&acc)[4][2], const u16* __restrict__ A, int lda, int rlo, int rhi,
;                       const u16* __restrict__ B, int ldb, int K, char* lds, const u16* zero_line) {
;     ...
;   const int gch = (lc ^ ((lr >> 1) & 7)) * 8;
;   const u16* ap = A + (ptrdiff_t)lr * lda + gch;
;   const u16* bp = B + (ptrdiff_t)lr * ldb + gch;
;   const int nk = K >> 6;
;   typedef __attribute__((address_space(3))) unsigned lds_u32;
;   auto glds = [&](int kt, int st) {
;     char* as_ = lds + st * 65536 + tid * 16;
; #pragma unroll
;     for (int i = 0; i < 4; ++i) {
;       const int rr = lr + 64 * i;
;       const u16* srca = (rr >= rlo && rr < rhi) ? (ap + (ptrdiff_t)(64 * i) * lda + kt * 64) : (zero_line + lc * 8);
;       __builtin_amdgcn_global_load_lds((const unsigned*)srca, (lds_u32*)(as_ + i * 8192), 16, 0, 0);
;       __builtin_amdgcn_global_load_lds((const unsigned*)(bp + (ptrdiff_t)(64 * i) * ldb + kt * 64), (lds_u32*)(as_ + 32768 + i * 8192), 16, 0, 0);
;     }
;   };
;   const int sw = (r >> 1) & 7;
;   const int arow_off = (wm * 128 + r) * 128;
;   const int brow_off = 32768 + (wn * 64 + r) * 128;
;   __syncthreads();
;   glds(0, 0);
;   asm volatile("s_waitcnt vmcnt(0)" ::: "memory");
;   __syncthreads();
; template <int EPI>
; DI void phase_gemm(const Params& p, const GemmArgs& ga, char* lds) {
;     ...
;   for (int it = 0; it * (int)gridDim.x < total; ++it) {
;     const int lt = logical_index(it);
;     if (lt >= total) continue;
;     int mt, nt;
;     tile_mn(lt, Mt, ga.Nt, mt, nt);
;     int bb, tokbase, S, pos0, rlo = 0, rhi = 256;
;     if (EPI == EPI_UP) {
;       bb = 0; tokbase = 0; S = NTOK;
;       pos0 = 254 * mt - 1;
;       rlo = (mt == 0) ? 1 : 0;
;       rhi = NTOK - pos0; if (rhi > 256) rhi = 256;
;     } else {
;       seq_of_token(mt * 256, bb, tokbase, S);
;       pos0 = mt * 256 - tokbase;
;     }
;     const u16* A = ga.A + (ptrdiff_t)(tokbase + pos0) * ga.lda;
;     const u16* B = ga.Bt + (size_t)(nt * 256) * ga.K;
.LBB0_196:
	s_add_i32 s6, s6, s27
	s_cmpk_gt_i32 s6, 0x8ff
	s_cbranch_scc1 .LBB0_195
	s_mul_hi_i32 s7, s6, 0x2aaaaaab
	s_lshr_b32 s8, s7, 31
	s_ashr_i32 s7, s7, 4
	s_add_i32 s8, s7, s8
	s_mul_i32 s7, s8, 0xffffffa0
	s_add_i32 s9, s7, s6
	s_ashr_i32 s7, s9, 31
	s_lshr_b32 s7, s7, 29
	s_lshl_b32 s6, s8, 3
	s_add_i32 s10, s9, s7
	s_add_i32 s6, s9, s6
	s_and_b32 s31, s10, -8
	s_sub_i32 s30, s6, s31
	s_lshl_b32 s12, s30, 8
	s_ashr_i32 s13, s12, 31
	s_lshl_b64 s[6:7], s[12:13], 11
	s_add_u32 s20, s90, s6
	s_addc_u32 s21, s91, s7
	s_lshl_b32 s6, s10, 5
	s_and_b32 s14, s6, 0xffffff00
	s_ashr_i32 s15, s14, 31
	s_lshl_b64 s[18:19], s[14:15], 11
	v_readlane_b32 s6, v253, 43
	v_readlane_b32 s7, v253, 44
	s_add_u32 s22, s6, s18
	s_addc_u32 s23, s7, s19
	s_cmp_gt_i32 s9, 63
	s_cselect_b64 s[16:17], -1, 0
	s_mov_b64 s[6:7], -1
	s_and_b64 vcc, exec, s[16:17]
	s_mul_i32 s13, s8, 0x58
	s_cbranch_vccz .LBB0_203
	v_mov_b32_e32 v12, v204
	s_mov_b64 s[10:11], 0x20000
	v_ashrrev_i32_e32 v2, 3, v12
	v_lshrrev_b32_e32 v14, 1, v2
	v_xor_b32_e32 v0, v14, v12
	v_ashrrev_i32_e32 v3, 31, v2
	v_lshlrev_b64 v[4:5], 11, v[2:3]
	v_lshlrev_b32_e32 v0, 4, v0
	v_and_b32_e32 v10, 31, v12
	v_lshl_add_u64 v[6:7], s[20:21], 0, v[4:5]
	v_and_b32_e32 v0, 0x70, v0
	v_lshl_add_u64 v[8:9], s[22:23], 0, v[4:5]
	v_lshrrev_b32_e32 v15, 1, v12
	v_lshl_add_u64 v[6:7], v[6:7], 0, v[0:1]
	v_lshl_add_u64 v[8:9], v[8:9], 0, v[0:1]
	v_and_or_b32 v0, v15, s51, v10
	v_lshlrev_b32_e32 v169, 7, v0
	v_lshlrev_b32_e32 v0, 7, v12
	v_lshlrev_b32_e32 v171, 4, v12
	v_and_b32_e32 v170, 0x6f80, v0
	v_and_b32_e32 v0, 0x70, v171
	v_add_u32_e32 v172, 0x8000, v171
	v_lshl_add_u64 v[156:157], s[80:81], 0, v[0:1]
	v_cmp_gt_u32_e32 vcc, s50, v2
	v_readfirstlane_b32 s6, v171
	s_mov_b32 m0, s6
	v_cndmask_b32_e32 v11, v157, v7, vcc
	v_cndmask_b32_e32 v10, v156, v6, vcc
	v_readfirstlane_b32 s6, v172
	v_add_u32_e32 v0, 64, v2
	v_add_u32_e32 v173, 0x2000, v171
	s_barrier
	s_mov_b32 m0, s6
	v_lshl_add_u64 v[10:11], v[6:7], 0, s[10:11]
	v_cmp_gt_u32_e64 s[6:7], s50, v0
	v_readfirstlane_b32 s8, v173
	v_add_u32_e32 v174, 0xa000, v171
	v_cndmask_b32_e64 v11, v157, v11, s[6:7]
	v_cndmask_b32_e64 v10, v156, v10, s[6:7]
	s_mov_b32 m0, s8
	v_readfirstlane_b32 s8, v174
	v_lshl_add_u64 v[10:11], v[8:9], 0, s[10:11]
	s_mov_b32 m0, s8
	v_add_u32_e32 v0, 0x80, v2
	s_mov_b64 s[24:25], 0x40000
	v_add_u32_e32 v175, 0x4000, v171
	v_lshl_add_u64 v[10:11], v[6:7], 0, s[24:25]
	v_cmp_gt_u32_e64 s[8:9], s50, v0
	v_readfirstlane_b32 s10, v175
	v_add_u32_e32 v176, 0xc000, v171
	v_cndmask_b32_e64 v11, v157, v11, s[8:9]
	v_cndmask_b32_e64 v10, v156, v10, s[8:9]
	s_mov_b32 m0, s10
	v_readfirstlane_b32 s10, v176
	v_add_u32_e32 v0, 0xc0, v2
	s_mov_b64 s[34:35], 0x60000
	v_add_u32_e32 v177, 0x6000, v171
	v_lshl_add_u64 v[10:11], v[8:9], 0, s[24:25]
	s_mov_b32 m0, s10
	v_lshl_add_u64 v[2:3], v[6:7], 0, s[34:35]
	v_cmp_gt_u32_e64 s[10:11], s50, v0
	v_readfirstlane_b32 s24, v177
	v_add_u32_e32 v178, 0xe000, v171
	v_cndmask_b32_e64 v3, v157, v3, s[10:11]
	v_cndmask_b32_e64 v2, v156, v2, s[10:11]
	s_mov_b32 m0, s24
	v_readfirstlane_b32 s24, v178
	v_lshl_add_u64 v[2:3], v[8:9], 0, s[34:35]
	s_mov_b32 m0, s24
	v_bfe_u32 v13, v12, 5, 1
	v_bfe_u32 v16, v12, 1, 3
	v_bitop3_b32 v0, v15, v13, 7 bitop3:0x6c
	s_sub_i32 s24, s28, s31
	v_lshlrev_b32_e32 v179, 4, v0
	v_bitop3_b32 v0, v13, v16, 2 bitop3:0x36
	s_sub_i32 s24, s24, s13
	v_lshlrev_b32_e32 v180, 4, v0
	v_bitop3_b32 v0, v13, v16, 4 bitop3:0x36
	s_lshl_b32 s24, s24, 8
	v_lshlrev_b32_e32 v181, 4, v0
	v_bitop3_b32 v0, v13, v16, 6 bitop3:0x36
	s_ashr_i32 s25, s24, 31
	v_lshlrev_b32_e32 v182, 4, v0
	s_lshl_b64 s[24:25], s[24:25], 11
	v_bitop3_b32 v0, v14, 7, v12 bitop3:0x48
	v_lshl_add_u64 v[2:3], v[4:5], 0, s[24:25]
	v_lshlrev_b32_e32 v0, 4, v0
	v_or_b32_e32 v2, v2, v0
	v_lshl_add_u64 v[158:159], s[70:71], 0, v[2:3]
	v_lshl_add_u64 v[2:3], v[4:5], 0, s[18:19]
	s_waitcnt vmcnt(0)
	s_ashr_i32 s7, s12, 31
	s_mov_b32 s6, s12
	s_lshl_b64 s[6:7], s[6:7], 11
	s_add_u32 s6, s90, s6
	s_addc_u32 s7, s91, s7
	s_ashr_i32 s9, s14, 31
	s_mov_b32 s8, s14
	s_lshl_b64 s[8:9], s[8:9], 11
	v_readlane_b32 s10, v253, 43
	v_readlane_b32 s11, v253, 44
	s_add_u32 s8, s10, s8
	s_addc_u32 s9, s11, s9
	v_and_b32_e32 v130, 63, v204
	v_lshrrev_b32_e32 v131, 6, v204
	v_lshrrev_b32_e32 v132, 3, v204
	v_lshrrev_b32_e32 v0, 4, v130
	v_lshl_add_u32 v0, v131, 2, v0
	v_xor_b32_e32 v0, v0, v130
	v_and_b32_e32 v0, 7, v0
	v_lshlrev_b32_e32 v133, 4, v0
	v_lshl_add_u32 v232, v132, 11, v133
	v_add_u32_e32 v233, 0x20000, v232
	v_add_u32_e32 v234, 0x40000, v232
	v_add_u32_e32 v235, 0x60000, v232
	v_and_b32_e32 v0, 31, v132
	v_lshrrev_b32_e32 v130, 5, v132
	v_lshl_add_u32 v0, v130, 6, v0
	v_lshl_add_u32 v236, v0, 11, v133
	v_add_u32_e32 v237, 0x10000, v236
	v_add_u32_e32 v238, 0x40000, v236
	v_add_u32_e32 v239, 0x50000, v236
	v_and_b32_e32 v132, 31, v204
	v_lshrrev_b32_e32 v0, 2, v131
	v_lshl_add_u32 v0, v0, 6, v132
	v_lshlrev_b32_e32 v244, 7, v0
	v_and_b32_e32 v0, 3, v131
	v_lshl_add_u32 v0, v0, 5, v132
	v_lshlrev_b32_e32 v245, 7, v0
	v_bfe_u32 v0, v204, 5, 1
	v_bfe_u32 v130, v132, 1, 3
	v_or_b32_e32 v133, 0, v0
	v_xor_b32_e32 v133, v133, v130
	v_lshlrev_b32_e32 v240, 4, v133
	v_or_b32_e32 v133, 2, v0
	v_xor_b32_e32 v133, v133, v130
	v_lshlrev_b32_e32 v241, 4, v133
	v_or_b32_e32 v133, 4, v0
	v_xor_b32_e32 v133, v133, v130
	v_lshlrev_b32_e32 v242, 4, v133
	v_or_b32_e32 v133, 6, v0
	v_xor_b32_e32 v133, v133, v130
	v_lshlrev_b32_e32 v243, 4, v133
	v_lshlrev_b32_e32 v131, 10, v131
	s_nop 0
	v_readfirstlane_b32 s100, v131
	v_mov_b32_e32 v146, 0
	v_mov_b32_e32 v147, 0
	v_mov_b32_e32 v148, 0
	v_mov_b32_e32 v149, 0
	v_lshlrev_b32_e32 v130, 4, v204
	v_add_u32_e32 v132, 0x10000, v130
	s_mov_b64 exec, -1
	s_mov_b32 s11, 0
	s_mov_b32 s10, 0x10000
	s_waitcnt lgkmcnt(0)
; template <bool SWAP>
; DI void gemm_mainloop(f32x16 (&acc)[4][2], const u16* __restrict__ A, int lda, int rlo, int rhi,
;                       const u16* __restrict__ B, int ldb, int K, char* lds, const u16* zero_line) {
;     ...
; #pragma unroll
;   for (int mi = 0; mi < 4; ++mi)
; #pragma unroll
;     for (int ni = 0; ni < 2; ++ni)
; #pragma unroll
;       for (int i = 0; i < 16; ++i) acc[mi][ni][i] = 0.f;
;     ...
;   auto glds = [&](int kt, int st) {
;     char* as_ = lds + st * 65536 + tid * 16;
; #pragma unroll
;     for (int i = 0; i < 4; ++i) {
;       const int rr = lr + 64 * i;
;       const u16* srca = (rr >= rlo && rr < rhi) ? (ap + (ptrdiff_t)(64 * i) * lda + kt * 64) : (zero_line + lc * 8);
;       __builtin_amdgcn_global_load_lds((const unsigned*)srca, (lds_u32*)(as_ + i * 8192), 16, 0, 0);
;       __builtin_amdgcn_global_load_lds((const unsigned*)(bp + (ptrdiff_t)(64 * i) * ldb + kt * 64), (lds_u32*)(as_ + 32768 + i * 8192), 16, 0, 0);
;     }
;   };
;   const int sw = (r >> 1) & 7;
;   const int arow_off = (wm * 128 + r) * 128;
;   const int brow_off = 32768 + (wn * 64 + r) * 128;
;   __syncthreads();
;   glds(0, 0);
;   asm volatile("s_waitcnt vmcnt(0)" ::: "memory");
;   __syncthreads();
	s_add_u32 m0, s100, 0x8000
	s_nop 0
	global_load_lds_dwordx4 v236, s[8:9]
	v_add_u32_e32 v236, 0x80, v236
	s_add_u32 m0, s100, 0xa000
	s_nop 0
	global_load_lds_dwordx4 v238, s[8:9]
	v_add_u32_e32 v238, 0x80, v238
	s_add_u32 m0, s100, 0x0
	s_nop 0
	global_load_lds_dwordx4 v232, s[6:7]
	v_add_u32_e32 v232, 0x80, v232
	s_add_u32 m0, s100, 0x2000
	s_nop 0
	global_load_lds_dwordx4 v234, s[6:7]
	v_add_u32_e32 v234, 0x80, v234
	s_add_u32 m0, s100, 0xc000
	s_nop 0
	global_load_lds_dwordx4 v237, s[8:9]
	v_add_u32_e32 v237, 0x80, v237
	s_add_u32 m0, s100, 0xe000
	s_nop 0
	global_load_lds_dwordx4 v239, s[8:9]
	v_add_u32_e32 v239, 0x80, v239
	s_add_u32 m0, s100, 0x4000
	s_nop 0
	global_load_lds_dwordx4 v233, s[6:7]
	v_add_u32_e32 v233, 0x80, v233
	s_add_u32 m0, s100, 0x6000
	s_nop 0
	global_load_lds_dwordx4 v235, s[6:7]
	v_add_u32_e32 v235, 0x80, v235
	v_lshl_add_u64 v[2:3], v[2:3], 0, v[0:1]
	v_lshl_add_u64 v[160:161], s[70:71], 0, v[2:3]
	v_mov_b32_e32 v130, 0
	v_mov_b32_e32 v2, 0
	s_mov_b32 s15, 1
	v_add_u32_e32 v183, 0x10000, v171
	v_add_u32_e32 v185, 0x18000, v171
	v_add_u32_e32 v186, 0x12000, v171
	v_add_u32_e32 v187, 0x1a000, v171
	v_add_u32_e32 v188, 0x14000, v171
	v_add_u32_e32 v189, 0x1c000, v171
	v_add_u32_e32 v190, 0x16000, v171
	v_add_u32_e32 v191, 0x1e000, v171
	v_add_u32_e32 v192, 0x10000, v169
	v_or_b32_e32 v193, 0x10000, v170
	s_mov_b64 s[24:25], 0
	v_mov_b32_e32 v3, v2
	v_mov_b32_e32 v4, v2
	v_mov_b32_e32 v5, v2
	v_mov_b32_e32 v6, v2
	v_mov_b32_e32 v7, v2
	v_mov_b32_e32 v8, v2
	v_mov_b32_e32 v9, v2
	v_mov_b32_e32 v10, v2
	v_mov_b32_e32 v11, v2
	v_mov_b32_e32 v12, v2
	v_mov_b32_e32 v13, v2
	v_mov_b32_e32 v14, v2
	v_mov_b32_e32 v15, v2
	v_mov_b32_e32 v16, v2
	v_mov_b32_e32 v17, v2
	v_mov_b32_e32 v18, v2
	v_mov_b32_e32 v19, v2
	v_mov_b32_e32 v20, v2
	v_mov_b32_e32 v21, v2
	v_mov_b32_e32 v22, v2
	v_mov_b32_e32 v23, v2
	v_mov_b32_e32 v24, v2
	v_mov_b32_e32 v25, v2
	v_mov_b32_e32 v26, v2
	v_mov_b32_e32 v27, v2
	v_mov_b32_e32 v28, v2
	v_mov_b32_e32 v29, v2
	v_mov_b32_e32 v30, v2
	v_mov_b32_e32 v31, v2
	v_mov_b32_e32 v32, v2
	v_mov_b32_e32 v33, v2
	v_mov_b32_e32 v34, v2
	v_mov_b32_e32 v35, v2
	v_mov_b32_e32 v36, v2
	v_mov_b32_e32 v37, v2
	v_mov_b32_e32 v38, v2
	v_mov_b32_e32 v39, v2
	v_mov_b32_e32 v40, v2
	v_mov_b32_e32 v41, v2
	v_mov_b32_e32 v42, v2
	v_mov_b32_e32 v43, v2
	v_mov_b32_e32 v44, v2
	v_mov_b32_e32 v45, v2
	v_mov_b32_e32 v46, v2
	v_mov_b32_e32 v47, v2
	v_mov_b32_e32 v48, v2
	v_mov_b32_e32 v49, v2
	v_mov_b32_e32 v50, v2
	v_mov_b32_e32 v51, v2
	v_mov_b32_e32 v52, v2
	v_mov_b32_e32 v53, v2
	v_mov_b32_e32 v54, v2
	v_mov_b32_e32 v55, v2
	v_mov_b32_e32 v56, v2
	v_mov_b32_e32 v57, v2
	v_mov_b32_e32 v58, v2
	v_mov_b32_e32 v59, v2
	v_mov_b32_e32 v60, v2
	v_mov_b32_e32 v61, v2
	v_mov_b32_e32 v62, v2
	v_mov_b32_e32 v63, v2
	v_mov_b32_e32 v64, v2
	v_mov_b32_e32 v65, v2
	v_mov_b32_e32 v66, v2
	v_mov_b32_e32 v67, v2
	v_mov_b32_e32 v68, v2
	v_mov_b32_e32 v69, v2
	v_mov_b32_e32 v70, v2
	v_mov_b32_e32 v71, v2
	v_mov_b32_e32 v72, v2
	v_mov_b32_e32 v73, v2
	v_mov_b32_e32 v74, v2
	v_mov_b32_e32 v75, v2
	v_mov_b32_e32 v76, v2
	v_mov_b32_e32 v77, v2
	v_mov_b32_e32 v78, v2
	v_mov_b32_e32 v79, v2
	v_mov_b32_e32 v80, v2
	v_mov_b32_e32 v81, v2
	v_mov_b32_e32 v82, v2
	v_mov_b32_e32 v83, v2
	v_mov_b32_e32 v84, v2
	v_mov_b32_e32 v85, v2
	v_mov_b32_e32 v86, v2
	v_mov_b32_e32 v87, v2
	v_mov_b32_e32 v88, v2
	v_mov_b32_e32 v89, v2
	v_mov_b32_e32 v90, v2
	v_mov_b32_e32 v91, v2
	v_mov_b32_e32 v92, v2
	v_mov_b32_e32 v93, v2
	v_mov_b32_e32 v94, v2
	v_mov_b32_e32 v95, v2
	v_mov_b32_e32 v96, v2
	v_mov_b32_e32 v97, v2
	v_mov_b32_e32 v98, v2
	v_mov_b32_e32 v99, v2
	v_mov_b32_e32 v100, v2
	v_mov_b32_e32 v101, v2
	v_mov_b32_e32 v102, v2
	v_mov_b32_e32 v103, v2
	v_mov_b32_e32 v104, v2
	v_mov_b32_e32 v105, v2
	v_mov_b32_e32 v106, v2
	v_mov_b32_e32 v107, v2
	v_mov_b32_e32 v108, v2
	v_mov_b32_e32 v109, v2
	v_mov_b32_e32 v110, v2
	v_mov_b32_e32 v111, v2
	v_mov_b32_e32 v112, v2
	v_mov_b32_e32 v113, v2
	v_mov_b32_e32 v114, v2
	v_mov_b32_e32 v115, v2
	v_mov_b32_e32 v116, v2
	v_mov_b32_e32 v117, v2
	v_mov_b32_e32 v118, v2
	v_mov_b32_e32 v119, v2
	v_mov_b32_e32 v120, v2
	v_mov_b32_e32 v121, v2
	v_mov_b32_e32 v122, v2
	v_mov_b32_e32 v123, v2
	v_mov_b32_e32 v124, v2
	v_mov_b32_e32 v125, v2
	v_mov_b32_e32 v126, v2
	v_mov_b32_e32 v127, v2
	v_mov_b32_e32 v128, v2
	v_mov_b32_e32 v129, v2
	v_mov_b32_e32 v131, v130
	v_mov_b32_e32 v132, v130
	v_mov_b32_e32 v133, v130
	v_mov_b32_e32 v134, v130
	v_mov_b32_e32 v135, v130
	v_mov_b32_e32 v136, v130
	v_mov_b32_e32 v137, v130
	v_mov_b32_e32 v138, v130
	v_mov_b32_e32 v139, v130
	v_mov_b32_e32 v140, v130
	v_mov_b32_e32 v141, v130
	v_mov_b32_e32 v146, v130
	v_mov_b32_e32 v147, v130
	v_mov_b32_e32 v148, v130
	v_mov_b32_e32 v149, v130
	v_mov_b32_e32 v142, v130
	v_mov_b32_e32 v143, v130
	v_mov_b32_e32 v144, v130
	v_mov_b32_e32 v145, v130
	v_mov_b32_e32 v150, v130
	v_mov_b32_e32 v151, v130
	v_mov_b32_e32 v152, v130
	v_mov_b32_e32 v153, v130
	s_waitcnt vmcnt(0) lgkmcnt(0)
	s_barrier
	s_ashr_i32 s7, s12, 31
	s_mov_b32 s6, s12
	s_lshl_b64 s[6:7], s[6:7], 11
	s_add_u32 s6, s90, s6
	s_addc_u32 s7, s91, s7
	s_ashr_i32 s9, s14, 31
	s_mov_b32 s8, s14
	s_lshl_b64 s[8:9], s[8:9], 11
	v_readlane_b32 s10, v253, 43
	v_readlane_b32 s11, v253, 44
	s_add_u32 s8, s10, s8
	s_addc_u32 s9, s11, s9
	s_mov_b32 s11, 0
	s_mov_b32 s10, 0x10000
	s_cmp_eq_u32 s101, 1
	s_cbranch_scc0 .Lg8_qa_p0
	s_barrier

; template <bool SWAP>
; DI void gemm_mainloop(f32x16 (&acc)[4][2], const u16* __restrict__ A, int lda, int rlo, int rhi,
;                       const u16* __restrict__ B, int ldb, int K, char* lds, const u16* zero_line) {
;     ...
;   const int gch = (lc ^ ((lr >> 1) & 7)) * 8;
;   const u16* ap = A + (ptrdiff_t)lr * lda + gch;
;   const u16* bp = B + (ptrdiff_t)lr * ldb + gch;
;   const int nk = K >> 6;
;   typedef __attribute__((address_space(3))) unsigned lds_u32;
;   auto glds = [&](int kt, int st) {
;     char* as_ = lds + st * 65536 + tid * 16;
; #pragma unroll
;     for (int i = 0; i < 4; ++i) {
;       const int rr = lr + 64 * i;
;       const u16* srca = (rr >= rlo && rr < rhi) ? (ap + (ptrdiff_t)(64 * i) * lda + kt * 64) : (zero_line + lc * 8);
;       __builtin_amdgcn_global_load_lds((const unsigned*)srca, (lds_u32*)(as_ + i * 8192), 16, 0, 0);
;       __builtin_amdgcn_global_load_lds((const unsigned*)(bp + (ptrdiff_t)(64 * i) * ldb + kt * 64), (lds_u32*)(as_ + 32768 + i * 8192), 16, 0, 0);
;     }
;   };
;   const int sw = (r >> 1) & 7;
;   const int arow_off = (wm * 128 + r) * 128;
;   const int brow_off = 32768 + (wn * 64 + r) * 128;
;   __syncthreads();
;   glds(0, 0);
;   asm volatile("s_waitcnt vmcnt(0)" ::: "memory");
;   __syncthreads();
; template <int EPI>
; DI void phase_gemm(const Params& p, const GemmArgs& ga, char* lds) {
;     ...
;     if (EPI == EPI_M) swap = true;
;     else if (EPI == EPI_UP) swap = true;
;     else if (EPI == EPI_QKV1) swap = (nt < 8);
;     else swap = !(nt == 4 || nt == 5);
;     if (swap) gemm_mainloop<true>(acc, A, ga.lda, rlo, rhi, B, ga.K, ga.K, lds, (const u16*)(p.ws + OFF_ZERO));
;     else gemm_mainloop<false>(acc, A, ga.lda, rlo, rhi, B, ga.K, ga.K, lds, (const u16*)(p.ws + OFF_ZERO));
.LBB0_203:
	s_and_b64 vcc, exec, s[6:7]
	s_cbranch_vccz .LBB0_209
	s_nop 9
	v_mov_b32_e32 v12, v204
	s_mov_b64 s[10:11], 0x20000
	v_ashrrev_i32_e32 v2, 3, v12
	v_lshrrev_b32_e32 v14, 1, v2
	v_xor_b32_e32 v0, v14, v12
	v_ashrrev_i32_e32 v3, 31, v2
	v_lshlrev_b64 v[4:5], 11, v[2:3]
	v_lshlrev_b32_e32 v0, 4, v0
	v_and_b32_e32 v10, 31, v12
	v_lshl_add_u64 v[6:7], s[20:21], 0, v[4:5]
	v_and_b32_e32 v0, 0x70, v0
	v_lshl_add_u64 v[8:9], s[22:23], 0, v[4:5]
	v_lshrrev_b32_e32 v15, 1, v12
	v_lshl_add_u64 v[6:7], v[6:7], 0, v[0:1]
	v_lshl_add_u64 v[8:9], v[8:9], 0, v[0:1]
	v_and_or_b32 v0, v15, s51, v10
	v_lshlrev_b32_e32 v169, 7, v0
	v_lshlrev_b32_e32 v0, 7, v12
	v_lshlrev_b32_e32 v171, 4, v12
	v_and_b32_e32 v170, 0x6f80, v0
	v_and_b32_e32 v0, 0x70, v171
	v_add_u32_e32 v172, 0x8000, v171
	v_lshl_add_u64 v[156:157], s[80:81], 0, v[0:1]
	v_cmp_gt_u32_e32 vcc, s50, v2
	v_readfirstlane_b32 s6, v171
	s_mov_b32 m0, s6
	v_cndmask_b32_e32 v11, v157, v7, vcc
	v_cndmask_b32_e32 v10, v156, v6, vcc
	v_readfirstlane_b32 s6, v172
	v_add_u32_e32 v0, 64, v2
	v_add_u32_e32 v173, 0x2000, v171
	s_barrier
	s_mov_b32 m0, s6
	v_lshl_add_u64 v[10:11], v[6:7], 0, s[10:11]
	v_cmp_gt_u32_e64 s[6:7], s50, v0
	v_readfirstlane_b32 s8, v173
	v_add_u32_e32 v174, 0xa000, v171
	v_cndmask_b32_e64 v11, v157, v11, s[6:7]
	v_cndmask_b32_e64 v10, v156, v10, s[6:7]
	s_mov_b32 m0, s8
	v_readfirstlane_b32 s8, v174
	v_lshl_add_u64 v[10:11], v[8:9], 0, s[10:11]
	s_mov_b32 m0, s8
	v_add_u32_e32 v0, 0x80, v2
	s_mov_b64 s[20:21], 0x40000
	v_add_u32_e32 v175, 0x4000, v171
	v_lshl_add_u64 v[10:11], v[6:7], 0, s[20:21]
	v_cmp_gt_u32_e64 s[8:9], s50, v0
	v_readfirstlane_b32 s10, v175
	v_add_u32_e32 v176, 0xc000, v171
	v_cndmask_b32_e64 v11, v157, v11, s[8:9]
	v_cndmask_b32_e64 v10, v156, v10, s[8:9]
	s_mov_b32 m0, s10
	v_readfirstlane_b32 s10, v176
	v_add_u32_e32 v0, 0xc0, v2
	s_mov_b64 s[22:23], 0x60000
	v_add_u32_e32 v177, 0x6000, v171
	v_lshl_add_u64 v[10:11], v[8:9], 0, s[20:21]
	s_mov_b32 m0, s10
	v_lshl_add_u64 v[2:3], v[6:7], 0, s[22:23]
	v_cmp_gt_u32_e64 s[10:11], s50, v0
	v_readfirstlane_b32 s20, v177
	v_add_u32_e32 v178, 0xe000, v171
	v_cndmask_b32_e64 v3, v157, v3, s[10:11]
	v_cndmask_b32_e64 v2, v156, v2, s[10:11]
	s_mov_b32 m0, s20
	v_readfirstlane_b32 s20, v178
	v_lshl_add_u64 v[2:3], v[8:9], 0, s[22:23]
	s_mov_b32 m0, s20
	v_bfe_u32 v13, v12, 5, 1
	v_bfe_u32 v16, v12, 1, 3
	v_bitop3_b32 v0, v15, v13, 7 bitop3:0x6c
	s_sub_i32 s20, s28, s31
	v_lshlrev_b32_e32 v179, 4, v0
	v_bitop3_b32 v0, v13, v16, 2 bitop3:0x36
	s_sub_i32 s13, s20, s13
	v_lshlrev_b32_e32 v180, 4, v0
	v_bitop3_b32 v0, v13, v16, 4 bitop3:0x36
	s_lshl_b32 s20, s13, 8
	v_lshlrev_b32_e32 v181, 4, v0
	v_bitop3_b32 v0, v13, v16, 6 bitop3:0x36
	s_ashr_i32 s21, s20, 31
	v_lshlrev_b32_e32 v182, 4, v0
	s_lshl_b64 s[20:21], s[20:21], 11
	v_bitop3_b32 v0, v14, 7, v12 bitop3:0x48
	v_lshl_add_u64 v[2:3], v[4:5], 0, s[20:21]
	v_lshlrev_b32_e32 v0, 4, v0
	v_or_b32_e32 v2, v2, v0
	v_lshl_add_u64 v[158:159], s[70:71], 0, v[2:3]
	v_lshl_add_u64 v[2:3], v[4:5], 0, s[18:19]
	s_waitcnt vmcnt(0)
	s_ashr_i32 s7, s12, 31
	s_mov_b32 s6, s12
	s_lshl_b64 s[6:7], s[6:7], 11
	s_add_u32 s6, s90, s6
	s_addc_u32 s7, s91, s7
	s_ashr_i32 s9, s14, 31
	s_mov_b32 s8, s14
	s_lshl_b64 s[8:9], s[8:9], 11
	v_readlane_b32 s10, v253, 43
	v_readlane_b32 s11, v253, 44
	s_add_u32 s8, s10, s8
	s_addc_u32 s9, s11, s9
	v_and_b32_e32 v130, 63, v204
	v_lshrrev_b32_e32 v131, 6, v204
	v_lshrrev_b32_e32 v132, 3, v204
	v_lshrrev_b32_e32 v0, 4, v130
	v_lshl_add_u32 v0, v131, 2, v0
	v_xor_b32_e32 v0, v0, v130
	v_and_b32_e32 v0, 7, v0
	v_lshlrev_b32_e32 v133, 4, v0
	v_lshl_add_u32 v232, v132, 11, v133
	v_add_u32_e32 v233, 0x20000, v232
	v_add_u32_e32 v234, 0x40000, v232
	v_add_u32_e32 v235, 0x60000, v232
	v_and_b32_e32 v0, 31, v132
	v_lshrrev_b32_e32 v130, 5, v132
	v_lshl_add_u32 v0, v130, 6, v0
	v_lshl_add_u32 v236, v0, 11, v133
	v_add_u32_e32 v237, 0x10000, v236
	v_add_u32_e32 v238, 0x40000, v236
	v_add_u32_e32 v239, 0x50000, v236
	v_and_b32_e32 v132, 31, v204
	v_lshrrev_b32_e32 v0, 2, v131
	v_lshl_add_u32 v0, v0, 6, v132
	v_lshlrev_b32_e32 v244, 7, v0
	v_and_b32_e32 v0, 3, v131
	v_lshl_add_u32 v0, v0, 5, v132
	v_lshlrev_b32_e32 v245, 7, v0
	v_bfe_u32 v0, v204, 5, 1
	v_bfe_u32 v130, v132, 1, 3
	v_or_b32_e32 v133, 0, v0
	v_xor_b32_e32 v133, v133, v130
	v_lshlrev_b32_e32 v240, 4, v133
	v_or_b32_e32 v133, 2, v0
	v_xor_b32_e32 v133, v133, v130
	v_lshlrev_b32_e32 v241, 4, v133
	v_or_b32_e32 v133, 4, v0
	v_xor_b32_e32 v133, v133, v130
	v_lshlrev_b32_e32 v242, 4, v133
	v_or_b32_e32 v133, 6, v0
	v_xor_b32_e32 v133, v133, v130
	v_lshlrev_b32_e32 v243, 4, v133
	v_lshlrev_b32_e32 v131, 10, v131
	s_nop 0
	v_readfirstlane_b32 s100, v131
	v_mov_b32_e32 v146, 0
	v_mov_b32_e32 v147, 0
	v_mov_b32_e32 v148, 0
	v_mov_b32_e32 v149, 0
	v_lshlrev_b32_e32 v130, 4, v204
	v_add_u32_e32 v132, 0x10000, v130
	s_mov_b64 exec, -1
	s_mov_b32 s11, 0
	s_mov_b32 s10, 0x10000
	s_waitcnt lgkmcnt(0)
; template <bool SWAP>
; DI void gemm_mainloop(f32x16 (&acc)[4][2], const u16* __restrict__ A, int lda, int rlo, int rhi,
;                       const u16* __restrict__ B, int ldb, int K, char* lds, const u16* zero_line) {
;     ...
; #pragma unroll
;   for (int mi = 0; mi < 4; ++mi)
; #pragma unroll
;     for (int ni = 0; ni < 2; ++ni)
; #pragma unroll
;       for (int i = 0; i < 16; ++i) acc[mi][ni][i] = 0.f;
;     ...
;   auto glds = [&](int kt, int st) {
;     char* as_ = lds + st * 65536 + tid * 16;
; #pragma unroll
;     for (int i = 0; i < 4; ++i) {
;       const int rr = lr + 64 * i;
;       const u16* srca = (rr >= rlo && rr < rhi) ? (ap + (ptrdiff_t)(64 * i) * lda + kt * 64) : (zero_line + lc * 8);
;       __builtin_amdgcn_global_load_lds((const unsigned*)srca, (lds_u32*)(as_ + i * 8192), 16, 0, 0);
;       __builtin_amdgcn_global_load_lds((const unsigned*)(bp + (ptrdiff_t)(64 * i) * ldb + kt * 64), (lds_u32*)(as_ + 32768 + i * 8192), 16, 0, 0);
;     }
;   };
;   const int sw = (r >> 1) & 7;
;   const int arow_off = (wm * 128 + r) * 128;
;   const int brow_off = 32768 + (wn * 64 + r) * 128;
;   __syncthreads();
;   glds(0, 0);
;   asm volatile("s_waitcnt vmcnt(0)" ::: "memory");
;   __syncthreads();
	s_add_u32 m0, s100, 0x8000
	s_nop 0
	global_load_lds_dwordx4 v236, s[8:9]
	v_add_u32_e32 v236, 0x80, v236
	s_add_u32 m0, s100, 0xa000
	s_nop 0
	global_load_lds_dwordx4 v238, s[8:9]
	v_add_u32_e32 v238, 0x80, v238
	s_add_u32 m0, s100, 0x0
	s_nop 0
	global_load_lds_dwordx4 v232, s[6:7]
	v_add_u32_e32 v232, 0x80, v232
	s_add_u32 m0, s100, 0x2000
	s_nop 0
	global_load_lds_dwordx4 v234, s[6:7]
	v_add_u32_e32 v234, 0x80, v234
	s_add_u32 m0, s100, 0xc000
	s_nop 0
	global_load_lds_dwordx4 v237, s[8:9]
	v_add_u32_e32 v237, 0x80, v237
	s_add_u32 m0, s100, 0xe000
	s_nop 0
	global_load_lds_dwordx4 v239, s[8:9]
	v_add_u32_e32 v239, 0x80, v239
	s_add_u32 m0, s100, 0x4000
	s_nop 0
	global_load_lds_dwordx4 v233, s[6:7]
	v_add_u32_e32 v233, 0x80, v233
	s_add_u32 m0, s100, 0x6000
	s_nop 0
	global_load_lds_dwordx4 v235, s[6:7]
	v_add_u32_e32 v235, 0x80, v235
	v_lshl_add_u64 v[2:3], v[2:3], 0, v[0:1]
	v_lshl_add_u64 v[160:161], s[70:71], 0, v[2:3]
	v_mov_b32_e32 v130, 0
	v_mov_b32_e32 v2, 0
	s_mov_b32 s15, 1
	v_add_u32_e32 v183, 0x10000, v171
	v_add_u32_e32 v185, 0x18000, v171
	v_add_u32_e32 v186, 0x12000, v171
	v_add_u32_e32 v187, 0x1a000, v171
	v_add_u32_e32 v188, 0x14000, v171
	v_add_u32_e32 v189, 0x1c000, v171
	v_add_u32_e32 v190, 0x16000, v171
	v_add_u32_e32 v191, 0x1e000, v171
	v_add_u32_e32 v192, 0x10000, v169
	v_or_b32_e32 v193, 0x10000, v170
	s_mov_b64 s[18:19], 0
	v_mov_b32_e32 v3, v2
	v_mov_b32_e32 v4, v2
	v_mov_b32_e32 v5, v2
	v_mov_b32_e32 v6, v2
	v_mov_b32_e32 v7, v2
	v_mov_b32_e32 v8, v2
	v_mov_b32_e32 v9, v2
	v_mov_b32_e32 v10, v2
	v_mov_b32_e32 v11, v2
	v_mov_b32_e32 v12, v2
	v_mov_b32_e32 v13, v2
	v_mov_b32_e32 v14, v2
	v_mov_b32_e32 v15, v2
	v_mov_b32_e32 v16, v2
	v_mov_b32_e32 v17, v2
	v_mov_b32_e32 v18, v2
	v_mov_b32_e32 v19, v2
	v_mov_b32_e32 v20, v2
	v_mov_b32_e32 v21, v2
	v_mov_b32_e32 v22, v2
	v_mov_b32_e32 v23, v2
	v_mov_b32_e32 v24, v2
	v_mov_b32_e32 v25, v2
	v_mov_b32_e32 v26, v2
	v_mov_b32_e32 v27, v2
	v_mov_b32_e32 v28, v2
	v_mov_b32_e32 v29, v2
	v_mov_b32_e32 v30, v2
	v_mov_b32_e32 v31, v2
	v_mov_b32_e32 v32, v2
	v_mov_b32_e32 v33, v2
	v_mov_b32_e32 v34, v2
	v_mov_b32_e32 v35, v2
	v_mov_b32_e32 v36, v2
	v_mov_b32_e32 v37, v2
	v_mov_b32_e32 v38, v2
	v_mov_b32_e32 v39, v2
	v_mov_b32_e32 v40, v2
	v_mov_b32_e32 v41, v2
	v_mov_b32_e32 v42, v2
	v_mov_b32_e32 v43, v2
	v_mov_b32_e32 v44, v2
	v_mov_b32_e32 v45, v2
	v_mov_b32_e32 v46, v2
	v_mov_b32_e32 v47, v2
	v_mov_b32_e32 v48, v2
	v_mov_b32_e32 v49, v2
	v_mov_b32_e32 v50, v2
	v_mov_b32_e32 v51, v2
	v_mov_b32_e32 v52, v2
	v_mov_b32_e32 v53, v2
	v_mov_b32_e32 v54, v2
	v_mov_b32_e32 v55, v2
	v_mov_b32_e32 v56, v2
	v_mov_b32_e32 v57, v2
	v_mov_b32_e32 v58, v2
	v_mov_b32_e32 v59, v2
	v_mov_b32_e32 v60, v2
	v_mov_b32_e32 v61, v2
	v_mov_b32_e32 v62, v2
	v_mov_b32_e32 v63, v2
	v_mov_b32_e32 v64, v2
	v_mov_b32_e32 v65, v2
	v_mov_b32_e32 v66, v2
	v_mov_b32_e32 v67, v2
	v_mov_b32_e32 v68, v2
	v_mov_b32_e32 v69, v2
	v_mov_b32_e32 v70, v2
	v_mov_b32_e32 v71, v2
	v_mov_b32_e32 v72, v2
	v_mov_b32_e32 v73, v2
	v_mov_b32_e32 v74, v2
	v_mov_b32_e32 v75, v2
	v_mov_b32_e32 v76, v2
	v_mov_b32_e32 v77, v2
	v_mov_b32_e32 v78, v2
	v_mov_b32_e32 v79, v2
	v_mov_b32_e32 v80, v2
	v_mov_b32_e32 v81, v2
	v_mov_b32_e32 v82, v2
	v_mov_b32_e32 v83, v2
	v_mov_b32_e32 v84, v2
	v_mov_b32_e32 v85, v2
	v_mov_b32_e32 v86, v2
	v_mov_b32_e32 v87, v2
	v_mov_b32_e32 v88, v2
	v_mov_b32_e32 v89, v2
	v_mov_b32_e32 v90, v2
	v_mov_b32_e32 v91, v2
	v_mov_b32_e32 v92, v2
	v_mov_b32_e32 v93, v2
	v_mov_b32_e32 v94, v2
	v_mov_b32_e32 v95, v2
	v_mov_b32_e32 v96, v2
	v_mov_b32_e32 v97, v2
	v_mov_b32_e32 v98, v2
	v_mov_b32_e32 v99, v2
	v_mov_b32_e32 v100, v2
	v_mov_b32_e32 v101, v2
	v_mov_b32_e32 v102, v2
	v_mov_b32_e32 v103, v2
	v_mov_b32_e32 v104, v2
	v_mov_b32_e32 v105, v2
	v_mov_b32_e32 v106, v2
	v_mov_b32_e32 v107, v2
	v_mov_b32_e32 v108, v2
	v_mov_b32_e32 v109, v2
	v_mov_b32_e32 v110, v2
	v_mov_b32_e32 v111, v2
	v_mov_b32_e32 v112, v2
	v_mov_b32_e32 v113, v2
	v_mov_b32_e32 v114, v2
	v_mov_b32_e32 v115, v2
	v_mov_b32_e32 v116, v2
	v_mov_b32_e32 v117, v2
	v_mov_b32_e32 v118, v2
	v_mov_b32_e32 v119, v2
	v_mov_b32_e32 v120, v2
	v_mov_b32_e32 v121, v2
	v_mov_b32_e32 v122, v2
	v_mov_b32_e32 v123, v2
	v_mov_b32_e32 v124, v2
	v_mov_b32_e32 v125, v2
	v_mov_b32_e32 v126, v2
	v_mov_b32_e32 v127, v2
	v_mov_b32_e32 v128, v2
	v_mov_b32_e32 v129, v2
	v_mov_b32_e32 v131, v130
	v_mov_b32_e32 v132, v130
	v_mov_b32_e32 v133, v130
	v_mov_b32_e32 v134, v130
	v_mov_b32_e32 v135, v130
	v_mov_b32_e32 v136, v130
	v_mov_b32_e32 v137, v130
	v_mov_b32_e32 v138, v130
	v_mov_b32_e32 v139, v130
	v_mov_b32_e32 v140, v130
	v_mov_b32_e32 v141, v130
	v_mov_b32_e32 v146, v130
	v_mov_b32_e32 v147, v130
	v_mov_b32_e32 v148, v130
	v_mov_b32_e32 v149, v130
	v_mov_b32_e32 v142, v130
	v_mov_b32_e32 v143, v130
	v_mov_b32_e32 v144, v130
	v_mov_b32_e32 v145, v130
	v_mov_b32_e32 v150, v130
	v_mov_b32_e32 v151, v130
	v_mov_b32_e32 v152, v130
	v_mov_b32_e32 v153, v130
	s_waitcnt vmcnt(0) lgkmcnt(0)
	s_barrier
	s_ashr_i32 s7, s12, 31
	s_mov_b32 s6, s12
	s_lshl_b64 s[6:7], s[6:7], 11
	s_add_u32 s6, s90, s6
	s_addc_u32 s7, s91, s7
	s_ashr_i32 s9, s14, 31
	s_mov_b32 s8, s14
	s_lshl_b64 s[8:9], s[8:9], 11
	v_readlane_b32 s10, v253, 43
	v_readlane_b32 s11, v253, 44
	s_add_u32 s8, s10, s8
	s_addc_u32 s9, s11, s9
	s_mov_b32 s11, 0
	s_mov_b32 s10, 0x10000
	s_cmp_eq_u32 s101, 1
	s_cbranch_scc0 .Lg8_qb_p0
	s_barrier

; template <bool SWAP>
; DI void gemm_mainloop(f32x16 (&acc)[4][2], const u16* __restrict__ A, int lda, int rlo, int rhi,
;                       const u16* __restrict__ B, int ldb, int K, char* lds, const u16* zero_line) {
;     ...
;   const int gch = (lc ^ ((lr >> 1) & 7)) * 8;
;   const u16* ap = A + (ptrdiff_t)lr * lda + gch;
;   const u16* bp = B + (ptrdiff_t)lr * ldb + gch;
;   const int nk = K >> 6;
;   typedef __attribute__((address_space(3))) unsigned lds_u32;
;   auto glds = [&](int kt, int st) {
;     char* as_ = lds + st * 65536 + tid * 16;
; #pragma unroll
;     for (int i = 0; i < 4; ++i) {
;       const int rr = lr + 64 * i;
;       const u16* srca = (rr >= rlo && rr < rhi) ? (ap + (ptrdiff_t)(64 * i) * lda + kt * 64) : (zero_line + lc * 8);
;       __builtin_amdgcn_global_load_lds((const unsigned*)srca, (lds_u32*)(as_ + i * 8192), 16, 0, 0);
;       __builtin_amdgcn_global_load_lds((const unsigned*)(bp + (ptrdiff_t)(64 * i) * ldb + kt * 64), (lds_u32*)(as_ + 32768 + i * 8192), 16, 0, 0);
;     }
;   };
;   const int sw = (r >> 1) & 7;
;   const int arow_off = (wm * 128 + r) * 128;
;   const int brow_off = 32768 + (wn * 64 + r) * 128;
;   __syncthreads();
;   glds(0, 0);
;   asm volatile("s_waitcnt vmcnt(0)" ::: "memory");
;   __syncthreads();
; DI void tile_mn(int t, int Mt, int Nt, int& m, int& n) {
;   const int per = 8 * Nt;
;   int g = t / per;
;   int rem = t - g * per;
;   int gs = Mt - g * 8;
;   if (gs > 8) gs = 8;
;   n = rem / gs;
;   m = g * 8 + (rem - n * gs);
; }
.LBB0_244:
	s_add_i32 s6, s6, s27
	s_cmpk_gt_i32 s6, 0x2ff
	s_cbranch_scc1 .LBB0_243
	s_ashr_i32 s7, s6, 31
	s_lshr_b32 s7, s7, 27
	s_add_i32 s7, s6, s7
	s_ashr_i32 s35, s7, 5
	s_andn2_b32 s7, s7, 31
	s_sub_i32 s6, s6, s7
	s_ashr_i32 s7, s6, 31
	s_lshr_b32 s7, s7, 29
	s_add_i32 s7, s6, s7
	s_ashr_i32 s7, s7, 3
	s_lshl_b32 s8, s35, 11
	s_lshl_b32 s6, s6, 8
	s_lshl_b32 s24, s7, 8
	s_add_i32 s6, s6, s8
	s_lshl_b32 s36, s7, 11
	s_ashr_i32 s25, s24, 31
	s_sub_i32 s34, s6, s36
	s_mul_i32 s6, s25, s98
	s_mul_hi_u32 s7, s24, s98
	s_add_i32 s7, s7, s6
	s_mul_i32 s6, s24, s98
	s_lshl_b64 s[6:7], s[6:7], 1
	s_add_u32 s6, s16, s6
	v_mov_b32_e32 v10, v204
	s_addc_u32 s7, s17, s7
	s_ashr_i32 s8, s34, 31
	s_mul_i32 s8, s8, s98
	v_ashrrev_i32_e32 v2, 3, v10
	s_mul_hi_u32 s9, s34, s98
	v_mad_u64_u32 v[4:5], s[10:11], v2, s98, 0
	s_add_i32 s9, s9, s8
	s_mul_i32 s8, s34, s98
	v_ashrrev_i32_e32 v3, 31, v2
	v_mov_b32_e32 v0, v5
	s_lshl_b64 s[8:9], s[8:9], 1
	v_lshrrev_b32_e32 v12, 1, v2
	v_mad_u64_u32 v[6:7], s[10:11], v3, s98, v[0:1]
	s_add_u32 s8, s12, s8
	v_xor_b32_e32 v9, v12, v10
	v_mov_b32_e32 v5, v6
	s_addc_u32 s9, s13, s9
	v_lshlrev_b64 v[4:5], 1, v[4:5]
	v_lshlrev_b32_e32 v0, 4, v9
	v_and_b32_e32 v8, 31, v10
	v_lshl_add_u64 v[6:7], s[8:9], 0, v[4:5]
	v_and_b32_e32 v0, 0x70, v0
	v_lshl_add_u64 v[4:5], s[6:7], 0, v[4:5]
	v_lshrrev_b32_e32 v13, 1, v10
	v_lshl_add_u64 v[6:7], v[6:7], 0, v[0:1]
	v_lshl_add_u64 v[4:5], v[4:5], 0, v[0:1]
	v_and_or_b32 v0, v13, s51, v8
	v_lshlrev_b32_e32 v203, 7, v0
	v_lshlrev_b32_e32 v0, 7, v10
	v_lshlrev_b32_e32 v226, 4, v10
	v_and_b32_e32 v202, 0x6f80, v0
	v_and_b32_e32 v0, 0x70, v226
	v_add_u32_e32 v15, 0x8000, v226
	v_lshl_add_u64 v[180:181], s[80:81], 0, v[0:1]
	v_cmp_gt_u32_e32 vcc, s50, v2
	v_readfirstlane_b32 s6, v226
	s_mov_b32 m0, s6
	v_cndmask_b32_e32 v9, v181, v7, vcc
	v_cndmask_b32_e32 v8, v180, v6, vcc
	v_readfirstlane_b32 s6, v15
	v_add_u32_e32 v0, 64, v2
	s_barrier
	s_mov_b32 m0, s6
	v_cmp_gt_u32_e64 s[6:7], s50, v0
	v_add_u32_e32 v0, 0x2000, v226
	v_lshl_add_u64 v[6:7], v[6:7], 0, s[18:19]
	v_readfirstlane_b32 s8, v0
	v_add_u32_e32 v0, 0xa000, v226
	v_cndmask_b32_e64 v9, v181, v7, s[6:7]
	v_cndmask_b32_e64 v8, v180, v6, s[6:7]
	s_mov_b32 m0, s8
	v_readfirstlane_b32 s8, v0
	v_add_u32_e32 v0, 0x80, v2
	s_mov_b32 m0, s8
	v_cmp_gt_u32_e64 s[8:9], s50, v0
	v_add_u32_e32 v0, 0x4000, v226
	v_lshl_add_u64 v[4:5], v[4:5], 0, s[18:19]
	v_lshl_add_u64 v[6:7], v[6:7], 0, s[18:19]
	v_readfirstlane_b32 s10, v0
	v_add_u32_e32 v0, 0xc000, v226
	v_cndmask_b32_e64 v9, v181, v7, s[8:9]
	v_cndmask_b32_e64 v8, v180, v6, s[8:9]
	s_mov_b32 m0, s10
	v_readfirstlane_b32 s10, v0
	v_add_u32_e32 v0, 0xc0, v2
	s_mov_b32 m0, s10
	v_cmp_gt_u32_e64 s[10:11], s50, v0
	v_add_u32_e32 v0, 0x6000, v226
	v_lshl_add_u64 v[4:5], v[4:5], 0, s[18:19]
	v_lshl_add_u64 v[6:7], v[6:7], 0, s[18:19]
	v_readfirstlane_b32 s37, v0
	v_add_u32_e32 v0, 0xe000, v226
	v_cndmask_b32_e64 v7, v181, v7, s[10:11]
	v_cndmask_b32_e64 v6, v180, v6, s[10:11]
	s_mov_b32 m0, s37
	v_readfirstlane_b32 s37, v0
	v_lshl_add_u64 v[4:5], v[4:5], 0, s[18:19]
	s_mov_b32 m0, s37
	s_sub_i32 s36, s29, s36
	s_mulk_i32 s35, 0x1800
	s_sub_i32 s36, s36, s35
	s_ashr_i32 s37, s36, 31
	v_lshlrev_b64 v[2:3], 1, v[2:3]
	s_lshl_b64 s[36:37], s[36:37], 1
	v_lshl_add_u64 v[4:5], v[2:3], 0, s[36:37]
	v_mov_b64_e32 v[6:7], s[20:21]
	v_mad_u64_u32 v[182:183], s[38:39], s98, v4, v[6:7]
	v_mov_b32_e32 v4, v183
	v_mad_u64_u32 v[4:5], s[38:39], s98, v5, v[4:5]
	s_lshl_b64 s[38:39], s[24:25], 1
	v_bfe_u32 v11, v10, 5, 1
	v_mov_b32_e32 v183, v4
	v_lshl_add_u64 v[4:5], v[2:3], 0, s[38:39]
	v_mov_b64_e32 v[8:9], s[22:23]
	v_bfe_u32 v14, v10, 1, 3
	v_bitop3_b32 v0, v13, v11, 7 bitop3:0x6c
	v_mad_u64_u32 v[186:187], s[40:41], s98, v4, v[8:9]
	v_lshlrev_b32_e32 v228, 4, v0
	v_bitop3_b32 v0, v11, v14, 2 bitop3:0x36
	v_mov_b32_e32 v4, v187
	v_lshlrev_b32_e32 v227, 4, v0
	v_bitop3_b32 v0, v11, v14, 4 bitop3:0x36
	v_mad_u64_u32 v[4:5], s[40:41], s98, v5, v[4:5]
	v_lshlrev_b32_e32 v201, 4, v0
	v_bitop3_b32 v0, v11, v14, 6 bitop3:0x36
	v_mov_b32_e32 v187, v4
	v_lshl_add_u64 v[4:5], v[2:3], 0, s[4:5]
	v_lshlrev_b32_e32 v179, 4, v0
	v_bitop3_b32 v0, v12, 7, v10 bitop3:0x48
	v_lshl_add_u64 v[10:11], v[4:5], 0, s[36:37]
	v_lshl_add_u64 v[4:5], v[4:5], 0, s[38:39]
	v_mad_u64_u32 v[188:189], s[40:41], s98, v10, v[6:7]
	v_mad_u64_u32 v[190:191], s[40:41], s98, v4, v[8:9]
	v_mov_b32_e32 v10, v189
	v_mov_b32_e32 v4, v191
	v_mad_u64_u32 v[10:11], s[40:41], s98, v11, v[10:11]
	v_mad_u64_u32 v[4:5], s[40:41], s98, v5, v[4:5]
	s_mov_b64 s[40:41], 0x100
	v_mov_b32_e32 v191, v4
	v_lshl_add_u64 v[4:5], v[2:3], 0, s[40:41]
	v_mov_b32_e32 v189, v10
	v_lshl_add_u64 v[10:11], v[4:5], 0, s[36:37]
	v_lshl_add_u64 v[4:5], v[4:5], 0, s[38:39]
	v_mad_u64_u32 v[192:193], s[40:41], s98, v10, v[6:7]
	v_mad_u64_u32 v[194:195], s[40:41], s98, v4, v[8:9]
	v_mov_b32_e32 v10, v193
	v_mov_b32_e32 v4, v195
	v_mad_u64_u32 v[10:11], s[40:41], s98, v11, v[10:11]
	v_mad_u64_u32 v[4:5], s[40:41], s98, v5, v[4:5]
	s_mov_b64 s[40:41], 0x180
	s_nop 0
	v_lshl_add_u64 v[2:3], v[2:3], 0, s[40:41]
	v_mov_b32_e32 v195, v4
	v_lshl_add_u64 v[4:5], v[2:3], 0, s[36:37]
	v_lshl_add_u64 v[2:3], v[2:3], 0, s[38:39]
	v_mad_u64_u32 v[198:199], s[36:37], s98, v2, v[8:9]
	v_mad_u64_u32 v[196:197], s[36:37], s98, v4, v[6:7]
	v_mov_b32_e32 v2, v199
	s_waitcnt vmcnt(0)
; template <bool SWAP>
; DI void gemm_mainloop(f32x16 (&acc)[4][2], const u16* __restrict__ A, int lda, int rlo, int rhi,
;                       const u16* __restrict__ B, int ldb, int K, char* lds, const u16* zero_line) {
;     ...
; #pragma unroll
;   for (int mi = 0; mi < 4; ++mi)
; #pragma unroll
;     for (int ni = 0; ni < 2; ++ni)
; #pragma unroll
;       for (int i = 0; i < 16; ++i) acc[mi][ni][i] = 0.f;
;   const int gch = (lc ^ ((lr >> 1) & 7)) * 8;
;   const u16* ap = A + (ptrdiff_t)lr * lda + gch;
;   const u16* bp = B + (ptrdiff_t)lr * ldb + gch;
;   const int nk = K >> 6;
;   typedef __attribute__((address_space(3))) unsigned lds_u32;
;   auto glds = [&](int kt, int st) {
;     char* as_ = lds + st * 65536 + tid * 16;
; #pragma unroll
;     for (int i = 0; i < 4; ++i) {
;       const int rr = lr + 64 * i;
;       const u16* srca = (rr >= rlo && rr < rhi) ? (ap + (ptrdiff_t)(64 * i) * lda + kt * 64) : (zero_line + lc * 8);
;       __builtin_amdgcn_global_load_lds((const unsigned*)srca, (lds_u32*)(as_ + i * 8192), 16, 0, 0);
;       __builtin_amdgcn_global_load_lds((const unsigned*)(bp + (ptrdiff_t)(64 * i) * ldb + kt * 64), (lds_u32*)(as_ + 32768 + i * 8192), 16, 0, 0);
;     }
;   };
;   const int sw = (r >> 1) & 7;
;   const int arow_off = (wm * 128 + r) * 128;
;   const int brow_off = 32768 + (wn * 64 + r) * 128;
;   __syncthreads();
;   glds(0, 0);
;   asm volatile("s_waitcnt vmcnt(0)" ::: "memory");
;   __syncthreads();
	s_mul_i32 s6, s34, s98
	s_mul_hi_u32 s7, s34, s98
	s_lshl_b64 s[6:7], s[6:7], 1
	s_add_u32 s6, s12, s6
	s_addc_u32 s7, s13, s7
	s_mul_i32 s8, s24, s98
	s_mul_hi_u32 s9, s24, s98
	s_lshl_b64 s[8:9], s[8:9], 1
	s_add_u32 s8, s16, s8
	s_addc_u32 s9, s17, s9
	v_and_b32_e32 v130, 63, v204
	v_lshrrev_b32_e32 v131, 6, v204
	v_lshrrev_b32_e32 v132, 3, v204
	v_lshrrev_b32_e32 v0, 4, v130
	v_lshl_add_u32 v0, v131, 2, v0
	v_xor_b32_e32 v0, v0, v130
	v_and_b32_e32 v0, 7, v0
	v_lshlrev_b32_e32 v133, 4, v0
	v_mul_lo_u32 v0, v132, s98
	v_lshl_add_u32 v232, v0, 1, v133
	s_lshl_b32 s28, s98, 7
	v_add_u32_e32 v233, s28, v232
	v_add_u32_e32 v234, s28, v233
	v_add_u32_e32 v235, s28, v234
	v_and_b32_e32 v0, 31, v132
	v_lshrrev_b32_e32 v130, 5, v132
	v_lshl_add_u32 v0, v130, 6, v0
	v_mul_lo_u32 v0, v0, s98
	v_lshl_add_u32 v236, v0, 1, v133
	s_lshl_b32 s28, s98, 6
	v_add_u32_e32 v237, s28, v236
	s_lshl_b32 s28, s98, 8
	v_add_u32_e32 v238, s28, v236
	v_add_u32_e32 v239, s28, v237
	s_lshr_b32 s25, s98, 6
	s_add_i32 s25, s25, -2
	v_and_b32_e32 v132, 31, v204
	v_lshrrev_b32_e32 v0, 2, v131
	v_lshl_add_u32 v0, v0, 6, v132
	v_lshlrev_b32_e32 v244, 7, v0
	v_and_b32_e32 v0, 3, v131
	v_lshl_add_u32 v0, v0, 5, v132
	v_lshlrev_b32_e32 v245, 7, v0
	v_bfe_u32 v0, v204, 5, 1
	v_bfe_u32 v130, v132, 1, 3
	v_or_b32_e32 v133, 0, v0
	v_xor_b32_e32 v133, v133, v130
	v_lshlrev_b32_e32 v240, 4, v133
	v_or_b32_e32 v133, 2, v0
	v_xor_b32_e32 v133, v133, v130
	v_lshlrev_b32_e32 v241, 4, v133
	v_or_b32_e32 v133, 4, v0
	v_xor_b32_e32 v133, v133, v130
	v_lshlrev_b32_e32 v242, 4, v133
	v_or_b32_e32 v133, 6, v0
	v_xor_b32_e32 v133, v133, v130
	v_lshlrev_b32_e32 v243, 4, v133
	v_lshlrev_b32_e32 v131, 10, v131
	s_nop 0
	v_readfirstlane_b32 s100, v131
	v_mov_b32_e32 v146, 0
	v_mov_b32_e32 v147, 0
	v_mov_b32_e32 v148, 0
	v_mov_b32_e32 v149, 0
	v_lshlrev_b32_e32 v130, 4, v204
	v_add_u32_e32 v132, 0x10000, v130
	s_mov_b64 exec, -1
	s_mov_b32 s11, 0
	s_mov_b32 s10, 0x10000
	s_waitcnt lgkmcnt(0)
	s_add_u32 m0, s100, 0x8000
	s_nop 0
	global_load_lds_dwordx4 v236, s[8:9]
	v_add_u32_e32 v236, 0x80, v236
	s_add_u32 m0, s100, 0xa000
	s_nop 0
	global_load_lds_dwordx4 v238, s[8:9]
	v_add_u32_e32 v238, 0x80, v238
	s_add_u32 m0, s100, 0x0
	s_nop 0
	global_load_lds_dwordx4 v232, s[6:7]
	v_add_u32_e32 v232, 0x80, v232
	s_add_u32 m0, s100, 0x2000
	s_nop 0
	global_load_lds_dwordx4 v234, s[6:7]
	v_add_u32_e32 v234, 0x80, v234
	s_add_u32 m0, s100, 0xc000
	s_nop 0
	global_load_lds_dwordx4 v237, s[8:9]
	v_add_u32_e32 v237, 0x80, v237
	s_add_u32 m0, s100, 0xe000
	s_nop 0
	global_load_lds_dwordx4 v239, s[8:9]
	v_add_u32_e32 v239, 0x80, v239
	s_add_u32 m0, s100, 0x4000
	s_nop 0
	global_load_lds_dwordx4 v233, s[6:7]
	v_add_u32_e32 v233, 0x80, v233
	s_add_u32 m0, s100, 0x6000
	s_nop 0
	global_load_lds_dwordx4 v235, s[6:7]
	v_add_u32_e32 v235, 0x80, v235
	v_mov_b32_e32 v4, v197
	v_mad_u64_u32 v[2:3], s[36:37], s98, v3, v[2:3]
	v_mad_u64_u32 v[4:5], s[36:37], s98, v5, v[4:5]
	v_mov_b32_e32 v199, v2
	v_mov_b32_e32 v130, 0
	v_mov_b32_e32 v2, 0
	v_lshlrev_b32_e32 v0, 4, v0
	v_mov_b32_e32 v193, v10
	v_mov_b32_e32 v197, v4
	s_mov_b32 s25, 0x10000
	v_mov_b32_e32 v3, v2
	v_mov_b32_e32 v4, v2
	v_mov_b32_e32 v5, v2
	v_mov_b32_e32 v6, v2
	v_mov_b32_e32 v7, v2
	v_mov_b32_e32 v8, v2
	v_mov_b32_e32 v9, v2
	v_mov_b32_e32 v10, v2
	v_mov_b32_e32 v11, v2
	v_mov_b32_e32 v12, v2
	v_mov_b32_e32 v13, v2
	v_mov_b32_e32 v14, v2
	v_mov_b32_e32 v15, v2
	v_mov_b32_e32 v16, v2
	v_mov_b32_e32 v17, v2
	v_mov_b32_e32 v18, v2
	v_mov_b32_e32 v19, v2
	v_mov_b32_e32 v20, v2
	v_mov_b32_e32 v21, v2
	v_mov_b32_e32 v22, v2
	v_mov_b32_e32 v23, v2
	v_mov_b32_e32 v24, v2
	v_mov_b32_e32 v25, v2
	v_mov_b32_e32 v26, v2
	v_mov_b32_e32 v27, v2
	v_mov_b32_e32 v28, v2
	v_mov_b32_e32 v29, v2
	v_mov_b32_e32 v30, v2
	v_mov_b32_e32 v31, v2
	v_mov_b32_e32 v32, v2
	v_mov_b32_e32 v33, v2
	v_mov_b32_e32 v34, v2
	v_mov_b32_e32 v35, v2
	v_mov_b32_e32 v36, v2
	v_mov_b32_e32 v37, v2
	v_mov_b32_e32 v38, v2
	v_mov_b32_e32 v39, v2
	v_mov_b32_e32 v40, v2
	v_mov_b32_e32 v41, v2
	v_mov_b32_e32 v42, v2
	v_mov_b32_e32 v43, v2
	v_mov_b32_e32 v44, v2
	v_mov_b32_e32 v45, v2
	v_mov_b32_e32 v46, v2
	v_mov_b32_e32 v47, v2
	v_mov_b32_e32 v48, v2
	v_mov_b32_e32 v49, v2
	v_mov_b32_e32 v50, v2
	v_mov_b32_e32 v51, v2
	v_mov_b32_e32 v52, v2
	v_mov_b32_e32 v53, v2
	v_mov_b32_e32 v54, v2
	v_mov_b32_e32 v55, v2
	v_mov_b32_e32 v56, v2
	v_mov_b32_e32 v57, v2
	v_mov_b32_e32 v58, v2
	v_mov_b32_e32 v59, v2
	v_mov_b32_e32 v60, v2
	v_mov_b32_e32 v61, v2
	v_mov_b32_e32 v62, v2
	v_mov_b32_e32 v63, v2
	v_mov_b32_e32 v64, v2
	v_mov_b32_e32 v65, v2
	v_mov_b32_e32 v66, v2
	v_mov_b32_e32 v67, v2
	v_mov_b32_e32 v68, v2
	v_mov_b32_e32 v69, v2
	v_mov_b32_e32 v70, v2
	v_mov_b32_e32 v71, v2
	v_mov_b32_e32 v72, v2
	v_mov_b32_e32 v73, v2
	v_mov_b32_e32 v74, v2
	v_mov_b32_e32 v75, v2
	v_mov_b32_e32 v76, v2
	v_mov_b32_e32 v77, v2
	v_mov_b32_e32 v78, v2
	v_mov_b32_e32 v79, v2
	v_mov_b32_e32 v80, v2
	v_mov_b32_e32 v81, v2
	v_mov_b32_e32 v82, v2
	v_mov_b32_e32 v83, v2
	v_mov_b32_e32 v84, v2
	v_mov_b32_e32 v85, v2
	v_mov_b32_e32 v86, v2
	v_mov_b32_e32 v87, v2
	v_mov_b32_e32 v88, v2
	v_mov_b32_e32 v89, v2
	v_mov_b32_e32 v90, v2
	v_mov_b32_e32 v91, v2
	v_mov_b32_e32 v92, v2
	v_mov_b32_e32 v93, v2
	v_mov_b32_e32 v94, v2
	v_mov_b32_e32 v95, v2
	v_mov_b32_e32 v96, v2
	v_mov_b32_e32 v97, v2
	v_mov_b32_e32 v98, v2
	v_mov_b32_e32 v99, v2
	v_mov_b32_e32 v100, v2
	v_mov_b32_e32 v101, v2
	v_mov_b32_e32 v102, v2
	v_mov_b32_e32 v103, v2
	v_mov_b32_e32 v104, v2
	v_mov_b32_e32 v105, v2
	v_mov_b32_e32 v106, v2
	v_mov_b32_e32 v107, v2
	v_mov_b32_e32 v108, v2
	v_mov_b32_e32 v109, v2
	v_mov_b32_e32 v110, v2
	v_mov_b32_e32 v111, v2
	v_mov_b32_e32 v112, v2
	v_mov_b32_e32 v113, v2
	v_mov_b32_e32 v114, v2
	v_mov_b32_e32 v115, v2
	v_mov_b32_e32 v116, v2
	v_mov_b32_e32 v117, v2
	v_mov_b32_e32 v118, v2
	v_mov_b32_e32 v119, v2
	v_mov_b32_e32 v120, v2
	v_mov_b32_e32 v121, v2
	v_mov_b32_e32 v122, v2
	v_mov_b32_e32 v123, v2
	v_mov_b32_e32 v124, v2
	v_mov_b32_e32 v125, v2
	v_mov_b32_e32 v126, v2
	v_mov_b32_e32 v127, v2
	v_mov_b32_e32 v128, v2
	v_mov_b32_e32 v129, v2
	v_mov_b32_e32 v131, v130
	v_mov_b32_e32 v132, v130
	v_mov_b32_e32 v133, v130
	v_mov_b32_e32 v134, v130
	v_mov_b32_e32 v135, v130
	v_mov_b32_e32 v136, v130
	v_mov_b32_e32 v137, v130
	v_mov_b32_e32 v142, v130
	v_mov_b32_e32 v143, v130
	v_mov_b32_e32 v144, v130
	v_mov_b32_e32 v145, v130
	v_mov_b32_e32 v150, v130
	v_mov_b32_e32 v151, v130
	v_mov_b32_e32 v152, v130
	v_mov_b32_e32 v153, v130
	v_mov_b32_e32 v138, v130
	v_mov_b32_e32 v139, v130
	v_mov_b32_e32 v140, v130
	v_mov_b32_e32 v141, v130
	v_mov_b32_e32 v146, v130
	v_mov_b32_e32 v147, v130
	v_mov_b32_e32 v148, v130
	v_mov_b32_e32 v149, v130
	s_waitcnt vmcnt(0) lgkmcnt(0)
	s_barrier
; template <bool SWAP>
; DI void gemm_mainloop(f32x16 (&acc)[4][2], const u16* __restrict__ A, int lda, int rlo, int rhi,
;                       const u16* __restrict__ B, int ldb, int K, char* lds, const u16* zero_line) {
;     ...
;   auto glds = [&](int kt, int st) {
;     char* as_ = lds + st * 65536 + tid * 16;
; #pragma unroll
;     for (int i = 0; i < 4; ++i) {
;       const int rr = lr + 64 * i;
;       const u16* srca = (rr >= rlo && rr < rhi) ? (ap + (ptrdiff_t)(64 * i) * lda + kt * 64) : (zero_line + lc * 8);
;       __builtin_amdgcn_global_load_lds((const unsigned*)srca, (lds_u32*)(as_ + i * 8192), 16, 0, 0);
;       __builtin_amdgcn_global_load_lds((const unsigned*)(bp + (ptrdiff_t)(64 * i) * ldb + kt * 64), (lds_u32*)(as_ + 32768 + i * 8192), 16, 0, 0);
;     }
;   };
;   const int sw = (r >> 1) & 7;
;   const int arow_off = (wm * 128 + r) * 128;
;   const int brow_off = 32768 + (wn * 64 + r) * 128;
;   __syncthreads();
;   glds(0, 0);
;   asm volatile("s_waitcnt vmcnt(0)" ::: "memory");
;   __syncthreads();
;   bf16x8 fa[2][4], fb[2][2];
; #pragma unroll
;   for (int mi = 0; mi < 4; ++mi)
; #pragma unroll
;     for (int e = 0; e < 8; ++e) fa[1][mi][e] = 0;
; #pragma unroll
;   for (int ni = 0; ni < 2; ++ni)
; #pragma unroll
;     for (int e = 0; e < 8; ++e) fb[1][ni][e] = 0;
;   auto ldfrag = [&](const char* st, int ks, int buf) {
;     const int co = ((2 * ks + h) ^ sw) << 4;
; #pragma unroll
;     for (int mi = 0; mi < 4; ++mi) fa[buf][mi] = *(const bf16x8*)(st + arow_off + mi * 4096 + co);
; #pragma unroll
;     for (int ni = 0; ni < 2; ++ni) fb[buf][ni] = *(const bf16x8*)(st + brow_off + ni * 4096 + co);
;   };
;   auto mma = [&](int buf) {
; #pragma unroll
;     for (int mi = 0; mi < 4; ++mi)
; #pragma unroll
;       for (int ni = 0; ni < 2; ++ni)
;         acc[mi][ni] = SWAP ? MFMA(fb[buf][ni], fa[buf][mi], acc[mi][ni]) : MFMA(fa[buf][mi], fb[buf][ni], acc[mi][ni]);
;   };
;   auto pat_rd = [&]() {
; #pragma unroll
;     for (int g = 0; g < 6; ++g) {
;       __builtin_amdgcn_sched_group_barrier(0x100, 1, 0);
;       __builtin_amdgcn_sched_group_barrier(0x008, 1, 0);
;     }
;     __builtin_amdgcn_sched_group_barrier(0x008, 2, 0);
;   };
; #pragma unroll 2
;   for (int kt = 0; kt < nk; ++kt) {
;     const char* st = lds + (kt & 1) * 65536;
;     ldfrag(st, 0, 0);
;     mma(1);
;     pat_rd();
;     if (kt + 1 < nk) glds(kt + 1, (kt + 1) & 1);
	s_mul_i32 s6, s34, s98
	s_mul_hi_u32 s7, s34, s98
	s_lshl_b64 s[6:7], s[6:7], 1
	s_add_u32 s6, s12, s6
	s_addc_u32 s7, s13, s7
	s_mul_i32 s8, s24, s98
	s_mul_hi_u32 s9, s24, s98
	s_lshl_b64 s[8:9], s[8:9], 1
	s_add_u32 s8, s16, s8
	s_addc_u32 s9, s17, s9
	s_lshr_b32 s25, s98, 6
	s_add_i32 s25, s25, -2
	s_mov_b32 s11, 0
	s_mov_b32 s10, 0x10000
	s_cmp_eq_u32 s101, 1
	s_cbranch_scc0 .Lg8_m246_p0
	s_barrier
.Lg8_m246_p0:
	s_waitcnt vmcnt(4)
	s_barrier
	s_add_u32 m0, s100, 0x18000
	s_nop 0
	global_load_lds_dwordx4 v236, s[8:9]
	v_add_u32_e32 v236, 0x80, v236
	s_add_u32 m0, s100, 0x1a000
	s_nop 0
	global_load_lds_dwordx4 v238, s[8:9]
	v_add_u32_e32 v238, 0x80, v238
	s_add_u32 m0, s100, 0x10000
	s_nop 0
	global_load_lds_dwordx4 v232, s[6:7]
	v_add_u32_e32 v232, 0x80, v232
	s_add_u32 m0, s100, 0x12000
	s_nop 0
	global_load_lds_dwordx4 v234, s[6:7]
	v_add_u32_e32 v234, 0x80, v234
	s_add_u32 m0, s100, 0x1c000
	s_nop 0
	global_load_lds_dwordx4 v237, s[8:9]
	v_add_u32_e32 v237, 0x80, v237
	s_add_u32 m0, s100, 0x1e000
	s_nop 0
	global_load_lds_dwordx4 v239, s[8:9]
	v_add_u32_e32 v239, 0x80, v239
	s_waitcnt vmcnt(6)
	s_barrier
	v_add3_u32 v246, v245, v240, 0
	v_add3_u32 v247, v245, v241, 0
	v_add3_u32 v248, v245, v242, 0
	v_add3_u32 v249, v245, v243, 0
	ds_read_b128 v[162:165], v246 offset:32768
	ds_read_b128 v[166:169], v247 offset:32768
	ds_read_b128 v[170:173], v248 offset:32768
	ds_read_b128 v[174:177], v249 offset:32768
.Lg8_m246:
	v_add3_u32 v246, v244, v240, 0
	v_add3_u32 v247, v244, v241, 0
	v_add3_u32 v248, v244, v242, 0
	v_add3_u32 v249, v244, v243, 0
	ds_read_b128 v[130:133], v246
	ds_read_b128 v[134:137], v247
	ds_read_b128 v[138:141], v248
	ds_read_b128 v[142:145], v249
	ds_read_b128 v[146:149], v246 offset:4096
	ds_read_b128 v[150:153], v247 offset:4096
	ds_read_b128 v[154:157], v248 offset:4096
	ds_read_b128 v[158:161], v249 offset:4096
	s_add_u32 m0, s100, 0x14000
	s_nop 0
	global_load_lds_dwordx4 v233, s[6:7]
	v_add_u32_e32 v233, 0x80, v233
	s_add_u32 m0, s100, 0x16000
	s_nop 0
	global_load_lds_dwordx4 v235, s[6:7]
	v_add_u32_e32 v235, 0x80, v235
	s_barrier
	s_waitcnt lgkmcnt(0)
	v_mfma_f32_32x32x16_bf16 v[114:129], v[162:165], v[130:133], v[114:129]
	v_mfma_f32_32x32x16_bf16 v[82:97], v[162:165], v[146:149], v[82:97]
	v_mfma_f32_32x32x16_bf16 v[114:129], v[166:169], v[134:137], v[114:129]
	v_mfma_f32_32x32x16_bf16 v[82:97], v[166:169], v[150:153], v[82:97]
	v_mfma_f32_32x32x16_bf16 v[114:129], v[170:173], v[138:141], v[114:129]
	v_mfma_f32_32x32x16_bf16 v[82:97], v[170:173], v[154:157], v[82:97]
	v_mfma_f32_32x32x16_bf16 v[114:129], v[174:177], v[142:145], v[114:129]
	v_mfma_f32_32x32x16_bf16 v[82:97], v[174:177], v[158:161], v[82:97]
	s_barrier
	v_add3_u32 v246, v245, v240, 0
	v_add3_u32 v247, v245, v241, 0
	v_add3_u32 v248, v245, v242, 0
	v_add3_u32 v249, v245, v243, 0
	ds_read_b128 v[180:183], v246 offset:49152
	ds_read_b128 v[186:189], v247 offset:49152
	ds_read_b128 v[190:193], v248 offset:49152
	ds_read_b128 v[194:197], v249 offset:49152
	s_add_u32 m0, s100, 0x8000
	s_nop 0
	global_load_lds_dwordx4 v236, s[8:9]
	v_add_u32_e32 v236, 0x80, v236
	s_add_u32 m0, s100, 0xa000
	s_nop 0
	global_load_lds_dwordx4 v238, s[8:9]
	v_add_u32_e32 v238, 0x80, v238
	s_barrier
	s_waitcnt lgkmcnt(0)
	v_mfma_f32_32x32x16_bf16 v[98:113], v[180:183], v[130:133], v[98:113]
	v_mfma_f32_32x32x16_bf16 v[66:81], v[180:183], v[146:149], v[66:81]
	v_mfma_f32_32x32x16_bf16 v[98:113], v[186:189], v[134:137], v[98:113]
	v_mfma_f32_32x32x16_bf16 v[66:81], v[186:189], v[150:153], v[66:81]
	v_mfma_f32_32x32x16_bf16 v[98:113], v[190:193], v[138:141], v[98:113]
	v_mfma_f32_32x32x16_bf16 v[66:81], v[190:193], v[154:157], v[66:81]
	v_mfma_f32_32x32x16_bf16 v[98:113], v[194:197], v[142:145], v[98:113]
	v_mfma_f32_32x32x16_bf16 v[66:81], v[194:197], v[158:161], v[66:81]
	s_barrier
	v_add3_u32 v246, v244, v240, 0
	v_add3_u32 v247, v244, v241, 0
	v_add3_u32 v248, v244, v242, 0
	v_add3_u32 v249, v244, v243, 0
	ds_read_b128 v[130:133], v246 offset:16384
	ds_read_b128 v[134:137], v247 offset:16384
	ds_read_b128 v[138:141], v248 offset:16384
	ds_read_b128 v[142:145], v249 offset:16384
	ds_read_b128 v[146:149], v246 offset:20480
	ds_read_b128 v[150:153], v247 offset:20480
	ds_read_b128 v[154:157], v248 offset:20480
	ds_read_b128 v[158:161], v249 offset:20480
	s_add_u32 m0, s100, 0x0
	s_nop 0
	global_load_lds_dwordx4 v232, s[6:7]
	v_add_u32_e32 v232, 0x80, v232
	s_add_u32 m0, s100, 0x2000
	s_nop 0
	global_load_lds_dwordx4 v234, s[6:7]
	v_add_u32_e32 v234, 0x80, v234
	s_waitcnt vmcnt(10)
	s_barrier
	s_waitcnt lgkmcnt(0)
	v_mfma_f32_32x32x16_bf16 v[50:65], v[162:165], v[130:133], v[50:65]
	v_mfma_f32_32x32x16_bf16 v[18:33], v[162:165], v[146:149], v[18:33]
	v_mfma_f32_32x32x16_bf16 v[50:65], v[166:169], v[134:137], v[50:65]
	v_mfma_f32_32x32x16_bf16 v[18:33], v[166:169], v[150:153], v[18:33]
	v_mfma_f32_32x32x16_bf16 v[50:65], v[170:173], v[138:141], v[50:65]
	v_mfma_f32_32x32x16_bf16 v[18:33], v[170:173], v[154:157], v[18:33]
	v_mfma_f32_32x32x16_bf16 v[50:65], v[174:177], v[142:145], v[50:65]
	v_mfma_f32_32x32x16_bf16 v[18:33], v[174:177], v[158:161], v[18:33]
	s_barrier
	v_add3_u32 v246, v245, v240, s10
	v_add3_u32 v247, v245, v241, s10
	v_add3_u32 v248, v245, v242, s10
	v_add3_u32 v249, v245, v243, s10
	ds_read_b128 v[162:165], v246 offset:32768
	ds_read_b128 v[166:169], v247 offset:32768
	ds_read_b128 v[170:173], v248 offset:32768
	ds_read_b128 v[174:177], v249 offset:32768
	s_add_u32 m0, s100, 0xc000
	s_nop 0
	global_load_lds_dwordx4 v237, s[8:9]
	v_add_u32_e32 v237, 0x80, v237
	s_add_u32 m0, s100, 0xe000
	s_nop 0
	global_load_lds_dwordx4 v239, s[8:9]
	v_add_u32_e32 v239, 0x80, v239
	s_waitcnt vmcnt(6)
	s_barrier
; #define MFMA(a, b, c) __builtin_amdgcn_mfma_f32_32x32x16_bf16((a), (b), (c), 0, 0, 0)
; template <bool SWAP>
; DI void gemm_mainloop(f32x16 (&acc)[4][2], const u16* __restrict__ A, int lda, int rlo, int rhi,
;                       const u16* __restrict__ B, int ldb, int K, char* lds, const u16* zero_line) {
;     ...
;   auto ldfrag = [&](const char* st, int ks, int buf) {
;     const int co = ((2 * ks + h) ^ sw) << 4;
; #pragma unroll
;     for (int mi = 0; mi < 4; ++mi) fa[buf][mi] = *(const bf16x8*)(st + arow_off + mi * 4096 + co);
; #pragma unroll
;     for (int ni = 0; ni < 2; ++ni) fb[buf][ni] = *(const bf16x8*)(st + brow_off + ni * 4096 + co);
;   };
;   auto mma = [&](int buf) {
; #pragma unroll
;     for (int mi = 0; mi < 4; ++mi)
; #pragma unroll
;       for (int ni = 0; ni < 2; ++ni)
;         acc[mi][ni] = SWAP ? MFMA(fb[buf][ni], fa[buf][mi], acc[mi][ni]) : MFMA(fa[buf][mi], fb[buf][ni], acc[mi][ni]);
;   };
;   auto pat_rd = [&]() {
; #pragma unroll
;     for (int g = 0; g < 6; ++g) {
;       __builtin_amdgcn_sched_group_barrier(0x100, 1, 0);
;       __builtin_amdgcn_sched_group_barrier(0x008, 1, 0);
;     }
;     __builtin_amdgcn_sched_group_barrier(0x008, 2, 0);
;   };
; #pragma unroll 2
;   for (int kt = 0; kt < nk; ++kt) {
;     const char* st = lds + (kt & 1) * 65536;
;     ldfrag(st, 0, 0);
;     mma(1);
;     pat_rd();
;     if (kt + 1 < nk) glds(kt + 1, (kt + 1) & 1);
;     ldfrag(st, 1, 1);
;     mma(0);
;     pat_rd();
;     ldfrag(st, 2, 0);
;     mma(1);
;     pat_rd();
;     ldfrag(st, 3, 1);
;     mma(0);
;     pat_rd();
;     asm volatile("s_waitcnt vmcnt(0)" ::: "memory");
;     __syncthreads();
	s_waitcnt lgkmcnt(0)
	v_mfma_f32_32x32x16_bf16 v[34:49], v[180:183], v[130:133], v[34:49]
	v_mfma_f32_32x32x16_bf16 v[2:17], v[180:183], v[146:149], v[2:17]
	v_mfma_f32_32x32x16_bf16 v[34:49], v[186:189], v[134:137], v[34:49]
	v_mfma_f32_32x32x16_bf16 v[2:17], v[186:189], v[150:153], v[2:17]
	v_mfma_f32_32x32x16_bf16 v[34:49], v[190:193], v[138:141], v[34:49]
	v_mfma_f32_32x32x16_bf16 v[2:17], v[190:193], v[154:157], v[2:17]
	v_mfma_f32_32x32x16_bf16 v[34:49], v[194:197], v[142:145], v[34:49]
	v_mfma_f32_32x32x16_bf16 v[2:17], v[194:197], v[158:161], v[2:17]
	s_barrier
	v_add3_u32 v246, v244, v240, s10
	v_add3_u32 v247, v244, v241, s10
	v_add3_u32 v248, v244, v242, s10
	v_add3_u32 v249, v244, v243, s10
	ds_read_b128 v[130:133], v246
	ds_read_b128 v[134:137], v247
	ds_read_b128 v[138:141], v248
	ds_read_b128 v[142:145], v249
	ds_read_b128 v[146:149], v246 offset:4096
	ds_read_b128 v[150:153], v247 offset:4096
	ds_read_b128 v[154:157], v248 offset:4096
	ds_read_b128 v[158:161], v249 offset:4096
	s_add_u32 m0, s100, 0x4000
	s_nop 0
	global_load_lds_dwordx4 v233, s[6:7]
	v_add_u32_e32 v233, 0x80, v233
	s_add_u32 m0, s100, 0x6000
	s_nop 0
	global_load_lds_dwordx4 v235, s[6:7]
	v_add_u32_e32 v235, 0x80, v235
	s_barrier
	s_waitcnt lgkmcnt(0)
	v_mfma_f32_32x32x16_bf16 v[114:129], v[162:165], v[130:133], v[114:129]
	v_mfma_f32_32x32x16_bf16 v[82:97], v[162:165], v[146:149], v[82:97]
	v_mfma_f32_32x32x16_bf16 v[114:129], v[166:169], v[134:137], v[114:129]
	v_mfma_f32_32x32x16_bf16 v[82:97], v[166:169], v[150:153], v[82:97]
	v_mfma_f32_32x32x16_bf16 v[114:129], v[170:173], v[138:141], v[114:129]
	v_mfma_f32_32x32x16_bf16 v[82:97], v[170:173], v[154:157], v[82:97]
	v_mfma_f32_32x32x16_bf16 v[114:129], v[174:177], v[142:145], v[114:129]
	v_mfma_f32_32x32x16_bf16 v[82:97], v[174:177], v[158:161], v[82:97]
	s_barrier
	v_add3_u32 v246, v245, v240, s10
	v_add3_u32 v247, v245, v241, s10
	v_add3_u32 v248, v245, v242, s10
	v_add3_u32 v249, v245, v243, s10
	ds_read_b128 v[180:183], v246 offset:49152
	ds_read_b128 v[186:189], v247 offset:49152
	ds_read_b128 v[190:193], v248 offset:49152
	ds_read_b128 v[194:197], v249 offset:49152
	s_add_u32 m0, s100, 0x18000
	s_nop 0
	global_load_lds_dwordx4 v236, s[8:9]
	v_add_u32_e32 v236, 0x80, v236
	s_add_u32 m0, s100, 0x1a000
	s_nop 0
	global_load_lds_dwordx4 v238, s[8:9]
	v_add_u32_e32 v238, 0x80, v238
	s_barrier
	s_waitcnt lgkmcnt(0)
	v_mfma_f32_32x32x16_bf16 v[98:113], v[180:183], v[130:133], v[98:113]
	v_mfma_f32_32x32x16_bf16 v[66:81], v[180:183], v[146:149], v[66:81]
	v_mfma_f32_32x32x16_bf16 v[98:113], v[186:189], v[134:137], v[98:113]
	v_mfma_f32_32x32x16_bf16 v[66:81], v[186:189], v[150:153], v[66:81]
	v_mfma_f32_32x32x16_bf16 v[98:113], v[190:193], v[138:141], v[98:113]
	v_mfma_f32_32x32x16_bf16 v[66:81], v[190:193], v[154:157], v[66:81]
	v_mfma_f32_32x32x16_bf16 v[98:113], v[194:197], v[142:145], v[98:113]
	v_mfma_f32_32x32x16_bf16 v[66:81], v[194:197], v[158:161], v[66:81]
	s_barrier
	v_add3_u32 v246, v244, v240, s10
	v_add3_u32 v247, v244, v241, s10
	v_add3_u32 v248, v244, v242, s10
	v_add3_u32 v249, v244, v243, s10
	ds_read_b128 v[130:133], v246 offset:16384
	ds_read_b128 v[134:137], v247 offset:16384
	ds_read_b128 v[138:141], v248 offset:16384
	ds_read_b128 v[142:145], v249 offset:16384
	ds_read_b128 v[146:149], v246 offset:20480
	ds_read_b128 v[150:153], v247 offset:20480
	ds_read_b128 v[154:157], v248 offset:20480
	ds_read_b128 v[158:161], v249 offset:20480
	s_add_u32 m0, s100, 0x10000
	s_nop 0
	global_load_lds_dwordx4 v232, s[6:7]
	v_add_u32_e32 v232, 0x80, v232
	s_add_u32 m0, s100, 0x12000
	s_nop 0
	global_load_lds_dwordx4 v234, s[6:7]
	v_add_u32_e32 v234, 0x80, v234
	s_waitcnt vmcnt(10)
	s_barrier
	s_waitcnt lgkmcnt(0)
	v_mfma_f32_32x32x16_bf16 v[50:65], v[162:165], v[130:133], v[50:65]
	v_mfma_f32_32x32x16_bf16 v[18:33], v[162:165], v[146:149], v[18:33]
	v_mfma_f32_32x32x16_bf16 v[50:65], v[166:169], v[134:137], v[50:65]
	v_mfma_f32_32x32x16_bf16 v[18:33], v[166:169], v[150:153], v[18:33]
	v_mfma_f32_32x32x16_bf16 v[50:65], v[170:173], v[138:141], v[50:65]
	v_mfma_f32_32x32x16_bf16 v[18:33], v[170:173], v[154:157], v[18:33]
	v_mfma_f32_32x32x16_bf16 v[50:65], v[174:177], v[142:145], v[50:65]
	v_mfma_f32_32x32x16_bf16 v[18:33], v[174:177], v[158:161], v[18:33]
	s_barrier
	v_add3_u32 v246, v245, v240, 0
	v_add3_u32 v247, v245, v241, 0
	v_add3_u32 v248, v245, v242, 0
	v_add3_u32 v249, v245, v243, 0
	ds_read_b128 v[162:165], v246 offset:32768
	ds_read_b128 v[166:169], v247 offset:32768
	ds_read_b128 v[170:173], v248 offset:32768
	ds_read_b128 v[174:177], v249 offset:32768
	s_add_u32 m0, s100, 0x1c000
	s_nop 0
	global_load_lds_dwordx4 v237, s[8:9]
	v_add_u32_e32 v237, 0x80, v237
	s_add_u32 m0, s100, 0x1e000
	s_nop 0
	global_load_lds_dwordx4 v239, s[8:9]
	v_add_u32_e32 v239, 0x80, v239
	s_waitcnt vmcnt(6)
	s_barrier
	s_waitcnt lgkmcnt(0)
	v_mfma_f32_32x32x16_bf16 v[34:49], v[180:183], v[130:133], v[34:49]
	v_mfma_f32_32x32x16_bf16 v[2:17], v[180:183], v[146:149], v[2:17]
	v_mfma_f32_32x32x16_bf16 v[34:49], v[186:189], v[134:137], v[34:49]
	v_mfma_f32_32x32x16_bf16 v[2:17], v[186:189], v[150:153], v[2:17]
	v_mfma_f32_32x32x16_bf16 v[34:49], v[190:193], v[138:141], v[34:49]
	v_mfma_f32_32x32x16_bf16 v[2:17], v[190:193], v[154:157], v[2:17]
	v_mfma_f32_32x32x16_bf16 v[34:49], v[194:197], v[142:145], v[34:49]
	v_mfma_f32_32x32x16_bf16 v[2:17], v[194:197], v[158:161], v[2:17]
	s_barrier
	s_add_i32 s11, s11, 2
	s_cmp_lt_u32 s11, s25
	s_cbranch_scc1 .Lg8_m246
; template <bool SWAP>
; DI void gemm_mainloop(f32x16 (&acc)[4][2], const u16* __restrict__ A, int lda, int rlo, int rhi,
;                       const u16* __restrict__ B, int ldb, int K, char* lds, const u16* zero_line) {
;     ...
; #pragma unroll 2
;   for (int kt = 0; kt < nk; ++kt) {
;     const char* st = lds + (kt & 1) * 65536;
;     ldfrag(st, 0, 0);
;     mma(1);
;     pat_rd();
;     if (kt + 1 < nk) glds(kt + 1, (kt + 1) & 1);
;     ldfrag(st, 1, 1);
;     mma(0);
;     pat_rd();
;     ldfrag(st, 2, 0);
;     mma(1);
;     pat_rd();
;     ldfrag(st, 3, 1);
;     mma(0);
;     pat_rd();
;     asm volatile("s_waitcnt vmcnt(0)" ::: "memory");
;     __syncthreads();
;   }
;   mma(1);
	v_add3_u32 v246, v244, v240, 0
	v_add3_u32 v247, v244, v241, 0
	v_add3_u32 v248, v244, v242, 0
	v_add3_u32 v249, v244, v243, 0
	ds_read_b128 v[130:133], v246
	ds_read_b128 v[134:137], v247
	ds_read_b128 v[138:141], v248
	ds_read_b128 v[142:145], v249
	ds_read_b128 v[146:149], v246 offset:4096
	ds_read_b128 v[150:153], v247 offset:4096
	ds_read_b128 v[154:157], v248 offset:4096
	ds_read_b128 v[158:161], v249 offset:4096
	s_add_u32 m0, s100, 0x14000
	s_nop 0
	global_load_lds_dwordx4 v233, s[6:7]
	v_add_u32_e32 v233, 0x80, v233
	s_add_u32 m0, s100, 0x16000
	s_nop 0
	global_load_lds_dwordx4 v235, s[6:7]
	v_add_u32_e32 v235, 0x80, v235
	s_barrier
	s_waitcnt lgkmcnt(0)
	v_mfma_f32_32x32x16_bf16 v[114:129], v[162:165], v[130:133], v[114:129]
	v_mfma_f32_32x32x16_bf16 v[82:97], v[162:165], v[146:149], v[82:97]
	v_mfma_f32_32x32x16_bf16 v[114:129], v[166:169], v[134:137], v[114:129]
	v_mfma_f32_32x32x16_bf16 v[82:97], v[166:169], v[150:153], v[82:97]
	v_mfma_f32_32x32x16_bf16 v[114:129], v[170:173], v[138:141], v[114:129]
	v_mfma_f32_32x32x16_bf16 v[82:97], v[170:173], v[154:157], v[82:97]
	v_mfma_f32_32x32x16_bf16 v[114:129], v[174:177], v[142:145], v[114:129]
	v_mfma_f32_32x32x16_bf16 v[82:97], v[174:177], v[158:161], v[82:97]
	s_barrier
	v_add3_u32 v246, v245, v240, 0
	v_add3_u32 v247, v245, v241, 0
	v_add3_u32 v248, v245, v242, 0
	v_add3_u32 v249, v245, v243, 0
	ds_read_b128 v[180:183], v246 offset:49152
	ds_read_b128 v[186:189], v247 offset:49152
	ds_read_b128 v[190:193], v248 offset:49152
	ds_read_b128 v[194:197], v249 offset:49152
	s_barrier
	s_waitcnt lgkmcnt(0)
	v_mfma_f32_32x32x16_bf16 v[98:113], v[180:183], v[130:133], v[98:113]
	v_mfma_f32_32x32x16_bf16 v[66:81], v[180:183], v[146:149], v[66:81]
	v_mfma_f32_32x32x16_bf16 v[98:113], v[186:189], v[134:137], v[98:113]
	v_mfma_f32_32x32x16_bf16 v[66:81], v[186:189], v[150:153], v[66:81]
	v_mfma_f32_32x32x16_bf16 v[98:113], v[190:193], v[138:141], v[98:113]
	v_mfma_f32_32x32x16_bf16 v[66:81], v[190:193], v[154:157], v[66:81]
	v_mfma_f32_32x32x16_bf16 v[98:113], v[194:197], v[142:145], v[98:113]
	v_mfma_f32_32x32x16_bf16 v[66:81], v[194:197], v[158:161], v[66:81]
	s_barrier
	v_add3_u32 v246, v244, v240, 0
	v_add3_u32 v247, v244, v241, 0
	v_add3_u32 v248, v244, v242, 0
	v_add3_u32 v249, v244, v243, 0
	ds_read_b128 v[130:133], v246 offset:16384
	ds_read_b128 v[134:137], v247 offset:16384
	ds_read_b128 v[138:141], v248 offset:16384
	ds_read_b128 v[142:145], v249 offset:16384
	ds_read_b128 v[146:149], v246 offset:20480
	ds_read_b128 v[150:153], v247 offset:20480
	ds_read_b128 v[154:157], v248 offset:20480
	ds_read_b128 v[158:161], v249 offset:20480
	s_waitcnt vmcnt(4)
	s_barrier
	s_waitcnt lgkmcnt(0)
	v_mfma_f32_32x32x16_bf16 v[50:65], v[162:165], v[130:133], v[50:65]
	v_mfma_f32_32x32x16_bf16 v[18:33], v[162:165], v[146:149], v[18:33]
	v_mfma_f32_32x32x16_bf16 v[50:65], v[166:169], v[134:137], v[50:65]
	v_mfma_f32_32x32x16_bf16 v[18:33], v[166:169], v[150:153], v[18:33]
	v_mfma_f32_32x32x16_bf16 v[50:65], v[170:173], v[138:141], v[50:65]
	v_mfma_f32_32x32x16_bf16 v[18:33], v[170:173], v[154:157], v[18:33]
	v_mfma_f32_32x32x16_bf16 v[50:65], v[174:177], v[142:145], v[50:65]
	v_mfma_f32_32x32x16_bf16 v[18:33], v[174:177], v[158:161], v[18:33]
	v_mfma_f32_32x32x16_bf16 v[34:49], v[180:183], v[130:133], v[34:49]
	v_mfma_f32_32x32x16_bf16 v[2:17], v[180:183], v[146:149], v[2:17]
	v_mfma_f32_32x32x16_bf16 v[34:49], v[186:189], v[134:137], v[34:49]
	v_mfma_f32_32x32x16_bf16 v[2:17], v[186:189], v[150:153], v[2:17]
	v_mfma_f32_32x32x16_bf16 v[34:49], v[190:193], v[138:141], v[34:49]
	v_mfma_f32_32x32x16_bf16 v[2:17], v[190:193], v[154:157], v[2:17]
	v_mfma_f32_32x32x16_bf16 v[34:49], v[194:197], v[142:145], v[34:49]
	v_mfma_f32_32x32x16_bf16 v[2:17], v[194:197], v[158:161], v[2:17]
	s_barrier
; template <bool SWAP>
; DI void gemm_mainloop(f32x16 (&acc)[4][2], const u16* __restrict__ A, int lda, int rlo, int rhi,
;                       const u16* __restrict__ B, int ldb, int K, char* lds, const u16* zero_line) {
;     ...
; #pragma unroll 2
;   for (int kt = 0; kt < nk; ++kt) {
;     const char* st = lds + (kt & 1) * 65536;
;     ldfrag(st, 0, 0);
;     mma(1);
;     pat_rd();
;     if (kt + 1 < nk) glds(kt + 1, (kt + 1) & 1);
;     ldfrag(st, 1, 1);
;     mma(0);
;     pat_rd();
;     ldfrag(st, 2, 0);
;     mma(1);
;     pat_rd();
;     ldfrag(st, 3, 1);
;     mma(0);
;     pat_rd();
;     asm volatile("s_waitcnt vmcnt(0)" ::: "memory");
;     __syncthreads();
;   }
;   mma(1);
	v_add3_u32 v246, v245, v240, s10
	v_add3_u32 v247, v245, v241, s10
	v_add3_u32 v248, v245, v242, s10
	v_add3_u32 v249, v245, v243, s10
	ds_read_b128 v[162:165], v246 offset:32768
	ds_read_b128 v[166:169], v247 offset:32768
	ds_read_b128 v[170:173], v248 offset:32768
	ds_read_b128 v[174:177], v249 offset:32768
	v_add3_u32 v246, v244, v240, s10
	v_add3_u32 v247, v244, v241, s10
	v_add3_u32 v248, v244, v242, s10
	v_add3_u32 v249, v244, v243, s10
	ds_read_b128 v[130:133], v246
	ds_read_b128 v[134:137], v247
	ds_read_b128 v[138:141], v248
	ds_read_b128 v[142:145], v249
	ds_read_b128 v[146:149], v246 offset:4096
	ds_read_b128 v[150:153], v247 offset:4096
	ds_read_b128 v[154:157], v248 offset:4096
	ds_read_b128 v[158:161], v249 offset:4096
	s_waitcnt vmcnt(2)
	s_barrier
	s_waitcnt lgkmcnt(0)
	v_mfma_f32_32x32x16_bf16 v[114:129], v[162:165], v[130:133], v[114:129]
	v_mfma_f32_32x32x16_bf16 v[82:97], v[162:165], v[146:149], v[82:97]
	v_mfma_f32_32x32x16_bf16 v[114:129], v[166:169], v[134:137], v[114:129]
	v_mfma_f32_32x32x16_bf16 v[82:97], v[166:169], v[150:153], v[82:97]
	v_mfma_f32_32x32x16_bf16 v[114:129], v[170:173], v[138:141], v[114:129]
	v_mfma_f32_32x32x16_bf16 v[82:97], v[170:173], v[154:157], v[82:97]
	v_mfma_f32_32x32x16_bf16 v[114:129], v[174:177], v[142:145], v[114:129]
	v_mfma_f32_32x32x16_bf16 v[82:97], v[174:177], v[158:161], v[82:97]
	s_barrier
	v_add3_u32 v246, v245, v240, s10
	v_add3_u32 v247, v245, v241, s10
	v_add3_u32 v248, v245, v242, s10
	v_add3_u32 v249, v245, v243, s10
	ds_read_b128 v[180:183], v246 offset:49152
	ds_read_b128 v[186:189], v247 offset:49152
	ds_read_b128 v[190:193], v248 offset:49152
	ds_read_b128 v[194:197], v249 offset:49152
	s_waitcnt vmcnt(0)
	s_barrier
	s_waitcnt lgkmcnt(0)
	v_mfma_f32_32x32x16_bf16 v[98:113], v[180:183], v[130:133], v[98:113]
	v_mfma_f32_32x32x16_bf16 v[66:81], v[180:183], v[146:149], v[66:81]
	v_mfma_f32_32x32x16_bf16 v[98:113], v[186:189], v[134:137], v[98:113]
	v_mfma_f32_32x32x16_bf16 v[66:81], v[186:189], v[150:153], v[66:81]
	v_mfma_f32_32x32x16_bf16 v[98:113], v[190:193], v[138:141], v[98:113]
	v_mfma_f32_32x32x16_bf16 v[66:81], v[190:193], v[154:157], v[66:81]
	v_mfma_f32_32x32x16_bf16 v[98:113], v[194:197], v[142:145], v[98:113]
	v_mfma_f32_32x32x16_bf16 v[66:81], v[194:197], v[158:161], v[66:81]
	s_barrier
	v_add3_u32 v246, v244, v240, s10
	v_add3_u32 v247, v244, v241, s10
	v_add3_u32 v248, v244, v242, s10
	v_add3_u32 v249, v244, v243, s10
	ds_read_b128 v[130:133], v246 offset:16384
	ds_read_b128 v[134:137], v247 offset:16384
	ds_read_b128 v[138:141], v248 offset:16384
	ds_read_b128 v[142:145], v249 offset:16384
	ds_read_b128 v[146:149], v246 offset:20480
	ds_read_b128 v[150:153], v247 offset:20480
	ds_read_b128 v[154:157], v248 offset:20480
	ds_read_b128 v[158:161], v249 offset:20480
	s_barrier
	s_waitcnt lgkmcnt(0)
	v_mfma_f32_32x32x16_bf16 v[50:65], v[162:165], v[130:133], v[50:65]
	v_mfma_f32_32x32x16_bf16 v[18:33], v[162:165], v[146:149], v[18:33]
	v_mfma_f32_32x32x16_bf16 v[50:65], v[166:169], v[134:137], v[50:65]
	v_mfma_f32_32x32x16_bf16 v[18:33], v[166:169], v[150:153], v[18:33]
	v_mfma_f32_32x32x16_bf16 v[50:65], v[170:173], v[138:141], v[50:65]
	v_mfma_f32_32x32x16_bf16 v[18:33], v[170:173], v[154:157], v[18:33]
	v_mfma_f32_32x32x16_bf16 v[50:65], v[174:177], v[142:145], v[50:65]
	v_mfma_f32_32x32x16_bf16 v[18:33], v[174:177], v[158:161], v[18:33]
	v_mfma_f32_32x32x16_bf16 v[34:49], v[180:183], v[130:133], v[34:49]
	v_mfma_f32_32x32x16_bf16 v[2:17], v[180:183], v[146:149], v[2:17]
	v_mfma_f32_32x32x16_bf16 v[34:49], v[186:189], v[134:137], v[34:49]
	v_mfma_f32_32x32x16_bf16 v[2:17], v[186:189], v[150:153], v[2:17]
	v_mfma_f32_32x32x16_bf16 v[34:49], v[190:193], v[138:141], v[34:49]
	v_mfma_f32_32x32x16_bf16 v[2:17], v[190:193], v[154:157], v[2:17]
	v_mfma_f32_32x32x16_bf16 v[34:49], v[194:197], v[142:145], v[34:49]
	v_mfma_f32_32x32x16_bf16 v[2:17], v[194:197], v[158:161], v[2:17]
	s_barrier
	s_cmp_eq_u32 s101, 0
	s_cbranch_scc0 .Lg8_m246_p1
	s_barrier

; template <int EPI>
; DI void phase_gemm(const Params& p, const GemmArgs& ga, char* lds) {
;     ...
;   for (int it = 0; it * (int)gridDim.x < total; ++it) {
;     const int lt = logical_index(it);
;     if (lt >= total) continue;
;     int mt, nt;
;     tile_mn(lt, Mt, ga.Nt, mt, nt);
;     int bb, tokbase, S, pos0, rlo = 0, rhi = 256;
;     if (EPI == EPI_UP) {
;       bb = 0; tokbase = 0; S = NTOK;
;       pos0 = 254 * mt - 1;
;       rlo = (mt == 0) ? 1 : 0;
;       rhi = NTOK - pos0; if (rhi > 256) rhi = 256;
;     } else {
;       seq_of_token(mt * 256, bb, tokbase, S);
;       pos0 = mt * 256 - tokbase;
;     }
;     const u16* A = ga.A + (ptrdiff_t)(tokbase + pos0) * ga.lda;
;     const u16* B = ga.Bt + (size_t)(nt * 256) * ga.K;
;     f32x16 acc[4][2];
;     bool swap;
;     if (EPI == EPI_M) swap = true;
;     else if (EPI == EPI_UP) swap = true;
;     else if (EPI == EPI_QKV1) swap = (nt < 8);
;     else swap = !(nt == 4 || nt == 5);
;     if (swap) gemm_mainloop<true>(acc, A, ga.lda, rlo, rhi, B, ga.K, ga.K, lds, (const u16*)(p.ws + OFF_ZERO));
;     else gemm_mainloop<false>(acc, A, ga.lda, rlo, rhi, B, ga.K, ga.K, lds, (const u16*)(p.ws + OFF_ZERO));
.LBB0_315:
	s_add_i32 s6, s6, s25
	s_cmpk_gt_i32 s6, 0x6bf
	s_cbranch_scc1 .LBB0_314
	s_mul_hi_i32 s7, s6, 0x38e38e39
	s_lshr_b32 s8, s7, 31
	s_ashr_i32 s29, s7, 4
	s_add_i32 s29, s29, s8
	s_mul_i32 s7, s29, 0xffffffb8
	s_add_i32 s6, s7, s6
	s_ashr_i32 s8, s6, 31
	s_lshr_b32 s8, s8, 29
	s_lshl_b32 s7, s29, 3
	s_add_i32 s8, s6, s8
	s_add_i32 s6, s6, s7
	s_and_b32 s30, s8, -8
	s_sub_i32 s28, s6, s30
	s_lshl_b32 s12, s28, 8
	s_ashr_i32 s13, s12, 31
	s_ashr_i32 s9, s8, 3
	s_lshl_b64 s[6:7], s[12:13], 11
	s_add_u32 s14, s90, s6
	s_addc_u32 s15, s91, s7
	s_lshl_b32 s16, s9, 8
	s_ashr_i32 s17, s16, 31
	s_lshl_b64 s[6:7], s[16:17], 11
	s_add_u32 s20, s70, s6
	s_addc_u32 s21, s71, s7
	s_and_b32 s6, s9, -2
	s_cmp_lg_u32 s6, 4
	s_cselect_b64 s[18:19], -1, 0
	s_cmp_eq_u32 s6, 4
	s_mov_b64 s[6:7], -1
	s_cbranch_scc1 .LBB0_322
	s_waitcnt vmcnt(5)
	v_mov_b32_e32 v10, v204
	s_nop 0
	v_ashrrev_i32_e32 v2, 3, v10
	v_lshrrev_b32_e32 v13, 1, v2
	v_xor_b32_e32 v0, v13, v10
	v_ashrrev_i32_e32 v3, 31, v2
	v_lshlrev_b64 v[4:5], 11, v[2:3]
	v_lshlrev_b32_e32 v0, 4, v0
	v_and_b32_e32 v12, 31, v10
	v_lshl_add_u64 v[6:7], s[14:15], 0, v[4:5]
	v_and_b32_e32 v0, 0x70, v0
	v_lshl_add_u64 v[8:9], s[20:21], 0, v[4:5]
	s_waitcnt vmcnt(4)
	v_lshrrev_b32_e32 v14, 1, v10
	v_lshl_add_u64 v[6:7], v[6:7], 0, v[0:1]
	v_lshl_add_u64 v[164:165], v[8:9], 0, v[0:1]
	v_and_or_b32 v0, v14, s51, v12
	v_lshlrev_b32_e32 v161, 7, v0
	v_lshlrev_b32_e32 v0, 7, v10
	v_lshlrev_b32_e32 v174, 4, v10
	v_and_b32_e32 v163, 0x6f80, v0
	v_and_b32_e32 v0, 0x70, v174
	v_add_u32_e32 v175, 0x8000, v174
	v_lshl_add_u64 v[166:167], s[80:81], 0, v[0:1]
	v_cmp_gt_u32_e32 vcc, s50, v2
	v_readfirstlane_b32 s6, v174
	s_mov_b32 m0, s6
	v_cndmask_b32_e32 v9, v167, v7, vcc
	v_cndmask_b32_e32 v8, v166, v6, vcc
	v_readfirstlane_b32 s6, v175
	v_add_u32_e32 v0, 64, v2
	s_barrier
	s_mov_b32 m0, s6
	s_mov_b64 s[10:11], 0x20000
	v_cmp_gt_u32_e64 s[6:7], s50, v0
	v_add_u32_e32 v0, 0x2000, v174
	v_lshl_add_u64 v[8:9], v[6:7], 0, s[10:11]
	v_readfirstlane_b32 s8, v0
	v_add_u32_e32 v176, 0xa000, v174
	v_cndmask_b32_e64 v9, v167, v9, s[6:7]
	v_cndmask_b32_e64 v8, v166, v8, s[6:7]
	s_mov_b32 m0, s8
	v_readfirstlane_b32 s8, v176
	v_lshl_add_u64 v[8:9], v[164:165], 0, s[10:11]
	s_mov_b32 m0, s8
	v_add_u32_e32 v3, 0x80, v2
	s_mov_b64 s[22:23], 0x40000
	v_add_u32_e32 v177, 0x4000, v174
	v_lshl_add_u64 v[8:9], v[6:7], 0, s[22:23]
	v_cmp_gt_u32_e64 s[8:9], s50, v3
	v_readfirstlane_b32 s10, v177
	v_add_u32_e32 v178, 0xc000, v174
	v_cndmask_b32_e64 v9, v167, v9, s[8:9]
	v_cndmask_b32_e64 v8, v166, v8, s[8:9]
	s_mov_b32 m0, s10
	v_readfirstlane_b32 s10, v178
	v_lshl_add_u64 v[8:9], v[164:165], 0, s[22:23]
	s_mov_b32 m0, s10
	s_mov_b64 s[22:23], 0x60000
	v_add_u32_e32 v8, 0xc0, v2
	v_add_u32_e32 v179, 0x6000, v174
	v_lshl_add_u64 v[2:3], v[6:7], 0, s[22:23]
	v_cmp_gt_u32_e64 s[10:11], s50, v8
	v_readfirstlane_b32 s17, v179
	v_add_u32_e32 v180, 0xe000, v174
	v_cndmask_b32_e64 v3, v167, v3, s[10:11]
	v_cndmask_b32_e64 v2, v166, v2, s[10:11]
	s_mov_b32 m0, s17
	v_readfirstlane_b32 s17, v180
	v_lshl_add_u64 v[2:3], v[164:165], 0, s[22:23]
	s_mov_b32 m0, s17
	v_bfe_u32 v11, v10, 5, 1
	s_sub_i32 s17, s26, s30
	s_lshl_b32 s22, s29, 6
	v_bfe_u32 v15, v10, 1, 3
	v_bitop3_b32 v2, v14, v11, 7 bitop3:0x6c
	s_sub_i32 s17, s17, s22
	v_lshlrev_b32_e32 v181, 4, v2
	v_bitop3_b32 v2, v11, v15, 2 bitop3:0x36
	s_lshl_b32 s22, s17, 8
	v_lshlrev_b32_e32 v182, 4, v2
	v_bitop3_b32 v2, v11, v15, 4 bitop3:0x36
	s_ashr_i32 s23, s22, 31
	v_lshlrev_b32_e32 v183, 4, v2
	v_bitop3_b32 v2, v11, v15, 6 bitop3:0x36
	s_lshl_b64 s[22:23], s[22:23], 11
	v_lshlrev_b32_e32 v186, 4, v2
	v_lshl_add_u64 v[2:3], v[4:5], 0, s[22:23]
	v_bitop3_b32 v4, v13, 7, v10 bitop3:0x48
	s_waitcnt vmcnt(0)
	v_lshl_or_b32 v2, v4, 4, v2
	v_lshl_add_u64 v[168:169], s[70:71], 0, v[2:3]
	v_mov_b32_e32 v130, 0
	v_mov_b32_e32 v2, 0
	s_mov_b32 s13, 1
	v_add_u32_e32 v187, 0x10000, v174
	v_add_u32_e32 v192, 0x18000, v174
	v_add_u32_e32 v193, 0x12000, v174
	v_add_u32_e32 v194, 0x1a000, v174
	v_add_u32_e32 v195, 0x14000, v174
	v_add_u32_e32 v196, 0x1c000, v174
	v_add_u32_e32 v197, 0x16000, v174
	v_add_u32_e32 v198, 0x1e000, v174
	v_add_u32_e32 v199, 0x10000, v161
	v_or_b32_e32 v200, 0x10000, v163
	s_mov_b64 s[22:23], 0
	v_mov_b32_e32 v3, v2
	v_mov_b32_e32 v4, v2
	v_mov_b32_e32 v5, v2
	v_mov_b32_e32 v6, v2
	v_mov_b32_e32 v7, v2
	v_mov_b32_e32 v8, v2
	v_mov_b32_e32 v9, v2
	v_mov_b32_e32 v10, v2
	v_mov_b32_e32 v11, v2
	v_mov_b32_e32 v12, v2
	v_mov_b32_e32 v13, v2
	v_mov_b32_e32 v14, v2
	v_mov_b32_e32 v15, v2
	v_mov_b32_e32 v16, v2
	v_mov_b32_e32 v17, v2
	v_mov_b32_e32 v34, v2
	v_mov_b32_e32 v35, v2
	v_mov_b32_e32 v36, v2
	v_mov_b32_e32 v37, v2
	v_mov_b32_e32 v38, v2
	v_mov_b32_e32 v39, v2
	v_mov_b32_e32 v40, v2
	v_mov_b32_e32 v41, v2
	v_mov_b32_e32 v42, v2
	v_mov_b32_e32 v43, v2
	v_mov_b32_e32 v44, v2
	v_mov_b32_e32 v45, v2
	v_mov_b32_e32 v46, v2
	v_mov_b32_e32 v47, v2
	v_mov_b32_e32 v48, v2
	v_mov_b32_e32 v49, v2
	s_waitcnt vmcnt(0)
; template <bool SWAP>
; DI void gemm_mainloop(f32x16 (&acc)[4][2], const u16* __restrict__ A, int lda, int rlo, int rhi,
;                       const u16* __restrict__ B, int ldb, int K, char* lds, const u16* zero_line) {
;     ...
; #pragma unroll
;   for (int mi = 0; mi < 4; ++mi)
; #pragma unroll
;     for (int ni = 0; ni < 2; ++ni)
; #pragma unroll
;       for (int i = 0; i < 16; ++i) acc[mi][ni][i] = 0.f;
;   const int gch = (lc ^ ((lr >> 1) & 7)) * 8;
;   const u16* ap = A + (ptrdiff_t)lr * lda + gch;
;   const u16* bp = B + (ptrdiff_t)lr * ldb + gch;
;   const int nk = K >> 6;
;   typedef __attribute__((address_space(3))) unsigned lds_u32;
;   auto glds = [&](int kt, int st) {
;     char* as_ = lds + st * 65536 + tid * 16;
; #pragma unroll
;     for (int i = 0; i < 4; ++i) {
;       const int rr = lr + 64 * i;
;       const u16* srca = (rr >= rlo && rr < rhi) ? (ap + (ptrdiff_t)(64 * i) * lda + kt * 64) : (zero_line + lc * 8);
;       __builtin_amdgcn_global_load_lds((const unsigned*)srca, (lds_u32*)(as_ + i * 8192), 16, 0, 0);
;       __builtin_amdgcn_global_load_lds((const unsigned*)(bp + (ptrdiff_t)(64 * i) * ldb + kt * 64), (lds_u32*)(as_ + 32768 + i * 8192), 16, 0, 0);
;     }
;   };
;   const int sw = (r >> 1) & 7;
;   const int arow_off = (wm * 128 + r) * 128;
;   const int brow_off = 32768 + (wn * 64 + r) * 128;
;   __syncthreads();
;   glds(0, 0);
;   asm volatile("s_waitcnt vmcnt(0)" ::: "memory");
;   __syncthreads();
	s_ashr_i32 s7, s12, 31
	s_mov_b32 s6, s12
	s_lshl_b64 s[6:7], s[6:7], 11
	s_add_u32 s6, s90, s6
	s_addc_u32 s7, s91, s7
	s_ashr_i32 s9, s16, 31
	s_mov_b32 s8, s16
	s_lshl_b64 s[8:9], s[8:9], 11
	s_add_u32 s8, s70, s8
	s_addc_u32 s9, s71, s9
	v_and_b32_e32 v130, 63, v204
	v_lshrrev_b32_e32 v131, 6, v204
	v_lshrrev_b32_e32 v132, 3, v204
	v_lshrrev_b32_e32 v0, 4, v130
	v_lshl_add_u32 v0, v131, 2, v0
	v_xor_b32_e32 v0, v0, v130
	v_and_b32_e32 v0, 7, v0
	v_lshlrev_b32_e32 v133, 4, v0
	v_lshl_add_u32 v240, v132, 11, v133
	v_add_u32_e32 v241, 0x20000, v240
	v_add_u32_e32 v242, 0x40000, v240
	v_add_u32_e32 v243, 0x60000, v240
	v_and_b32_e32 v0, 31, v132
	v_lshrrev_b32_e32 v130, 5, v132
	v_lshl_add_u32 v0, v130, 6, v0
	v_lshl_add_u32 v244, v0, 11, v133
	v_add_u32_e32 v245, 0x10000, v244
	v_add_u32_e32 v246, 0x40000, v244
	v_add_u32_e32 v247, 0x50000, v244
	v_and_b32_e32 v132, 31, v204
	v_lshrrev_b32_e32 v0, 2, v131
	v_lshl_add_u32 v0, v0, 6, v132
	v_lshlrev_b32_e32 v166, 7, v0
	v_and_b32_e32 v0, 3, v131
	v_lshl_add_u32 v0, v0, 5, v132
	v_lshlrev_b32_e32 v249, 7, v0
	v_bfe_u32 v0, v204, 5, 1
	v_bfe_u32 v130, v132, 1, 3
	v_or_b32_e32 v133, 0, v0
	v_xor_b32_e32 v133, v133, v130
	v_lshlrev_b32_e32 v161, 4, v133
	v_or_b32_e32 v133, 2, v0
	v_xor_b32_e32 v133, v133, v130
	v_lshlrev_b32_e32 v163, 4, v133
	v_or_b32_e32 v133, 4, v0
	v_xor_b32_e32 v133, v133, v130
	v_lshlrev_b32_e32 v164, 4, v133
	v_or_b32_e32 v133, 6, v0
	v_xor_b32_e32 v133, v133, v130
	v_lshlrev_b32_e32 v165, 4, v133
	v_lshlrev_b32_e32 v131, 10, v131
	s_nop 0
	v_readfirstlane_b32 s100, v131
	v_mov_b32_e32 v146, 0
	v_mov_b32_e32 v147, 0
	v_mov_b32_e32 v148, 0
	v_mov_b32_e32 v149, 0
	v_lshlrev_b32_e32 v130, 4, v204
	v_add_u32_e32 v132, 0x10000, v130
	s_mov_b64 exec, -1
	s_mov_b32 s11, 0
	s_mov_b32 s10, 0x10000
	s_waitcnt lgkmcnt(0)
	s_add_u32 m0, s100, 0x8000
	s_nop 0
	global_load_lds_dwordx4 v244, s[8:9]
	v_add_u32_e32 v244, 0x80, v244
	s_add_u32 m0, s100, 0xa000
	s_nop 0
	global_load_lds_dwordx4 v246, s[8:9]
	v_add_u32_e32 v246, 0x80, v246
	s_add_u32 m0, s100, 0x0
	s_nop 0
	global_load_lds_dwordx4 v240, s[6:7]
	v_add_u32_e32 v240, 0x80, v240
	s_add_u32 m0, s100, 0x2000
	s_nop 0
	global_load_lds_dwordx4 v242, s[6:7]
	v_add_u32_e32 v242, 0x80, v242
	s_add_u32 m0, s100, 0xc000
	s_nop 0
	global_load_lds_dwordx4 v245, s[8:9]
	v_add_u32_e32 v245, 0x80, v245
	s_add_u32 m0, s100, 0xe000
	s_nop 0
	global_load_lds_dwordx4 v247, s[8:9]
	v_add_u32_e32 v247, 0x80, v247
	s_add_u32 m0, s100, 0x4000
	s_nop 0
	global_load_lds_dwordx4 v241, s[6:7]
	v_add_u32_e32 v241, 0x80, v241
	s_add_u32 m0, s100, 0x6000
	s_nop 0
	global_load_lds_dwordx4 v243, s[6:7]
	v_add_u32_e32 v243, 0x80, v243
	v_mov_b32_e32 v18, v2
	v_mov_b32_e32 v19, v2
	v_mov_b32_e32 v20, v2
	v_mov_b32_e32 v21, v2
	v_mov_b32_e32 v22, v2
	v_mov_b32_e32 v23, v2
	v_mov_b32_e32 v24, v2
	v_mov_b32_e32 v25, v2
	v_mov_b32_e32 v26, v2
	v_mov_b32_e32 v27, v2
	v_mov_b32_e32 v28, v2
	v_mov_b32_e32 v29, v2
	v_mov_b32_e32 v30, v2
	v_mov_b32_e32 v31, v2
	v_mov_b32_e32 v32, v2
	v_mov_b32_e32 v33, v2
	v_mov_b32_e32 v66, v2
	v_mov_b32_e32 v67, v2
	v_mov_b32_e32 v68, v2
	v_mov_b32_e32 v69, v2
	v_mov_b32_e32 v70, v2
	v_mov_b32_e32 v71, v2
	v_mov_b32_e32 v72, v2
	v_mov_b32_e32 v73, v2
	v_mov_b32_e32 v74, v2
	v_mov_b32_e32 v75, v2
	v_mov_b32_e32 v76, v2
	v_mov_b32_e32 v77, v2
	v_mov_b32_e32 v78, v2
	v_mov_b32_e32 v79, v2
	v_mov_b32_e32 v80, v2
	v_mov_b32_e32 v81, v2
	v_mov_b32_e32 v50, v2
	v_mov_b32_e32 v51, v2
	v_mov_b32_e32 v52, v2
	v_mov_b32_e32 v53, v2
	v_mov_b32_e32 v54, v2
	v_mov_b32_e32 v55, v2
	v_mov_b32_e32 v56, v2
	v_mov_b32_e32 v57, v2
	v_mov_b32_e32 v58, v2
	v_mov_b32_e32 v59, v2
	v_mov_b32_e32 v60, v2
	v_mov_b32_e32 v61, v2
	v_mov_b32_e32 v62, v2
	v_mov_b32_e32 v63, v2
	v_mov_b32_e32 v64, v2
	v_mov_b32_e32 v65, v2
	v_mov_b32_e32 v98, v2
	v_mov_b32_e32 v99, v2
	v_mov_b32_e32 v100, v2
	v_mov_b32_e32 v101, v2
	v_mov_b32_e32 v102, v2
	v_mov_b32_e32 v103, v2
	v_mov_b32_e32 v104, v2
	v_mov_b32_e32 v105, v2
	v_mov_b32_e32 v106, v2
	v_mov_b32_e32 v107, v2
	v_mov_b32_e32 v108, v2
	v_mov_b32_e32 v109, v2
	v_mov_b32_e32 v110, v2
	v_mov_b32_e32 v111, v2
	v_mov_b32_e32 v112, v2
	v_mov_b32_e32 v113, v2
	v_mov_b32_e32 v82, v2
	v_mov_b32_e32 v83, v2
	v_mov_b32_e32 v84, v2
	v_mov_b32_e32 v85, v2
	v_mov_b32_e32 v86, v2
	v_mov_b32_e32 v87, v2
	v_mov_b32_e32 v88, v2
	v_mov_b32_e32 v89, v2
	v_mov_b32_e32 v90, v2
	v_mov_b32_e32 v91, v2
	v_mov_b32_e32 v92, v2
	v_mov_b32_e32 v93, v2
	v_mov_b32_e32 v94, v2
	v_mov_b32_e32 v95, v2
	v_mov_b32_e32 v96, v2
	v_mov_b32_e32 v97, v2
	v_mov_b32_e32 v114, v2
	v_mov_b32_e32 v115, v2
	v_mov_b32_e32 v116, v2
	v_mov_b32_e32 v117, v2
	v_mov_b32_e32 v118, v2
	v_mov_b32_e32 v119, v2
	v_mov_b32_e32 v120, v2
	v_mov_b32_e32 v121, v2
	v_mov_b32_e32 v122, v2
	v_mov_b32_e32 v123, v2
	v_mov_b32_e32 v124, v2
	v_mov_b32_e32 v125, v2
	v_mov_b32_e32 v126, v2
	v_mov_b32_e32 v127, v2
	v_mov_b32_e32 v128, v2
	v_mov_b32_e32 v129, v2
	v_mov_b32_e32 v131, v130
	v_mov_b32_e32 v132, v130
	v_mov_b32_e32 v133, v130
	v_mov_b32_e32 v134, v130
	v_mov_b32_e32 v135, v130
	v_mov_b32_e32 v136, v130
	v_mov_b32_e32 v137, v130
	v_mov_b32_e32 v138, v130
	v_mov_b32_e32 v139, v130
	v_mov_b32_e32 v140, v130
	v_mov_b32_e32 v141, v130
	v_mov_b32_e32 v146, v130
	v_mov_b32_e32 v147, v130
	v_mov_b32_e32 v148, v130
	v_mov_b32_e32 v149, v130
	v_mov_b32_e32 v142, v130
	v_mov_b32_e32 v143, v130
	v_mov_b32_e32 v144, v130
	v_mov_b32_e32 v145, v130
	v_mov_b32_e32 v150, v130
	v_mov_b32_e32 v151, v130
	v_mov_b32_e32 v152, v130
	v_mov_b32_e32 v153, v130
	s_waitcnt lgkmcnt(0)
	s_barrier
	s_ashr_i32 s7, s12, 31
	s_mov_b32 s6, s12
	s_lshl_b64 s[6:7], s[6:7], 11
	s_add_u32 s6, s90, s6
	s_addc_u32 s7, s91, s7
	s_ashr_i32 s9, s16, 31
	s_mov_b32 s8, s16
	s_lshl_b64 s[8:9], s[8:9], 11
	s_add_u32 s8, s70, s8
	s_addc_u32 s9, s71, s9
	s_mov_b32 s11, 0
	s_mov_b32 s10, 0x10000
	s_cmp_eq_u32 s101, 1
	s_cbranch_scc0 .Lg8_ia_p0
	s_barrier
; #define MFMA(a, b, c) __builtin_amdgcn_mfma_f32_32x32x16_bf16((a), (b), (c), 0, 0, 0)
; template <bool SWAP>
; DI void gemm_mainloop(f32x16 (&acc)[4][2], const u16* __restrict__ A, int lda, int rlo, int rhi,
;                       const u16* __restrict__ B, int ldb, int K, char* lds, const u16* zero_line) {
;     ...
;   auto ldfrag = [&](const char* st, int ks, int buf) {
;     const int co = ((2 * ks + h) ^ sw) << 4;
; #pragma unroll
;     for (int mi = 0; mi < 4; ++mi) fa[buf][mi] = *(const bf16x8*)(st + arow_off + mi * 4096 + co);
; #pragma unroll
;     for (int ni = 0; ni < 2; ++ni) fb[buf][ni] = *(const bf16x8*)(st + brow_off + ni * 4096 + co);
;   };
;   auto mma = [&](int buf) {
; #pragma unroll
;     for (int mi = 0; mi < 4; ++mi)
; #pragma unroll
;       for (int ni = 0; ni < 2; ++ni)
;         acc[mi][ni] = SWAP ? MFMA(fb[buf][ni], fa[buf][mi], acc[mi][ni]) : MFMA(fa[buf][mi], fb[buf][ni], acc[mi][ni]);
;   };
;   auto pat_rd = [&]() {
; #pragma unroll
;     for (int g = 0; g < 6; ++g) {
;       __builtin_amdgcn_sched_group_barrier(0x100, 1, 0);
;       __builtin_amdgcn_sched_group_barrier(0x008, 1, 0);
;     }
;     __builtin_amdgcn_sched_group_barrier(0x008, 2, 0);
;   };
; #pragma unroll 2
;   for (int kt = 0; kt < nk; ++kt) {
;     const char* st = lds + (kt & 1) * 65536;
;     ldfrag(st, 0, 0);
;     mma(1);
;     pat_rd();
;     if (kt + 1 < nk) glds(kt + 1, (kt + 1) & 1);
;     ldfrag(st, 1, 1);
;     mma(0);
;     pat_rd();
;     ldfrag(st, 2, 0);
;     mma(1);
;     pat_rd();
;     ldfrag(st, 3, 1);
;     mma(0);
;     pat_rd();
;     asm volatile("s_waitcnt vmcnt(0)" ::: "memory");
;     __syncthreads();
;   }
;   mma(1);
.Lg8_ia_p0:
	s_waitcnt vmcnt(4)
	s_barrier
	s_add_u32 m0, s100, 0x18000
	s_nop 0
	global_load_lds_dwordx4 v244, s[8:9]
	v_add_u32_e32 v244, 0x80, v244
	s_add_u32 m0, s100, 0x1a000
	s_nop 0
	global_load_lds_dwordx4 v246, s[8:9]
	v_add_u32_e32 v246, 0x80, v246
	s_add_u32 m0, s100, 0x10000
	s_nop 0
	global_load_lds_dwordx4 v240, s[6:7]
	v_add_u32_e32 v240, 0x80, v240
	s_add_u32 m0, s100, 0x12000
	s_nop 0
	global_load_lds_dwordx4 v242, s[6:7]
	v_add_u32_e32 v242, 0x80, v242
	s_add_u32 m0, s100, 0x1c000
	s_nop 0
	global_load_lds_dwordx4 v245, s[8:9]
	v_add_u32_e32 v245, 0x80, v245
	s_add_u32 m0, s100, 0x1e000
	s_nop 0
	global_load_lds_dwordx4 v247, s[8:9]
	v_add_u32_e32 v247, 0x80, v247
	s_waitcnt vmcnt(6)
	s_barrier
	v_add3_u32 v186, v249, v161, 0
	v_add3_u32 v187, v249, v163, 0
	ds_read_b128 v[176:179], v186 offset:32768
	ds_read_b128 v[180:183], v187 offset:32768
	v_add3_u32 v186, v249, v164, 0
	v_add3_u32 v187, v249, v165, 0
	ds_read_b128 v[192:195], v186 offset:32768
	ds_read_b128 v[196:199], v187 offset:32768
.Lg8_ia:
	v_add3_u32 v186, v166, v161, 0
	v_add3_u32 v187, v166, v163, 0
	ds_read_b128 v[130:133], v186
	ds_read_b128 v[134:137], v187
	ds_read_b128 v[146:149], v186 offset:4096
	ds_read_b128 v[150:153], v187 offset:4096
	v_add3_u32 v186, v166, v164, 0
	v_add3_u32 v187, v166, v165, 0
	ds_read_b128 v[138:141], v186
	ds_read_b128 v[142:145], v187
	ds_read_b128 v[168:171], v186 offset:4096
	ds_read_b128 v[172:175], v187 offset:4096
	s_add_u32 m0, s100, 0x14000
	s_nop 0
	global_load_lds_dwordx4 v241, s[6:7]
	v_add_u32_e32 v241, 0x80, v241
	s_add_u32 m0, s100, 0x16000
	s_nop 0
	global_load_lds_dwordx4 v243, s[6:7]
	v_add_u32_e32 v243, 0x80, v243
	s_barrier
	s_waitcnt lgkmcnt(0)
	v_mfma_f32_32x32x16_bf16 v[114:129], v[176:179], v[130:133], v[114:129]
	v_mfma_f32_32x32x16_bf16 v[98:113], v[176:179], v[146:149], v[98:113]
	v_mfma_f32_32x32x16_bf16 v[114:129], v[180:183], v[134:137], v[114:129]
	v_mfma_f32_32x32x16_bf16 v[98:113], v[180:183], v[150:153], v[98:113]
	v_mfma_f32_32x32x16_bf16 v[114:129], v[192:195], v[138:141], v[114:129]
	v_mfma_f32_32x32x16_bf16 v[98:113], v[192:195], v[168:171], v[98:113]
	v_mfma_f32_32x32x16_bf16 v[114:129], v[196:199], v[142:145], v[114:129]
	v_mfma_f32_32x32x16_bf16 v[98:113], v[196:199], v[172:175], v[98:113]
	s_barrier
	v_add3_u32 v186, v249, v161, 0
	v_add3_u32 v187, v249, v163, 0
	ds_read_b128 v[200:203], v186 offset:49152
	ds_read_b128 v[228:231], v187 offset:49152
	v_add3_u32 v186, v249, v164, 0
	v_add3_u32 v187, v249, v165, 0
	ds_read_b128 v[232:235], v186 offset:49152
	ds_read_b128 v[236:239], v187 offset:49152
	s_add_u32 m0, s100, 0x8000
	s_nop 0
	global_load_lds_dwordx4 v244, s[8:9]
	v_add_u32_e32 v244, 0x80, v244
	s_add_u32 m0, s100, 0xa000
	s_nop 0
	global_load_lds_dwordx4 v246, s[8:9]
	v_add_u32_e32 v246, 0x80, v246
	s_barrier
	s_waitcnt lgkmcnt(0)
	v_mfma_f32_32x32x16_bf16 v[82:97], v[200:203], v[130:133], v[82:97]
	v_mfma_f32_32x32x16_bf16 v[50:65], v[200:203], v[146:149], v[50:65]
	v_mfma_f32_32x32x16_bf16 v[82:97], v[228:231], v[134:137], v[82:97]
	v_mfma_f32_32x32x16_bf16 v[50:65], v[228:231], v[150:153], v[50:65]
	v_mfma_f32_32x32x16_bf16 v[82:97], v[232:235], v[138:141], v[82:97]
	v_mfma_f32_32x32x16_bf16 v[50:65], v[232:235], v[168:171], v[50:65]
	v_mfma_f32_32x32x16_bf16 v[82:97], v[236:239], v[142:145], v[82:97]
	v_mfma_f32_32x32x16_bf16 v[50:65], v[236:239], v[172:175], v[50:65]
	s_barrier
	v_add3_u32 v186, v166, v161, 0
	v_add3_u32 v187, v166, v163, 0
	ds_read_b128 v[130:133], v186 offset:16384
	ds_read_b128 v[134:137], v187 offset:16384
	ds_read_b128 v[146:149], v186 offset:20480
	ds_read_b128 v[150:153], v187 offset:20480
	v_add3_u32 v186, v166, v164, 0
	v_add3_u32 v187, v166, v165, 0
	ds_read_b128 v[138:141], v186 offset:16384
	ds_read_b128 v[142:145], v187 offset:16384
	ds_read_b128 v[168:171], v186 offset:20480
	ds_read_b128 v[172:175], v187 offset:20480
	s_add_u32 m0, s100, 0x0
	s_nop 0
	global_load_lds_dwordx4 v240, s[6:7]
	v_add_u32_e32 v240, 0x80, v240
	s_add_u32 m0, s100, 0x2000
	s_nop 0
	global_load_lds_dwordx4 v242, s[6:7]
	v_add_u32_e32 v242, 0x80, v242
	s_waitcnt vmcnt(10)
	s_barrier
	s_waitcnt lgkmcnt(0)
	v_mfma_f32_32x32x16_bf16 v[66:81], v[176:179], v[130:133], v[66:81]
	v_mfma_f32_32x32x16_bf16 v[34:49], v[176:179], v[146:149], v[34:49]
	v_mfma_f32_32x32x16_bf16 v[66:81], v[180:183], v[134:137], v[66:81]
	v_mfma_f32_32x32x16_bf16 v[34:49], v[180:183], v[150:153], v[34:49]
	v_mfma_f32_32x32x16_bf16 v[66:81], v[192:195], v[138:141], v[66:81]
	v_mfma_f32_32x32x16_bf16 v[34:49], v[192:195], v[168:171], v[34:49]
	v_mfma_f32_32x32x16_bf16 v[66:81], v[196:199], v[142:145], v[66:81]
	v_mfma_f32_32x32x16_bf16 v[34:49], v[196:199], v[172:175], v[34:49]
	s_barrier
	v_add3_u32 v186, v249, v161, s10
	v_add3_u32 v187, v249, v163, s10
	ds_read_b128 v[176:179], v186 offset:32768
	ds_read_b128 v[180:183], v187 offset:32768
	v_add3_u32 v186, v249, v164, s10
	v_add3_u32 v187, v249, v165, s10
	ds_read_b128 v[192:195], v186 offset:32768
	ds_read_b128 v[196:199], v187 offset:32768
	s_add_u32 m0, s100, 0xc000
	s_nop 0
	global_load_lds_dwordx4 v245, s[8:9]
	v_add_u32_e32 v245, 0x80, v245
	s_add_u32 m0, s100, 0xe000
	s_nop 0
	global_load_lds_dwordx4 v247, s[8:9]
	v_add_u32_e32 v247, 0x80, v247
	s_waitcnt vmcnt(6)
	s_barrier
	s_waitcnt lgkmcnt(0)
	v_mfma_f32_32x32x16_bf16 v[18:33], v[200:203], v[130:133], v[18:33]
	v_mfma_f32_32x32x16_bf16 v[2:17], v[200:203], v[146:149], v[2:17]
	v_mfma_f32_32x32x16_bf16 v[18:33], v[228:231], v[134:137], v[18:33]
	v_mfma_f32_32x32x16_bf16 v[2:17], v[228:231], v[150:153], v[2:17]
	v_mfma_f32_32x32x16_bf16 v[18:33], v[232:235], v[138:141], v[18:33]
	v_mfma_f32_32x32x16_bf16 v[2:17], v[232:235], v[168:171], v[2:17]
	v_mfma_f32_32x32x16_bf16 v[18:33], v[236:239], v[142:145], v[18:33]
	v_mfma_f32_32x32x16_bf16 v[2:17], v[236:239], v[172:175], v[2:17]
	s_barrier
; #define MFMA(a, b, c) __builtin_amdgcn_mfma_f32_32x32x16_bf16((a), (b), (c), 0, 0, 0)
; template <bool SWAP>
; DI void gemm_mainloop(f32x16 (&acc)[4][2], const u16* __restrict__ A, int lda, int rlo, int rhi,
;                       const u16* __restrict__ B, int ldb, int K, char* lds, const u16* zero_line) {
;     ...
;   auto ldfrag = [&](const char* st, int ks, int buf) {
;     const int co = ((2 * ks + h) ^ sw) << 4;
; #pragma unroll
;     for (int mi = 0; mi < 4; ++mi) fa[buf][mi] = *(const bf16x8*)(st + arow_off + mi * 4096 + co);
; #pragma unroll
;     for (int ni = 0; ni < 2; ++ni) fb[buf][ni] = *(const bf16x8*)(st + brow_off + ni * 4096 + co);
;   };
;   auto mma = [&](int buf) {
; #pragma unroll
;     for (int mi = 0; mi < 4; ++mi)
; #pragma unroll
;       for (int ni = 0; ni < 2; ++ni)
;         acc[mi][ni] = SWAP ? MFMA(fb[buf][ni], fa[buf][mi], acc[mi][ni]) : MFMA(fa[buf][mi], fb[buf][ni], acc[mi][ni]);
;   };
;   auto pat_rd = [&]() {
; #pragma unroll
;     for (int g = 0; g < 6; ++g) {
;       __builtin_amdgcn_sched_group_barrier(0x100, 1, 0);
;       __builtin_amdgcn_sched_group_barrier(0x008, 1, 0);
;     }
;     __builtin_amdgcn_sched_group_barrier(0x008, 2, 0);
;   };
; #pragma unroll 2
;   for (int kt = 0; kt < nk; ++kt) {
;     const char* st = lds + (kt & 1) * 65536;
;     ldfrag(st, 0, 0);
;     mma(1);
;     pat_rd();
;     if (kt + 1 < nk) glds(kt + 1, (kt + 1) & 1);
;     ldfrag(st, 1, 1);
;     mma(0);
;     pat_rd();
;     ldfrag(st, 2, 0);
;     mma(1);
;     pat_rd();
;     ldfrag(st, 3, 1);
;     mma(0);
;     pat_rd();
;     asm volatile("s_waitcnt vmcnt(0)" ::: "memory");
;     __syncthreads();
	v_add3_u32 v186, v166, v161, s10
	v_add3_u32 v187, v166, v163, s10
	ds_read_b128 v[130:133], v186
	ds_read_b128 v[134:137], v187
	ds_read_b128 v[146:149], v186 offset:4096
	ds_read_b128 v[150:153], v187 offset:4096
	v_add3_u32 v186, v166, v164, s10
	v_add3_u32 v187, v166, v165, s10
	ds_read_b128 v[138:141], v186
	ds_read_b128 v[142:145], v187
	ds_read_b128 v[168:171], v186 offset:4096
	ds_read_b128 v[172:175], v187 offset:4096
	s_add_u32 m0, s100, 0x4000
	s_nop 0
	global_load_lds_dwordx4 v241, s[6:7]
	v_add_u32_e32 v241, 0x80, v241
	s_add_u32 m0, s100, 0x6000
	s_nop 0
	global_load_lds_dwordx4 v243, s[6:7]
	v_add_u32_e32 v243, 0x80, v243
	s_barrier
	s_waitcnt lgkmcnt(0)
	v_mfma_f32_32x32x16_bf16 v[114:129], v[176:179], v[130:133], v[114:129]
	v_mfma_f32_32x32x16_bf16 v[98:113], v[176:179], v[146:149], v[98:113]
	v_mfma_f32_32x32x16_bf16 v[114:129], v[180:183], v[134:137], v[114:129]
	v_mfma_f32_32x32x16_bf16 v[98:113], v[180:183], v[150:153], v[98:113]
	v_mfma_f32_32x32x16_bf16 v[114:129], v[192:195], v[138:141], v[114:129]
	v_mfma_f32_32x32x16_bf16 v[98:113], v[192:195], v[168:171], v[98:113]
	v_mfma_f32_32x32x16_bf16 v[114:129], v[196:199], v[142:145], v[114:129]
	v_mfma_f32_32x32x16_bf16 v[98:113], v[196:199], v[172:175], v[98:113]
	s_barrier
	v_add3_u32 v186, v249, v161, s10
	v_add3_u32 v187, v249, v163, s10
	ds_read_b128 v[200:203], v186 offset:49152
	ds_read_b128 v[228:231], v187 offset:49152
	v_add3_u32 v186, v249, v164, s10
	v_add3_u32 v187, v249, v165, s10
	ds_read_b128 v[232:235], v186 offset:49152
	ds_read_b128 v[236:239], v187 offset:49152
	s_add_u32 m0, s100, 0x18000
	s_nop 0
	global_load_lds_dwordx4 v244, s[8:9]
	v_add_u32_e32 v244, 0x80, v244
	s_add_u32 m0, s100, 0x1a000
	s_nop 0
	global_load_lds_dwordx4 v246, s[8:9]
	v_add_u32_e32 v246, 0x80, v246
	s_barrier
	s_waitcnt lgkmcnt(0)
	v_mfma_f32_32x32x16_bf16 v[82:97], v[200:203], v[130:133], v[82:97]
	v_mfma_f32_32x32x16_bf16 v[50:65], v[200:203], v[146:149], v[50:65]
	v_mfma_f32_32x32x16_bf16 v[82:97], v[228:231], v[134:137], v[82:97]
	v_mfma_f32_32x32x16_bf16 v[50:65], v[228:231], v[150:153], v[50:65]
	v_mfma_f32_32x32x16_bf16 v[82:97], v[232:235], v[138:141], v[82:97]
	v_mfma_f32_32x32x16_bf16 v[50:65], v[232:235], v[168:171], v[50:65]
	v_mfma_f32_32x32x16_bf16 v[82:97], v[236:239], v[142:145], v[82:97]
	v_mfma_f32_32x32x16_bf16 v[50:65], v[236:239], v[172:175], v[50:65]
	s_barrier
	v_add3_u32 v186, v166, v161, s10
	v_add3_u32 v187, v166, v163, s10
	ds_read_b128 v[130:133], v186 offset:16384
	ds_read_b128 v[134:137], v187 offset:16384
	ds_read_b128 v[146:149], v186 offset:20480
	ds_read_b128 v[150:153], v187 offset:20480
	v_add3_u32 v186, v166, v164, s10
	v_add3_u32 v187, v166, v165, s10
	ds_read_b128 v[138:141], v186 offset:16384
	ds_read_b128 v[142:145], v187 offset:16384
	ds_read_b128 v[168:171], v186 offset:20480
	ds_read_b128 v[172:175], v187 offset:20480
	s_add_u32 m0, s100, 0x10000
	s_nop 0
	global_load_lds_dwordx4 v240, s[6:7]
	v_add_u32_e32 v240, 0x80, v240
	s_add_u32 m0, s100, 0x12000
	s_nop 0
	global_load_lds_dwordx4 v242, s[6:7]
	v_add_u32_e32 v242, 0x80, v242
	s_waitcnt vmcnt(10)
	s_barrier
	s_waitcnt lgkmcnt(0)
	v_mfma_f32_32x32x16_bf16 v[66:81], v[176:179], v[130:133], v[66:81]
	v_mfma_f32_32x32x16_bf16 v[34:49], v[176:179], v[146:149], v[34:49]
	v_mfma_f32_32x32x16_bf16 v[66:81], v[180:183], v[134:137], v[66:81]
	v_mfma_f32_32x32x16_bf16 v[34:49], v[180:183], v[150:153], v[34:49]
	v_mfma_f32_32x32x16_bf16 v[66:81], v[192:195], v[138:141], v[66:81]
	v_mfma_f32_32x32x16_bf16 v[34:49], v[192:195], v[168:171], v[34:49]
	v_mfma_f32_32x32x16_bf16 v[66:81], v[196:199], v[142:145], v[66:81]
	v_mfma_f32_32x32x16_bf16 v[34:49], v[196:199], v[172:175], v[34:49]
	s_barrier
	v_add3_u32 v186, v249, v161, 0
	v_add3_u32 v187, v249, v163, 0
	ds_read_b128 v[176:179], v186 offset:32768
	ds_read_b128 v[180:183], v187 offset:32768
	v_add3_u32 v186, v249, v164, 0
	v_add3_u32 v187, v249, v165, 0
	ds_read_b128 v[192:195], v186 offset:32768
	ds_read_b128 v[196:199], v187 offset:32768
	s_add_u32 m0, s100, 0x1c000
	s_nop 0
	global_load_lds_dwordx4 v245, s[8:9]
	v_add_u32_e32 v245, 0x80, v245
	s_add_u32 m0, s100, 0x1e000
	s_nop 0
	global_load_lds_dwordx4 v247, s[8:9]
	v_add_u32_e32 v247, 0x80, v247
	s_waitcnt vmcnt(6)
	s_barrier
	s_waitcnt lgkmcnt(0)
	v_mfma_f32_32x32x16_bf16 v[18:33], v[200:203], v[130:133], v[18:33]
	v_mfma_f32_32x32x16_bf16 v[2:17], v[200:203], v[146:149], v[2:17]
	v_mfma_f32_32x32x16_bf16 v[18:33], v[228:231], v[134:137], v[18:33]
	v_mfma_f32_32x32x16_bf16 v[2:17], v[228:231], v[150:153], v[2:17]
	v_mfma_f32_32x32x16_bf16 v[18:33], v[232:235], v[138:141], v[18:33]
	v_mfma_f32_32x32x16_bf16 v[2:17], v[232:235], v[168:171], v[2:17]
	v_mfma_f32_32x32x16_bf16 v[18:33], v[236:239], v[142:145], v[18:33]
	v_mfma_f32_32x32x16_bf16 v[2:17], v[236:239], v[172:175], v[2:17]
	s_barrier
	s_add_i32 s11, s11, 2
	s_cmp_lt_u32 s11, 14
	s_cbranch_scc1 .Lg8_ia
	v_add3_u32 v186, v166, v161, 0
	v_add3_u32 v187, v166, v163, 0
	ds_read_b128 v[130:133], v186
	ds_read_b128 v[134:137], v187
	ds_read_b128 v[146:149], v186 offset:4096
	ds_read_b128 v[150:153], v187 offset:4096
	v_add3_u32 v186, v166, v164, 0
	v_add3_u32 v187, v166, v165, 0
	ds_read_b128 v[138:141], v186
	ds_read_b128 v[142:145], v187
	ds_read_b128 v[168:171], v186 offset:4096
	ds_read_b128 v[172:175], v187 offset:4096
	s_add_u32 m0, s100, 0x14000
	s_nop 0
	global_load_lds_dwordx4 v241, s[6:7]
	v_add_u32_e32 v241, 0x80, v241
	s_add_u32 m0, s100, 0x16000
	s_nop 0
	global_load_lds_dwordx4 v243, s[6:7]
	v_add_u32_e32 v243, 0x80, v243
	s_barrier
; template <bool SWAP>
; DI void gemm_mainloop(f32x16 (&acc)[4][2], const u16* __restrict__ A, int lda, int rlo, int rhi,
;                       const u16* __restrict__ B, int ldb, int K, char* lds, const u16* zero_line) {
;     ...
; #pragma unroll 2
;   for (int kt = 0; kt < nk; ++kt) {
;     const char* st = lds + (kt & 1) * 65536;
;     ldfrag(st, 0, 0);
;     mma(1);
;     pat_rd();
;     if (kt + 1 < nk) glds(kt + 1, (kt + 1) & 1);
;     ldfrag(st, 1, 1);
;     mma(0);
;     pat_rd();
;     ldfrag(st, 2, 0);
;     mma(1);
;     pat_rd();
;     ldfrag(st, 3, 1);
;     mma(0);
;     pat_rd();
;     asm volatile("s_waitcnt vmcnt(0)" ::: "memory");
;     __syncthreads();
;   }
;   mma(1);
	s_waitcnt lgkmcnt(0)
	v_mfma_f32_32x32x16_bf16 v[114:129], v[176:179], v[130:133], v[114:129]
	v_mfma_f32_32x32x16_bf16 v[98:113], v[176:179], v[146:149], v[98:113]
	v_mfma_f32_32x32x16_bf16 v[114:129], v[180:183], v[134:137], v[114:129]
	v_mfma_f32_32x32x16_bf16 v[98:113], v[180:183], v[150:153], v[98:113]
	v_mfma_f32_32x32x16_bf16 v[114:129], v[192:195], v[138:141], v[114:129]
	v_mfma_f32_32x32x16_bf16 v[98:113], v[192:195], v[168:171], v[98:113]
	v_mfma_f32_32x32x16_bf16 v[114:129], v[196:199], v[142:145], v[114:129]
	v_mfma_f32_32x32x16_bf16 v[98:113], v[196:199], v[172:175], v[98:113]
	s_barrier
	v_add3_u32 v186, v249, v161, 0
	v_add3_u32 v187, v249, v163, 0
	ds_read_b128 v[200:203], v186 offset:49152
	ds_read_b128 v[228:231], v187 offset:49152
	v_add3_u32 v186, v249, v164, 0
	v_add3_u32 v187, v249, v165, 0
	ds_read_b128 v[232:235], v186 offset:49152
	ds_read_b128 v[236:239], v187 offset:49152
	s_barrier
	s_waitcnt lgkmcnt(0)
	v_mfma_f32_32x32x16_bf16 v[82:97], v[200:203], v[130:133], v[82:97]
	v_mfma_f32_32x32x16_bf16 v[50:65], v[200:203], v[146:149], v[50:65]
	v_mfma_f32_32x32x16_bf16 v[82:97], v[228:231], v[134:137], v[82:97]
	v_mfma_f32_32x32x16_bf16 v[50:65], v[228:231], v[150:153], v[50:65]
	v_mfma_f32_32x32x16_bf16 v[82:97], v[232:235], v[138:141], v[82:97]
	v_mfma_f32_32x32x16_bf16 v[50:65], v[232:235], v[168:171], v[50:65]
	v_mfma_f32_32x32x16_bf16 v[82:97], v[236:239], v[142:145], v[82:97]
	v_mfma_f32_32x32x16_bf16 v[50:65], v[236:239], v[172:175], v[50:65]
	s_barrier
	v_add3_u32 v186, v166, v161, 0
	v_add3_u32 v187, v166, v163, 0
	ds_read_b128 v[130:133], v186 offset:16384
	ds_read_b128 v[134:137], v187 offset:16384
	ds_read_b128 v[146:149], v186 offset:20480
	ds_read_b128 v[150:153], v187 offset:20480
	v_add3_u32 v186, v166, v164, 0
	v_add3_u32 v187, v166, v165, 0
	ds_read_b128 v[138:141], v186 offset:16384
	ds_read_b128 v[142:145], v187 offset:16384
	ds_read_b128 v[168:171], v186 offset:20480
	ds_read_b128 v[172:175], v187 offset:20480
	s_waitcnt vmcnt(4)
	s_barrier
	s_waitcnt lgkmcnt(0)
	v_mfma_f32_32x32x16_bf16 v[66:81], v[176:179], v[130:133], v[66:81]
	v_mfma_f32_32x32x16_bf16 v[34:49], v[176:179], v[146:149], v[34:49]
	v_mfma_f32_32x32x16_bf16 v[66:81], v[180:183], v[134:137], v[66:81]
	v_mfma_f32_32x32x16_bf16 v[34:49], v[180:183], v[150:153], v[34:49]
	v_mfma_f32_32x32x16_bf16 v[66:81], v[192:195], v[138:141], v[66:81]
	v_mfma_f32_32x32x16_bf16 v[34:49], v[192:195], v[168:171], v[34:49]
	v_mfma_f32_32x32x16_bf16 v[66:81], v[196:199], v[142:145], v[66:81]
	v_mfma_f32_32x32x16_bf16 v[34:49], v[196:199], v[172:175], v[34:49]
	v_mfma_f32_32x32x16_bf16 v[18:33], v[200:203], v[130:133], v[18:33]
	v_mfma_f32_32x32x16_bf16 v[2:17], v[200:203], v[146:149], v[2:17]
	v_mfma_f32_32x32x16_bf16 v[18:33], v[228:231], v[134:137], v[18:33]
	v_mfma_f32_32x32x16_bf16 v[2:17], v[228:231], v[150:153], v[2:17]
	v_mfma_f32_32x32x16_bf16 v[18:33], v[232:235], v[138:141], v[18:33]
	v_mfma_f32_32x32x16_bf16 v[2:17], v[232:235], v[168:171], v[2:17]
	v_mfma_f32_32x32x16_bf16 v[18:33], v[236:239], v[142:145], v[18:33]
	v_mfma_f32_32x32x16_bf16 v[2:17], v[236:239], v[172:175], v[2:17]
	s_barrier
	v_add3_u32 v186, v249, v161, s10
	v_add3_u32 v187, v249, v163, s10
	ds_read_b128 v[176:179], v186 offset:32768
	ds_read_b128 v[180:183], v187 offset:32768
	v_add3_u32 v186, v249, v164, s10
	v_add3_u32 v187, v249, v165, s10
	ds_read_b128 v[192:195], v186 offset:32768
	ds_read_b128 v[196:199], v187 offset:32768
	v_add3_u32 v186, v166, v161, s10
	v_add3_u32 v187, v166, v163, s10
	ds_read_b128 v[130:133], v186
	ds_read_b128 v[134:137], v187
	ds_read_b128 v[146:149], v186 offset:4096
	ds_read_b128 v[150:153], v187 offset:4096
	v_add3_u32 v186, v166, v164, s10
	v_add3_u32 v187, v166, v165, s10
	ds_read_b128 v[138:141], v186
	ds_read_b128 v[142:145], v187
	ds_read_b128 v[168:171], v186 offset:4096
	ds_read_b128 v[172:175], v187 offset:4096
	s_waitcnt vmcnt(2)
	s_barrier
; template <bool SWAP>
; DI void gemm_mainloop(f32x16 (&acc)[4][2], const u16* __restrict__ A, int lda, int rlo, int rhi,
;                       const u16* __restrict__ B, int ldb, int K, char* lds, const u16* zero_line) {
;     ...
; #pragma unroll 2
;   for (int kt = 0; kt < nk; ++kt) {
;     const char* st = lds + (kt & 1) * 65536;
;     ldfrag(st, 0, 0);
;     mma(1);
;     pat_rd();
;     if (kt + 1 < nk) glds(kt + 1, (kt + 1) & 1);
;     ldfrag(st, 1, 1);
;     mma(0);
;     pat_rd();
;     ldfrag(st, 2, 0);
;     mma(1);
;     pat_rd();
;     ldfrag(st, 3, 1);
;     mma(0);
;     pat_rd();
;     asm volatile("s_waitcnt vmcnt(0)" ::: "memory");
;     __syncthreads();
;   }
;   mma(1);
	s_waitcnt lgkmcnt(0)
	v_mfma_f32_32x32x16_bf16 v[114:129], v[176:179], v[130:133], v[114:129]
	v_mfma_f32_32x32x16_bf16 v[98:113], v[176:179], v[146:149], v[98:113]
	v_mfma_f32_32x32x16_bf16 v[114:129], v[180:183], v[134:137], v[114:129]
	v_mfma_f32_32x32x16_bf16 v[98:113], v[180:183], v[150:153], v[98:113]
	v_mfma_f32_32x32x16_bf16 v[114:129], v[192:195], v[138:141], v[114:129]
	v_mfma_f32_32x32x16_bf16 v[98:113], v[192:195], v[168:171], v[98:113]
	v_mfma_f32_32x32x16_bf16 v[114:129], v[196:199], v[142:145], v[114:129]
	v_mfma_f32_32x32x16_bf16 v[98:113], v[196:199], v[172:175], v[98:113]
	s_barrier
	v_add3_u32 v186, v249, v161, s10
	v_add3_u32 v187, v249, v163, s10
	ds_read_b128 v[200:203], v186 offset:49152
	ds_read_b128 v[228:231], v187 offset:49152
	v_add3_u32 v186, v249, v164, s10
	v_add3_u32 v187, v249, v165, s10
	ds_read_b128 v[232:235], v186 offset:49152
	ds_read_b128 v[236:239], v187 offset:49152
	s_waitcnt vmcnt(0)
	s_barrier
	s_waitcnt lgkmcnt(0)
	v_mfma_f32_32x32x16_bf16 v[82:97], v[200:203], v[130:133], v[82:97]
	v_mfma_f32_32x32x16_bf16 v[50:65], v[200:203], v[146:149], v[50:65]
	v_mfma_f32_32x32x16_bf16 v[82:97], v[228:231], v[134:137], v[82:97]
	v_mfma_f32_32x32x16_bf16 v[50:65], v[228:231], v[150:153], v[50:65]
	v_mfma_f32_32x32x16_bf16 v[82:97], v[232:235], v[138:141], v[82:97]
	v_mfma_f32_32x32x16_bf16 v[50:65], v[232:235], v[168:171], v[50:65]
	v_mfma_f32_32x32x16_bf16 v[82:97], v[236:239], v[142:145], v[82:97]
	v_mfma_f32_32x32x16_bf16 v[50:65], v[236:239], v[172:175], v[50:65]
	s_barrier
	v_add3_u32 v186, v166, v161, s10
	v_add3_u32 v187, v166, v163, s10
	ds_read_b128 v[130:133], v186 offset:16384
	ds_read_b128 v[134:137], v187 offset:16384
	ds_read_b128 v[146:149], v186 offset:20480
	ds_read_b128 v[150:153], v187 offset:20480
	v_add3_u32 v186, v166, v164, s10
	v_add3_u32 v187, v166, v165, s10
	ds_read_b128 v[138:141], v186 offset:16384
	ds_read_b128 v[142:145], v187 offset:16384
	ds_read_b128 v[168:171], v186 offset:20480
	ds_read_b128 v[172:175], v187 offset:20480
	s_barrier
	s_waitcnt lgkmcnt(0)
	v_mfma_f32_32x32x16_bf16 v[66:81], v[176:179], v[130:133], v[66:81]
	v_mfma_f32_32x32x16_bf16 v[34:49], v[176:179], v[146:149], v[34:49]
	v_mfma_f32_32x32x16_bf16 v[66:81], v[180:183], v[134:137], v[66:81]
	v_mfma_f32_32x32x16_bf16 v[34:49], v[180:183], v[150:153], v[34:49]
	v_mfma_f32_32x32x16_bf16 v[66:81], v[192:195], v[138:141], v[66:81]
	v_mfma_f32_32x32x16_bf16 v[34:49], v[192:195], v[168:171], v[34:49]
	v_mfma_f32_32x32x16_bf16 v[66:81], v[196:199], v[142:145], v[66:81]
	v_mfma_f32_32x32x16_bf16 v[34:49], v[196:199], v[172:175], v[34:49]
	v_mfma_f32_32x32x16_bf16 v[18:33], v[200:203], v[130:133], v[18:33]
	v_mfma_f32_32x32x16_bf16 v[2:17], v[200:203], v[146:149], v[2:17]
	v_mfma_f32_32x32x16_bf16 v[18:33], v[228:231], v[134:137], v[18:33]
	v_mfma_f32_32x32x16_bf16 v[2:17], v[228:231], v[150:153], v[2:17]
	v_mfma_f32_32x32x16_bf16 v[18:33], v[232:235], v[138:141], v[18:33]
	v_mfma_f32_32x32x16_bf16 v[2:17], v[232:235], v[168:171], v[2:17]
	v_mfma_f32_32x32x16_bf16 v[18:33], v[236:239], v[142:145], v[18:33]
	v_mfma_f32_32x32x16_bf16 v[2:17], v[236:239], v[172:175], v[2:17]
	s_barrier
	s_cmp_eq_u32 s101, 0
	s_cbranch_scc0 .Lg8_ia_p1
	s_barrier

; template <bool SWAP>
; DI void gemm_mainloop(f32x16 (&acc)[4][2], const u16* __restrict__ A, int lda, int rlo, int rhi,
;                       const u16* __restrict__ B, int ldb, int K, char* lds, const u16* zero_line) {
;     ...
;   const int gch = (lc ^ ((lr >> 1) & 7)) * 8;
;   const u16* ap = A + (ptrdiff_t)lr * lda + gch;
;   const u16* bp = B + (ptrdiff_t)lr * ldb + gch;
;   const int nk = K >> 6;
;   typedef __attribute__((address_space(3))) unsigned lds_u32;
;   auto glds = [&](int kt, int st) {
;     char* as_ = lds + st * 65536 + tid * 16;
; #pragma unroll
;     for (int i = 0; i < 4; ++i) {
;       const int rr = lr + 64 * i;
;       const u16* srca = (rr >= rlo && rr < rhi) ? (ap + (ptrdiff_t)(64 * i) * lda + kt * 64) : (zero_line + lc * 8);
;       __builtin_amdgcn_global_load_lds((const unsigned*)srca, (lds_u32*)(as_ + i * 8192), 16, 0, 0);
;       __builtin_amdgcn_global_load_lds((const unsigned*)(bp + (ptrdiff_t)(64 * i) * ldb + kt * 64), (lds_u32*)(as_ + 32768 + i * 8192), 16, 0, 0);
;     }
;   };
;   const int sw = (r >> 1) & 7;
;   const int arow_off = (wm * 128 + r) * 128;
;   const int brow_off = 32768 + (wn * 64 + r) * 128;
;   __syncthreads();
;   glds(0, 0);
;   asm volatile("s_waitcnt vmcnt(0)" ::: "memory");
;   __syncthreads();
; template <int EPI>
; DI void phase_gemm(const Params& p, const GemmArgs& ga, char* lds) {
;     ...
;     else swap = !(nt == 4 || nt == 5);
;     if (swap) gemm_mainloop<true>(acc, A, ga.lda, rlo, rhi, B, ga.K, ga.K, lds, (const u16*)(p.ws + OFF_ZERO));
;     else gemm_mainloop<false>(acc, A, ga.lda, rlo, rhi, B, ga.K, ga.K, lds, (const u16*)(p.ws + OFF_ZERO));
.LBB0_322:
	s_and_b64 vcc, exec, s[6:7]
	s_cbranch_vccz .LBB0_328
	s_waitcnt vmcnt(5)
	s_nop 8
	v_mov_b32_e32 v10, v204
	s_nop 0
	v_ashrrev_i32_e32 v2, 3, v10
	v_lshrrev_b32_e32 v13, 1, v2
	v_xor_b32_e32 v0, v13, v10
	v_ashrrev_i32_e32 v3, 31, v2
	v_lshlrev_b64 v[4:5], 11, v[2:3]
	v_lshlrev_b32_e32 v0, 4, v0
	v_and_b32_e32 v12, 31, v10
	v_lshl_add_u64 v[6:7], s[14:15], 0, v[4:5]
	v_and_b32_e32 v0, 0x70, v0
	v_lshl_add_u64 v[8:9], s[20:21], 0, v[4:5]
	s_waitcnt vmcnt(4)
	v_lshrrev_b32_e32 v14, 1, v10
	v_lshl_add_u64 v[6:7], v[6:7], 0, v[0:1]
	v_lshl_add_u64 v[164:165], v[8:9], 0, v[0:1]
	v_and_or_b32 v0, v14, s51, v12
	v_lshlrev_b32_e32 v161, 7, v0
	v_lshlrev_b32_e32 v0, 7, v10
	v_lshlrev_b32_e32 v174, 4, v10
	v_and_b32_e32 v163, 0x6f80, v0
	v_and_b32_e32 v0, 0x70, v174
	v_add_u32_e32 v175, 0x8000, v174
	v_lshl_add_u64 v[166:167], s[80:81], 0, v[0:1]
	v_cmp_gt_u32_e32 vcc, s50, v2
	v_readfirstlane_b32 s6, v174
	s_mov_b32 m0, s6
	v_cndmask_b32_e32 v9, v167, v7, vcc
	v_cndmask_b32_e32 v8, v166, v6, vcc
	v_readfirstlane_b32 s6, v175
	v_add_u32_e32 v0, 64, v2
	s_barrier
	s_mov_b32 m0, s6
	s_mov_b64 s[10:11], 0x20000
	v_cmp_gt_u32_e64 s[6:7], s50, v0
	v_add_u32_e32 v0, 0x2000, v174
	v_lshl_add_u64 v[8:9], v[6:7], 0, s[10:11]
	v_readfirstlane_b32 s8, v0
	v_add_u32_e32 v176, 0xa000, v174
	v_cndmask_b32_e64 v9, v167, v9, s[6:7]
	v_cndmask_b32_e64 v8, v166, v8, s[6:7]
	s_mov_b32 m0, s8
	v_readfirstlane_b32 s8, v176
	v_lshl_add_u64 v[8:9], v[164:165], 0, s[10:11]
	s_mov_b32 m0, s8
	v_add_u32_e32 v3, 0x80, v2
	s_mov_b64 s[14:15], 0x40000
	v_add_u32_e32 v177, 0x4000, v174
	v_lshl_add_u64 v[8:9], v[6:7], 0, s[14:15]
	v_cmp_gt_u32_e64 s[8:9], s50, v3
	v_readfirstlane_b32 s10, v177
	v_add_u32_e32 v178, 0xc000, v174
	v_cndmask_b32_e64 v9, v167, v9, s[8:9]
	v_cndmask_b32_e64 v8, v166, v8, s[8:9]
	s_mov_b32 m0, s10
	v_readfirstlane_b32 s10, v178
	v_lshl_add_u64 v[8:9], v[164:165], 0, s[14:15]
	s_mov_b32 m0, s10
	s_mov_b64 s[20:21], 0x60000
	v_add_u32_e32 v8, 0xc0, v2
	v_add_u32_e32 v179, 0x6000, v174
	v_lshl_add_u64 v[2:3], v[6:7], 0, s[20:21]
	v_cmp_gt_u32_e64 s[10:11], s50, v8
	v_readfirstlane_b32 s14, v179
	v_add_u32_e32 v180, 0xe000, v174
	v_cndmask_b32_e64 v3, v167, v3, s[10:11]
	v_cndmask_b32_e64 v2, v166, v2, s[10:11]
	s_mov_b32 m0, s14
	v_readfirstlane_b32 s14, v180
	v_lshl_add_u64 v[2:3], v[164:165], 0, s[20:21]
	s_mov_b32 m0, s14
	v_bfe_u32 v11, v10, 5, 1
	s_sub_i32 s14, s26, s30
	s_lshl_b32 s15, s29, 6
	v_bfe_u32 v15, v10, 1, 3
	v_bitop3_b32 v2, v14, v11, 7 bitop3:0x6c
	s_sub_i32 s14, s14, s15
	v_lshlrev_b32_e32 v181, 4, v2
	v_bitop3_b32 v2, v11, v15, 2 bitop3:0x36
	s_lshl_b32 s14, s14, 8
	v_lshlrev_b32_e32 v182, 4, v2
	v_bitop3_b32 v2, v11, v15, 4 bitop3:0x36
	s_ashr_i32 s15, s14, 31
	v_lshlrev_b32_e32 v183, 4, v2
	v_bitop3_b32 v2, v11, v15, 6 bitop3:0x36
	s_lshl_b64 s[14:15], s[14:15], 11
	v_lshlrev_b32_e32 v186, 4, v2
	v_lshl_add_u64 v[2:3], v[4:5], 0, s[14:15]
	v_bitop3_b32 v4, v13, 7, v10 bitop3:0x48
	s_waitcnt vmcnt(0)
	v_lshl_or_b32 v2, v4, 4, v2
	v_lshl_add_u64 v[168:169], s[70:71], 0, v[2:3]
	v_mov_b32_e32 v130, 0
	v_mov_b32_e32 v2, 0
	s_mov_b32 s13, 1
	v_add_u32_e32 v187, 0x10000, v174
	v_add_u32_e32 v192, 0x18000, v174
	v_add_u32_e32 v193, 0x12000, v174
	v_add_u32_e32 v194, 0x1a000, v174
	v_add_u32_e32 v195, 0x14000, v174
	v_add_u32_e32 v196, 0x1c000, v174
	v_add_u32_e32 v197, 0x16000, v174
	v_add_u32_e32 v198, 0x1e000, v174
	v_add_u32_e32 v199, 0x10000, v161
	v_or_b32_e32 v200, 0x10000, v163
	s_mov_b64 s[14:15], 0
	v_mov_b32_e32 v3, v2
	v_mov_b32_e32 v4, v2
	v_mov_b32_e32 v5, v2
	v_mov_b32_e32 v6, v2
	v_mov_b32_e32 v7, v2
	v_mov_b32_e32 v8, v2
	v_mov_b32_e32 v9, v2
	v_mov_b32_e32 v10, v2
	v_mov_b32_e32 v11, v2
	v_mov_b32_e32 v12, v2
	v_mov_b32_e32 v13, v2
	v_mov_b32_e32 v14, v2
	v_mov_b32_e32 v15, v2
	v_mov_b32_e32 v16, v2
	v_mov_b32_e32 v17, v2
	v_mov_b32_e32 v34, v2
	v_mov_b32_e32 v35, v2
	v_mov_b32_e32 v36, v2
	v_mov_b32_e32 v37, v2
	v_mov_b32_e32 v38, v2
	v_mov_b32_e32 v39, v2
	v_mov_b32_e32 v40, v2
	v_mov_b32_e32 v41, v2
	v_mov_b32_e32 v42, v2
	v_mov_b32_e32 v43, v2
	v_mov_b32_e32 v44, v2
	v_mov_b32_e32 v45, v2
	v_mov_b32_e32 v46, v2
	v_mov_b32_e32 v47, v2
	v_mov_b32_e32 v48, v2
	v_mov_b32_e32 v49, v2
	s_waitcnt vmcnt(0)
; template <bool SWAP>
; DI void gemm_mainloop(f32x16 (&acc)[4][2], const u16* __restrict__ A, int lda, int rlo, int rhi,
;                       const u16* __restrict__ B, int ldb, int K, char* lds, const u16* zero_line) {
;     ...
; #pragma unroll
;   for (int mi = 0; mi < 4; ++mi)
; #pragma unroll
;     for (int ni = 0; ni < 2; ++ni)
; #pragma unroll
;       for (int i = 0; i < 16; ++i) acc[mi][ni][i] = 0.f;
;   const int gch = (lc ^ ((lr >> 1) & 7)) * 8;
;   const u16* ap = A + (ptrdiff_t)lr * lda + gch;
;   const u16* bp = B + (ptrdiff_t)lr * ldb + gch;
;   const int nk = K >> 6;
;   typedef __attribute__((address_space(3))) unsigned lds_u32;
;   auto glds = [&](int kt, int st) {
;     char* as_ = lds + st * 65536 + tid * 16;
; #pragma unroll
;     for (int i = 0; i < 4; ++i) {
;       const int rr = lr + 64 * i;
;       const u16* srca = (rr >= rlo && rr < rhi) ? (ap + (ptrdiff_t)(64 * i) * lda + kt * 64) : (zero_line + lc * 8);
;       __builtin_amdgcn_global_load_lds((const unsigned*)srca, (lds_u32*)(as_ + i * 8192), 16, 0, 0);
;       __builtin_amdgcn_global_load_lds((const unsigned*)(bp + (ptrdiff_t)(64 * i) * ldb + kt * 64), (lds_u32*)(as_ + 32768 + i * 8192), 16, 0, 0);
;     }
;   };
;   const int sw = (r >> 1) & 7;
;   const int arow_off = (wm * 128 + r) * 128;
;   const int brow_off = 32768 + (wn * 64 + r) * 128;
;   __syncthreads();
;   glds(0, 0);
;   asm volatile("s_waitcnt vmcnt(0)" ::: "memory");
;   __syncthreads();
	s_ashr_i32 s7, s12, 31
	s_mov_b32 s6, s12
	s_lshl_b64 s[6:7], s[6:7], 11
	s_add_u32 s6, s90, s6
	s_addc_u32 s7, s91, s7
	s_ashr_i32 s9, s16, 31
	s_mov_b32 s8, s16
	s_lshl_b64 s[8:9], s[8:9], 11
	s_add_u32 s8, s70, s8
	s_addc_u32 s9, s71, s9
	v_and_b32_e32 v130, 63, v204
	v_lshrrev_b32_e32 v131, 6, v204
	v_lshrrev_b32_e32 v132, 3, v204
	v_lshrrev_b32_e32 v0, 4, v130
	v_lshl_add_u32 v0, v131, 2, v0
	v_xor_b32_e32 v0, v0, v130
	v_and_b32_e32 v0, 7, v0
	v_lshlrev_b32_e32 v133, 4, v0
	v_lshl_add_u32 v240, v132, 11, v133
	v_add_u32_e32 v241, 0x20000, v240
	v_add_u32_e32 v242, 0x40000, v240
	v_add_u32_e32 v243, 0x60000, v240
	v_and_b32_e32 v0, 31, v132
	v_lshrrev_b32_e32 v130, 5, v132
	v_lshl_add_u32 v0, v130, 6, v0
	v_lshl_add_u32 v244, v0, 11, v133
	v_add_u32_e32 v245, 0x10000, v244
	v_add_u32_e32 v246, 0x40000, v244
	v_add_u32_e32 v247, 0x50000, v244
	v_and_b32_e32 v132, 31, v204
	v_lshrrev_b32_e32 v0, 2, v131
	v_lshl_add_u32 v0, v0, 6, v132
	v_lshlrev_b32_e32 v166, 7, v0
	v_and_b32_e32 v0, 3, v131
	v_lshl_add_u32 v0, v0, 5, v132
	v_lshlrev_b32_e32 v249, 7, v0
	v_bfe_u32 v0, v204, 5, 1
	v_bfe_u32 v130, v132, 1, 3
	v_or_b32_e32 v133, 0, v0
	v_xor_b32_e32 v133, v133, v130
	v_lshlrev_b32_e32 v161, 4, v133
	v_or_b32_e32 v133, 2, v0
	v_xor_b32_e32 v133, v133, v130
	v_lshlrev_b32_e32 v163, 4, v133
	v_or_b32_e32 v133, 4, v0
	v_xor_b32_e32 v133, v133, v130
	v_lshlrev_b32_e32 v164, 4, v133
	v_or_b32_e32 v133, 6, v0
	v_xor_b32_e32 v133, v133, v130
	v_lshlrev_b32_e32 v165, 4, v133
	v_lshlrev_b32_e32 v131, 10, v131
	s_nop 0
	v_readfirstlane_b32 s100, v131
	v_mov_b32_e32 v146, 0
	v_mov_b32_e32 v147, 0
	v_mov_b32_e32 v148, 0
	v_mov_b32_e32 v149, 0
	v_lshlrev_b32_e32 v130, 4, v204
	v_add_u32_e32 v132, 0x10000, v130
	s_mov_b64 exec, -1
	s_mov_b32 s11, 0
	s_mov_b32 s10, 0x10000
	s_waitcnt lgkmcnt(0)
	s_add_u32 m0, s100, 0x8000
	s_nop 0
	global_load_lds_dwordx4 v244, s[8:9]
	v_add_u32_e32 v244, 0x80, v244
	s_add_u32 m0, s100, 0xa000
	s_nop 0
	global_load_lds_dwordx4 v246, s[8:9]
	v_add_u32_e32 v246, 0x80, v246
	s_add_u32 m0, s100, 0x0
	s_nop 0
	global_load_lds_dwordx4 v240, s[6:7]
	v_add_u32_e32 v240, 0x80, v240
	s_add_u32 m0, s100, 0x2000
	s_nop 0
	global_load_lds_dwordx4 v242, s[6:7]
	v_add_u32_e32 v242, 0x80, v242
	s_add_u32 m0, s100, 0xc000
	s_nop 0
	global_load_lds_dwordx4 v245, s[8:9]
	v_add_u32_e32 v245, 0x80, v245
	s_add_u32 m0, s100, 0xe000
	s_nop 0
	global_load_lds_dwordx4 v247, s[8:9]
	v_add_u32_e32 v247, 0x80, v247
	s_add_u32 m0, s100, 0x4000
	s_nop 0
	global_load_lds_dwordx4 v241, s[6:7]
	v_add_u32_e32 v241, 0x80, v241
	s_add_u32 m0, s100, 0x6000
	s_nop 0
	global_load_lds_dwordx4 v243, s[6:7]
	v_add_u32_e32 v243, 0x80, v243
	v_mov_b32_e32 v18, v2
	v_mov_b32_e32 v19, v2
	v_mov_b32_e32 v20, v2
	v_mov_b32_e32 v21, v2
	v_mov_b32_e32 v22, v2
	v_mov_b32_e32 v23, v2
	v_mov_b32_e32 v24, v2
	v_mov_b32_e32 v25, v2
	v_mov_b32_e32 v26, v2
	v_mov_b32_e32 v27, v2
	v_mov_b32_e32 v28, v2
	v_mov_b32_e32 v29, v2
	v_mov_b32_e32 v30, v2
	v_mov_b32_e32 v31, v2
	v_mov_b32_e32 v32, v2
	v_mov_b32_e32 v33, v2
	v_mov_b32_e32 v66, v2
	v_mov_b32_e32 v67, v2
	v_mov_b32_e32 v68, v2
	v_mov_b32_e32 v69, v2
	v_mov_b32_e32 v70, v2
	v_mov_b32_e32 v71, v2
	v_mov_b32_e32 v72, v2
	v_mov_b32_e32 v73, v2
	v_mov_b32_e32 v74, v2
	v_mov_b32_e32 v75, v2
	v_mov_b32_e32 v76, v2
	v_mov_b32_e32 v77, v2
	v_mov_b32_e32 v78, v2
	v_mov_b32_e32 v79, v2
	v_mov_b32_e32 v80, v2
	v_mov_b32_e32 v81, v2
	v_mov_b32_e32 v50, v2
	v_mov_b32_e32 v51, v2
	v_mov_b32_e32 v52, v2
	v_mov_b32_e32 v53, v2
	v_mov_b32_e32 v54, v2
	v_mov_b32_e32 v55, v2
	v_mov_b32_e32 v56, v2
	v_mov_b32_e32 v57, v2
	v_mov_b32_e32 v58, v2
	v_mov_b32_e32 v59, v2
	v_mov_b32_e32 v60, v2
	v_mov_b32_e32 v61, v2
	v_mov_b32_e32 v62, v2
	v_mov_b32_e32 v63, v2
	v_mov_b32_e32 v64, v2
	v_mov_b32_e32 v65, v2
	v_mov_b32_e32 v98, v2
	v_mov_b32_e32 v99, v2
	v_mov_b32_e32 v100, v2
	v_mov_b32_e32 v101, v2
	v_mov_b32_e32 v102, v2
	v_mov_b32_e32 v103, v2
	v_mov_b32_e32 v104, v2
	v_mov_b32_e32 v105, v2
	v_mov_b32_e32 v106, v2
	v_mov_b32_e32 v107, v2
	v_mov_b32_e32 v108, v2
	v_mov_b32_e32 v109, v2
	v_mov_b32_e32 v110, v2
	v_mov_b32_e32 v111, v2
	v_mov_b32_e32 v112, v2
	v_mov_b32_e32 v113, v2
	v_mov_b32_e32 v82, v2
	v_mov_b32_e32 v83, v2
	v_mov_b32_e32 v84, v2
	v_mov_b32_e32 v85, v2
	v_mov_b32_e32 v86, v2
	v_mov_b32_e32 v87, v2
	v_mov_b32_e32 v88, v2
	v_mov_b32_e32 v89, v2
	v_mov_b32_e32 v90, v2
	v_mov_b32_e32 v91, v2
	v_mov_b32_e32 v92, v2
	v_mov_b32_e32 v93, v2
	v_mov_b32_e32 v94, v2
	v_mov_b32_e32 v95, v2
	v_mov_b32_e32 v96, v2
	v_mov_b32_e32 v97, v2
	v_mov_b32_e32 v114, v2
	v_mov_b32_e32 v115, v2
	v_mov_b32_e32 v116, v2
	v_mov_b32_e32 v117, v2
	v_mov_b32_e32 v118, v2
	v_mov_b32_e32 v119, v2
	v_mov_b32_e32 v120, v2
	v_mov_b32_e32 v121, v2
	v_mov_b32_e32 v122, v2
	v_mov_b32_e32 v123, v2
	v_mov_b32_e32 v124, v2
	v_mov_b32_e32 v125, v2
	v_mov_b32_e32 v126, v2
	v_mov_b32_e32 v127, v2
	v_mov_b32_e32 v128, v2
	v_mov_b32_e32 v129, v2
	v_mov_b32_e32 v131, v130
	v_mov_b32_e32 v132, v130
	v_mov_b32_e32 v133, v130
	v_mov_b32_e32 v134, v130
	v_mov_b32_e32 v135, v130
	v_mov_b32_e32 v136, v130
	v_mov_b32_e32 v137, v130
	v_mov_b32_e32 v138, v130
	v_mov_b32_e32 v139, v130
	v_mov_b32_e32 v140, v130
	v_mov_b32_e32 v141, v130
	v_mov_b32_e32 v146, v130
	v_mov_b32_e32 v147, v130
	v_mov_b32_e32 v148, v130
	v_mov_b32_e32 v149, v130
	v_mov_b32_e32 v142, v130
	v_mov_b32_e32 v143, v130
	v_mov_b32_e32 v144, v130
	v_mov_b32_e32 v145, v130
	v_mov_b32_e32 v150, v130
	v_mov_b32_e32 v151, v130
	v_mov_b32_e32 v152, v130
	v_mov_b32_e32 v153, v130
	s_waitcnt lgkmcnt(0)
	s_barrier
	s_ashr_i32 s7, s12, 31
	s_mov_b32 s6, s12
	s_lshl_b64 s[6:7], s[6:7], 11
	s_add_u32 s6, s90, s6
	s_addc_u32 s7, s91, s7
	s_ashr_i32 s9, s16, 31
	s_mov_b32 s8, s16
	s_lshl_b64 s[8:9], s[8:9], 11
	s_add_u32 s8, s70, s8
	s_addc_u32 s9, s71, s9
	s_mov_b32 s11, 0
	s_mov_b32 s10, 0x10000
	s_cmp_eq_u32 s101, 1
	s_cbranch_scc0 .Lg8_ib_p0
	s_barrier

; #define MFMA(a, b, c) __builtin_amdgcn_mfma_f32_32x32x16_bf16((a), (b), (c), 0, 0, 0)
; template <bool SWAP>
; DI void gemm_mainloop(f32x16 (&acc)[4][2], const u16* __restrict__ A, int lda, int rlo, int rhi,
;                       const u16* __restrict__ B, int ldb, int K, char* lds, const u16* zero_line) {
;     ...
;   auto ldfrag = [&](const char* st, int ks, int buf) {
;     const int co = ((2 * ks + h) ^ sw) << 4;
; #pragma unroll
;     for (int mi = 0; mi < 4; ++mi) fa[buf][mi] = *(const bf16x8*)(st + arow_off + mi * 4096 + co);
; #pragma unroll
;     for (int ni = 0; ni < 2; ++ni) fb[buf][ni] = *(const bf16x8*)(st + brow_off + ni * 4096 + co);
;   };
;   auto mma = [&](int buf) {
; #pragma unroll
;     for (int mi = 0; mi < 4; ++mi)
; #pragma unroll
;       for (int ni = 0; ni < 2; ++ni)
;         acc[mi][ni] = SWAP ? MFMA(fb[buf][ni], fa[buf][mi], acc[mi][ni]) : MFMA(fa[buf][mi], fb[buf][ni], acc[mi][ni]);
;   };
;   auto pat_rd = [&]() {
; #pragma unroll
;     for (int g = 0; g < 6; ++g) {
;       __builtin_amdgcn_sched_group_barrier(0x100, 1, 0);
;       __builtin_amdgcn_sched_group_barrier(0x008, 1, 0);
;     }
;     __builtin_amdgcn_sched_group_barrier(0x008, 2, 0);
;   };
; #pragma unroll 2
;   for (int kt = 0; kt < nk; ++kt) {
;     const char* st = lds + (kt & 1) * 65536;
;     ldfrag(st, 0, 0);
;     mma(1);
;     pat_rd();
;     if (kt + 1 < nk) glds(kt + 1, (kt + 1) & 1);
;     ldfrag(st, 1, 1);
;     mma(0);
;     pat_rd();
;     ldfrag(st, 2, 0);
;     mma(1);
;     pat_rd();
;     ldfrag(st, 3, 1);
;     mma(0);
;     pat_rd();
;     asm volatile("s_waitcnt vmcnt(0)" ::: "memory");
;     __syncthreads();
.Lg8_ib:
	v_add3_u32 v186, v166, v161, 0
	v_add3_u32 v187, v166, v163, 0
	ds_read_b128 v[130:133], v186
	ds_read_b128 v[134:137], v187
	ds_read_b128 v[146:149], v186 offset:4096
	ds_read_b128 v[150:153], v187 offset:4096
	v_add3_u32 v186, v166, v164, 0
	v_add3_u32 v187, v166, v165, 0
	ds_read_b128 v[138:141], v186
	ds_read_b128 v[142:145], v187
	ds_read_b128 v[168:171], v186 offset:4096
	ds_read_b128 v[172:175], v187 offset:4096
	s_add_u32 m0, s100, 0x14000
	s_nop 0
	global_load_lds_dwordx4 v241, s[6:7]
	v_add_u32_e32 v241, 0x80, v241
	s_add_u32 m0, s100, 0x16000
	s_nop 0
	global_load_lds_dwordx4 v243, s[6:7]
	v_add_u32_e32 v243, 0x80, v243
	s_barrier
	s_waitcnt lgkmcnt(0)
	v_mfma_f32_32x32x16_bf16 v[114:129], v[130:133], v[176:179], v[114:129]
	v_mfma_f32_32x32x16_bf16 v[98:113], v[146:149], v[176:179], v[98:113]
	v_mfma_f32_32x32x16_bf16 v[114:129], v[134:137], v[180:183], v[114:129]
	v_mfma_f32_32x32x16_bf16 v[98:113], v[150:153], v[180:183], v[98:113]
	v_mfma_f32_32x32x16_bf16 v[114:129], v[138:141], v[192:195], v[114:129]
	v_mfma_f32_32x32x16_bf16 v[98:113], v[168:171], v[192:195], v[98:113]
	v_mfma_f32_32x32x16_bf16 v[114:129], v[142:145], v[196:199], v[114:129]
	v_mfma_f32_32x32x16_bf16 v[98:113], v[172:175], v[196:199], v[98:113]
	s_barrier
	v_add3_u32 v186, v249, v161, 0
	v_add3_u32 v187, v249, v163, 0
	ds_read_b128 v[200:203], v186 offset:49152
	ds_read_b128 v[228:231], v187 offset:49152
	v_add3_u32 v186, v249, v164, 0
	v_add3_u32 v187, v249, v165, 0
	ds_read_b128 v[232:235], v186 offset:49152
	ds_read_b128 v[236:239], v187 offset:49152
	s_add_u32 m0, s100, 0x8000
	s_nop 0
	global_load_lds_dwordx4 v244, s[8:9]
	v_add_u32_e32 v244, 0x80, v244
	s_add_u32 m0, s100, 0xa000
	s_nop 0
	global_load_lds_dwordx4 v246, s[8:9]
	v_add_u32_e32 v246, 0x80, v246
	s_barrier
	s_waitcnt lgkmcnt(0)
	v_mfma_f32_32x32x16_bf16 v[82:97], v[130:133], v[200:203], v[82:97]
	v_mfma_f32_32x32x16_bf16 v[50:65], v[146:149], v[200:203], v[50:65]
	v_mfma_f32_32x32x16_bf16 v[82:97], v[134:137], v[228:231], v[82:97]
	v_mfma_f32_32x32x16_bf16 v[50:65], v[150:153], v[228:231], v[50:65]
	v_mfma_f32_32x32x16_bf16 v[82:97], v[138:141], v[232:235], v[82:97]
	v_mfma_f32_32x32x16_bf16 v[50:65], v[168:171], v[232:235], v[50:65]
	v_mfma_f32_32x32x16_bf16 v[82:97], v[142:145], v[236:239], v[82:97]
	v_mfma_f32_32x32x16_bf16 v[50:65], v[172:175], v[236:239], v[50:65]
	s_barrier
	v_add3_u32 v186, v166, v161, 0
	v_add3_u32 v187, v166, v163, 0
	ds_read_b128 v[130:133], v186 offset:16384
	ds_read_b128 v[134:137], v187 offset:16384
	ds_read_b128 v[146:149], v186 offset:20480
	ds_read_b128 v[150:153], v187 offset:20480
	v_add3_u32 v186, v166, v164, 0
	v_add3_u32 v187, v166, v165, 0
	ds_read_b128 v[138:141], v186 offset:16384
	ds_read_b128 v[142:145], v187 offset:16384
	ds_read_b128 v[168:171], v186 offset:20480
	ds_read_b128 v[172:175], v187 offset:20480
	s_add_u32 m0, s100, 0x0
	s_nop 0
	global_load_lds_dwordx4 v240, s[6:7]
	v_add_u32_e32 v240, 0x80, v240
	s_add_u32 m0, s100, 0x2000
	s_nop 0
	global_load_lds_dwordx4 v242, s[6:7]
	v_add_u32_e32 v242, 0x80, v242
	s_waitcnt vmcnt(10)
	s_barrier
	s_waitcnt lgkmcnt(0)
	v_mfma_f32_32x32x16_bf16 v[66:81], v[130:133], v[176:179], v[66:81]
	v_mfma_f32_32x32x16_bf16 v[34:49], v[146:149], v[176:179], v[34:49]
	v_mfma_f32_32x32x16_bf16 v[66:81], v[134:137], v[180:183], v[66:81]
	v_mfma_f32_32x32x16_bf16 v[34:49], v[150:153], v[180:183], v[34:49]
	v_mfma_f32_32x32x16_bf16 v[66:81], v[138:141], v[192:195], v[66:81]
	v_mfma_f32_32x32x16_bf16 v[34:49], v[168:171], v[192:195], v[34:49]
	v_mfma_f32_32x32x16_bf16 v[66:81], v[142:145], v[196:199], v[66:81]
	v_mfma_f32_32x32x16_bf16 v[34:49], v[172:175], v[196:199], v[34:49]
	s_barrier
	v_add3_u32 v186, v249, v161, s10
	v_add3_u32 v187, v249, v163, s10
	ds_read_b128 v[176:179], v186 offset:32768
	ds_read_b128 v[180:183], v187 offset:32768
	v_add3_u32 v186, v249, v164, s10
	v_add3_u32 v187, v249, v165, s10
	ds_read_b128 v[192:195], v186 offset:32768
	ds_read_b128 v[196:199], v187 offset:32768
	s_add_u32 m0, s100, 0xc000
	s_nop 0
	global_load_lds_dwordx4 v245, s[8:9]
	v_add_u32_e32 v245, 0x80, v245
	s_add_u32 m0, s100, 0xe000
	s_nop 0
	global_load_lds_dwordx4 v247, s[8:9]
	v_add_u32_e32 v247, 0x80, v247
	s_waitcnt vmcnt(6)
	s_barrier
	s_waitcnt lgkmcnt(0)
	v_mfma_f32_32x32x16_bf16 v[18:33], v[130:133], v[200:203], v[18:33]
	v_mfma_f32_32x32x16_bf16 v[2:17], v[146:149], v[200:203], v[2:17]
	v_mfma_f32_32x32x16_bf16 v[18:33], v[134:137], v[228:231], v[18:33]
	v_mfma_f32_32x32x16_bf16 v[2:17], v[150:153], v[228:231], v[2:17]
	v_mfma_f32_32x32x16_bf16 v[18:33], v[138:141], v[232:235], v[18:33]
	v_mfma_f32_32x32x16_bf16 v[2:17], v[168:171], v[232:235], v[2:17]
	v_mfma_f32_32x32x16_bf16 v[18:33], v[142:145], v[236:239], v[18:33]
	v_mfma_f32_32x32x16_bf16 v[2:17], v[172:175], v[236:239], v[2:17]
	s_barrier
	v_add3_u32 v186, v166, v161, s10
	v_add3_u32 v187, v166, v163, s10
	ds_read_b128 v[130:133], v186
	ds_read_b128 v[134:137], v187
	ds_read_b128 v[146:149], v186 offset:4096
	ds_read_b128 v[150:153], v187 offset:4096
	v_add3_u32 v186, v166, v164, s10
	v_add3_u32 v187, v166, v165, s10
	ds_read_b128 v[138:141], v186
	ds_read_b128 v[142:145], v187
	ds_read_b128 v[168:171], v186 offset:4096
	ds_read_b128 v[172:175], v187 offset:4096
	s_add_u32 m0, s100, 0x4000
	s_nop 0
	global_load_lds_dwordx4 v241, s[6:7]
	v_add_u32_e32 v241, 0x80, v241
	s_add_u32 m0, s100, 0x6000
	s_nop 0
	global_load_lds_dwordx4 v243, s[6:7]
	v_add_u32_e32 v243, 0x80, v243
	s_barrier
; #define MFMA(a, b, c) __builtin_amdgcn_mfma_f32_32x32x16_bf16((a), (b), (c), 0, 0, 0)
; template <bool SWAP>
; DI void gemm_mainloop(f32x16 (&acc)[4][2], const u16* __restrict__ A, int lda, int rlo, int rhi,
;                       const u16* __restrict__ B, int ldb, int K, char* lds, const u16* zero_line) {
;     ...
;   auto ldfrag = [&](const char* st, int ks, int buf) {
;     const int co = ((2 * ks + h) ^ sw) << 4;
; #pragma unroll
;     for (int mi = 0; mi < 4; ++mi) fa[buf][mi] = *(const bf16x8*)(st + arow_off + mi * 4096 + co);
; #pragma unroll
;     for (int ni = 0; ni < 2; ++ni) fb[buf][ni] = *(const bf16x8*)(st + brow_off + ni * 4096 + co);
;   };
;   auto mma = [&](int buf) {
; #pragma unroll
;     for (int mi = 0; mi < 4; ++mi)
; #pragma unroll
;       for (int ni = 0; ni < 2; ++ni)
;         acc[mi][ni] = SWAP ? MFMA(fb[buf][ni], fa[buf][mi], acc[mi][ni]) : MFMA(fa[buf][mi], fb[buf][ni], acc[mi][ni]);
;   };
;   auto pat_rd = [&]() {
; #pragma unroll
;     for (int g = 0; g < 6; ++g) {
;       __builtin_amdgcn_sched_group_barrier(0x100, 1, 0);
;       __builtin_amdgcn_sched_group_barrier(0x008, 1, 0);
;     }
;     __builtin_amdgcn_sched_group_barrier(0x008, 2, 0);
;   };
; #pragma unroll 2
;   for (int kt = 0; kt < nk; ++kt) {
;     const char* st = lds + (kt & 1) * 65536;
;     ldfrag(st, 0, 0);
;     mma(1);
;     pat_rd();
;     if (kt + 1 < nk) glds(kt + 1, (kt + 1) & 1);
;     ldfrag(st, 1, 1);
;     mma(0);
;     pat_rd();
;     ldfrag(st, 2, 0);
;     mma(1);
;     pat_rd();
;     ldfrag(st, 3, 1);
;     mma(0);
;     pat_rd();
;     asm volatile("s_waitcnt vmcnt(0)" ::: "memory");
;     __syncthreads();
	s_waitcnt lgkmcnt(0)
	v_mfma_f32_32x32x16_bf16 v[114:129], v[130:133], v[176:179], v[114:129]
	v_mfma_f32_32x32x16_bf16 v[98:113], v[146:149], v[176:179], v[98:113]
	v_mfma_f32_32x32x16_bf16 v[114:129], v[134:137], v[180:183], v[114:129]
	v_mfma_f32_32x32x16_bf16 v[98:113], v[150:153], v[180:183], v[98:113]
	v_mfma_f32_32x32x16_bf16 v[114:129], v[138:141], v[192:195], v[114:129]
	v_mfma_f32_32x32x16_bf16 v[98:113], v[168:171], v[192:195], v[98:113]
	v_mfma_f32_32x32x16_bf16 v[114:129], v[142:145], v[196:199], v[114:129]
	v_mfma_f32_32x32x16_bf16 v[98:113], v[172:175], v[196:199], v[98:113]
	s_barrier
	v_add3_u32 v186, v249, v161, s10
	v_add3_u32 v187, v249, v163, s10
	ds_read_b128 v[200:203], v186 offset:49152
	ds_read_b128 v[228:231], v187 offset:49152
	v_add3_u32 v186, v249, v164, s10
	v_add3_u32 v187, v249, v165, s10
	ds_read_b128 v[232:235], v186 offset:49152
	ds_read_b128 v[236:239], v187 offset:49152
	s_add_u32 m0, s100, 0x18000
	s_nop 0
	global_load_lds_dwordx4 v244, s[8:9]
	v_add_u32_e32 v244, 0x80, v244
	s_add_u32 m0, s100, 0x1a000
	s_nop 0
	global_load_lds_dwordx4 v246, s[8:9]
	v_add_u32_e32 v246, 0x80, v246
	s_barrier
	s_waitcnt lgkmcnt(0)
	v_mfma_f32_32x32x16_bf16 v[82:97], v[130:133], v[200:203], v[82:97]
	v_mfma_f32_32x32x16_bf16 v[50:65], v[146:149], v[200:203], v[50:65]
	v_mfma_f32_32x32x16_bf16 v[82:97], v[134:137], v[228:231], v[82:97]
	v_mfma_f32_32x32x16_bf16 v[50:65], v[150:153], v[228:231], v[50:65]
	v_mfma_f32_32x32x16_bf16 v[82:97], v[138:141], v[232:235], v[82:97]
	v_mfma_f32_32x32x16_bf16 v[50:65], v[168:171], v[232:235], v[50:65]
	v_mfma_f32_32x32x16_bf16 v[82:97], v[142:145], v[236:239], v[82:97]
	v_mfma_f32_32x32x16_bf16 v[50:65], v[172:175], v[236:239], v[50:65]
	s_barrier
	v_add3_u32 v186, v166, v161, s10
	v_add3_u32 v187, v166, v163, s10
	ds_read_b128 v[130:133], v186 offset:16384
	ds_read_b128 v[134:137], v187 offset:16384
	ds_read_b128 v[146:149], v186 offset:20480
	ds_read_b128 v[150:153], v187 offset:20480
	v_add3_u32 v186, v166, v164, s10
	v_add3_u32 v187, v166, v165, s10
	ds_read_b128 v[138:141], v186 offset:16384
	ds_read_b128 v[142:145], v187 offset:16384
	ds_read_b128 v[168:171], v186 offset:20480
	ds_read_b128 v[172:175], v187 offset:20480
	s_add_u32 m0, s100, 0x10000
	s_nop 0
	global_load_lds_dwordx4 v240, s[6:7]
	v_add_u32_e32 v240, 0x80, v240
	s_add_u32 m0, s100, 0x12000
	s_nop 0
	global_load_lds_dwordx4 v242, s[6:7]
	v_add_u32_e32 v242, 0x80, v242
	s_waitcnt vmcnt(10)
	s_barrier
	s_waitcnt lgkmcnt(0)
	v_mfma_f32_32x32x16_bf16 v[66:81], v[130:133], v[176:179], v[66:81]
	v_mfma_f32_32x32x16_bf16 v[34:49], v[146:149], v[176:179], v[34:49]
	v_mfma_f32_32x32x16_bf16 v[66:81], v[134:137], v[180:183], v[66:81]
	v_mfma_f32_32x32x16_bf16 v[34:49], v[150:153], v[180:183], v[34:49]
	v_mfma_f32_32x32x16_bf16 v[66:81], v[138:141], v[192:195], v[66:81]
	v_mfma_f32_32x32x16_bf16 v[34:49], v[168:171], v[192:195], v[34:49]
	v_mfma_f32_32x32x16_bf16 v[66:81], v[142:145], v[196:199], v[66:81]
	v_mfma_f32_32x32x16_bf16 v[34:49], v[172:175], v[196:199], v[34:49]
	s_barrier
	v_add3_u32 v186, v249, v161, 0
	v_add3_u32 v187, v249, v163, 0
	ds_read_b128 v[176:179], v186 offset:32768
	ds_read_b128 v[180:183], v187 offset:32768
	v_add3_u32 v186, v249, v164, 0
	v_add3_u32 v187, v249, v165, 0
	ds_read_b128 v[192:195], v186 offset:32768
	ds_read_b128 v[196:199], v187 offset:32768
	s_add_u32 m0, s100, 0x1c000
	s_nop 0
	global_load_lds_dwordx4 v245, s[8:9]
	v_add_u32_e32 v245, 0x80, v245
	s_add_u32 m0, s100, 0x1e000
	s_nop 0
	global_load_lds_dwordx4 v247, s[8:9]
	v_add_u32_e32 v247, 0x80, v247
	s_waitcnt vmcnt(6)
	s_barrier
	s_waitcnt lgkmcnt(0)
	v_mfma_f32_32x32x16_bf16 v[18:33], v[130:133], v[200:203], v[18:33]
	v_mfma_f32_32x32x16_bf16 v[2:17], v[146:149], v[200:203], v[2:17]
	v_mfma_f32_32x32x16_bf16 v[18:33], v[134:137], v[228:231], v[18:33]
	v_mfma_f32_32x32x16_bf16 v[2:17], v[150:153], v[228:231], v[2:17]
	v_mfma_f32_32x32x16_bf16 v[18:33], v[138:141], v[232:235], v[18:33]
	v_mfma_f32_32x32x16_bf16 v[2:17], v[168:171], v[232:235], v[2:17]
	v_mfma_f32_32x32x16_bf16 v[18:33], v[142:145], v[236:239], v[18:33]
	v_mfma_f32_32x32x16_bf16 v[2:17], v[172:175], v[236:239], v[2:17]
	s_barrier
	s_add_i32 s11, s11, 2
	s_cmp_lt_u32 s11, 14
	s_cbranch_scc1 .Lg8_ib
	v_add3_u32 v186, v166, v161, 0
	v_add3_u32 v187, v166, v163, 0
	ds_read_b128 v[130:133], v186
	ds_read_b128 v[134:137], v187
	ds_read_b128 v[146:149], v186 offset:4096
	ds_read_b128 v[150:153], v187 offset:4096
	v_add3_u32 v186, v166, v164, 0
	v_add3_u32 v187, v166, v165, 0
	ds_read_b128 v[138:141], v186
	ds_read_b128 v[142:145], v187
	ds_read_b128 v[168:171], v186 offset:4096
	ds_read_b128 v[172:175], v187 offset:4096
	s_add_u32 m0, s100, 0x14000
	s_nop 0
	global_load_lds_dwordx4 v241, s[6:7]
	v_add_u32_e32 v241, 0x80, v241
	s_add_u32 m0, s100, 0x16000
	s_nop 0
	global_load_lds_dwordx4 v243, s[6:7]
	v_add_u32_e32 v243, 0x80, v243
	s_barrier
	s_waitcnt lgkmcnt(0)
	v_mfma_f32_32x32x16_bf16 v[114:129], v[130:133], v[176:179], v[114:129]
	v_mfma_f32_32x32x16_bf16 v[98:113], v[146:149], v[176:179], v[98:113]
	v_mfma_f32_32x32x16_bf16 v[114:129], v[134:137], v[180:183], v[114:129]
	v_mfma_f32_32x32x16_bf16 v[98:113], v[150:153], v[180:183], v[98:113]
	v_mfma_f32_32x32x16_bf16 v[114:129], v[138:141], v[192:195], v[114:129]
	v_mfma_f32_32x32x16_bf16 v[98:113], v[168:171], v[192:195], v[98:113]
	v_mfma_f32_32x32x16_bf16 v[114:129], v[142:145], v[196:199], v[114:129]
	v_mfma_f32_32x32x16_bf16 v[98:113], v[172:175], v[196:199], v[98:113]
	s_barrier
; template <bool SWAP>
; DI void gemm_mainloop(f32x16 (&acc)[4][2], const u16* __restrict__ A, int lda, int rlo, int rhi,
;                       const u16* __restrict__ B, int ldb, int K, char* lds, const u16* zero_line) {
;     ...
; #pragma unroll 2
;   for (int kt = 0; kt < nk; ++kt) {
;     const char* st = lds + (kt & 1) * 65536;
;     ldfrag(st, 0, 0);
;     mma(1);
;     pat_rd();
;     if (kt + 1 < nk) glds(kt + 1, (kt + 1) & 1);
;     ldfrag(st, 1, 1);
;     mma(0);
;     pat_rd();
;     ldfrag(st, 2, 0);
;     mma(1);
;     pat_rd();
;     ldfrag(st, 3, 1);
;     mma(0);
;     pat_rd();
;     asm volatile("s_waitcnt vmcnt(0)" ::: "memory");
;     __syncthreads();
;   }
;   mma(1);
	v_add3_u32 v186, v249, v161, 0
	v_add3_u32 v187, v249, v163, 0
	ds_read_b128 v[200:203], v186 offset:49152
	ds_read_b128 v[228:231], v187 offset:49152
	v_add3_u32 v186, v249, v164, 0
	v_add3_u32 v187, v249, v165, 0
	ds_read_b128 v[232:235], v186 offset:49152
	ds_read_b128 v[236:239], v187 offset:49152
	s_barrier
	s_waitcnt lgkmcnt(0)
	v_mfma_f32_32x32x16_bf16 v[82:97], v[130:133], v[200:203], v[82:97]
	v_mfma_f32_32x32x16_bf16 v[50:65], v[146:149], v[200:203], v[50:65]
	v_mfma_f32_32x32x16_bf16 v[82:97], v[134:137], v[228:231], v[82:97]
	v_mfma_f32_32x32x16_bf16 v[50:65], v[150:153], v[228:231], v[50:65]
	v_mfma_f32_32x32x16_bf16 v[82:97], v[138:141], v[232:235], v[82:97]
	v_mfma_f32_32x32x16_bf16 v[50:65], v[168:171], v[232:235], v[50:65]
	v_mfma_f32_32x32x16_bf16 v[82:97], v[142:145], v[236:239], v[82:97]
	v_mfma_f32_32x32x16_bf16 v[50:65], v[172:175], v[236:239], v[50:65]
	s_barrier
	v_add3_u32 v186, v166, v161, 0
	v_add3_u32 v187, v166, v163, 0
	ds_read_b128 v[130:133], v186 offset:16384
	ds_read_b128 v[134:137], v187 offset:16384
	ds_read_b128 v[146:149], v186 offset:20480
	ds_read_b128 v[150:153], v187 offset:20480
	v_add3_u32 v186, v166, v164, 0
	v_add3_u32 v187, v166, v165, 0
	ds_read_b128 v[138:141], v186 offset:16384
	ds_read_b128 v[142:145], v187 offset:16384
	ds_read_b128 v[168:171], v186 offset:20480
	ds_read_b128 v[172:175], v187 offset:20480
	s_waitcnt vmcnt(4)
	s_barrier
	s_waitcnt lgkmcnt(0)
	v_mfma_f32_32x32x16_bf16 v[66:81], v[130:133], v[176:179], v[66:81]
	v_mfma_f32_32x32x16_bf16 v[34:49], v[146:149], v[176:179], v[34:49]
	v_mfma_f32_32x32x16_bf16 v[66:81], v[134:137], v[180:183], v[66:81]
	v_mfma_f32_32x32x16_bf16 v[34:49], v[150:153], v[180:183], v[34:49]
	v_mfma_f32_32x32x16_bf16 v[66:81], v[138:141], v[192:195], v[66:81]
	v_mfma_f32_32x32x16_bf16 v[34:49], v[168:171], v[192:195], v[34:49]
	v_mfma_f32_32x32x16_bf16 v[66:81], v[142:145], v[196:199], v[66:81]
	v_mfma_f32_32x32x16_bf16 v[34:49], v[172:175], v[196:199], v[34:49]
	v_mfma_f32_32x32x16_bf16 v[18:33], v[130:133], v[200:203], v[18:33]
	v_mfma_f32_32x32x16_bf16 v[2:17], v[146:149], v[200:203], v[2:17]
	v_mfma_f32_32x32x16_bf16 v[18:33], v[134:137], v[228:231], v[18:33]
	v_mfma_f32_32x32x16_bf16 v[2:17], v[150:153], v[228:231], v[2:17]
	v_mfma_f32_32x32x16_bf16 v[18:33], v[138:141], v[232:235], v[18:33]
	v_mfma_f32_32x32x16_bf16 v[2:17], v[168:171], v[232:235], v[2:17]
	v_mfma_f32_32x32x16_bf16 v[18:33], v[142:145], v[236:239], v[18:33]
	v_mfma_f32_32x32x16_bf16 v[2:17], v[172:175], v[236:239], v[2:17]
	s_barrier
	v_add3_u32 v186, v249, v161, s10
	v_add3_u32 v187, v249, v163, s10
	ds_read_b128 v[176:179], v186 offset:32768
	ds_read_b128 v[180:183], v187 offset:32768
	v_add3_u32 v186, v249, v164, s10
	v_add3_u32 v187, v249, v165, s10
	ds_read_b128 v[192:195], v186 offset:32768
	ds_read_b128 v[196:199], v187 offset:32768
	v_add3_u32 v186, v166, v161, s10
	v_add3_u32 v187, v166, v163, s10
	ds_read_b128 v[130:133], v186
	ds_read_b128 v[134:137], v187
	ds_read_b128 v[146:149], v186 offset:4096
	ds_read_b128 v[150:153], v187 offset:4096
	v_add3_u32 v186, v166, v164, s10
	v_add3_u32 v187, v166, v165, s10
	ds_read_b128 v[138:141], v186
	ds_read_b128 v[142:145], v187
	ds_read_b128 v[168:171], v186 offset:4096
	ds_read_b128 v[172:175], v187 offset:4096
	s_waitcnt vmcnt(2)
	s_barrier
	s_waitcnt lgkmcnt(0)
	v_mfma_f32_32x32x16_bf16 v[114:129], v[130:133], v[176:179], v[114:129]
	v_mfma_f32_32x32x16_bf16 v[98:113], v[146:149], v[176:179], v[98:113]
	v_mfma_f32_32x32x16_bf16 v[114:129], v[134:137], v[180:183], v[114:129]
	v_mfma_f32_32x32x16_bf16 v[98:113], v[150:153], v[180:183], v[98:113]
	v_mfma_f32_32x32x16_bf16 v[114:129], v[138:141], v[192:195], v[114:129]
	v_mfma_f32_32x32x16_bf16 v[98:113], v[168:171], v[192:195], v[98:113]
	v_mfma_f32_32x32x16_bf16 v[114:129], v[142:145], v[196:199], v[114:129]
	v_mfma_f32_32x32x16_bf16 v[98:113], v[172:175], v[196:199], v[98:113]
	s_barrier
	v_add3_u32 v186, v249, v161, s10
	v_add3_u32 v187, v249, v163, s10
	ds_read_b128 v[200:203], v186 offset:49152
	ds_read_b128 v[228:231], v187 offset:49152
	v_add3_u32 v186, v249, v164, s10
	v_add3_u32 v187, v249, v165, s10
	ds_read_b128 v[232:235], v186 offset:49152
	ds_read_b128 v[236:239], v187 offset:49152
	s_waitcnt vmcnt(0)
	s_barrier
	s_waitcnt lgkmcnt(0)
	v_mfma_f32_32x32x16_bf16 v[82:97], v[130:133], v[200:203], v[82:97]
	v_mfma_f32_32x32x16_bf16 v[50:65], v[146:149], v[200:203], v[50:65]
	v_mfma_f32_32x32x16_bf16 v[82:97], v[134:137], v[228:231], v[82:97]
	v_mfma_f32_32x32x16_bf16 v[50:65], v[150:153], v[228:231], v[50:65]
	v_mfma_f32_32x32x16_bf16 v[82:97], v[138:141], v[232:235], v[82:97]
	v_mfma_f32_32x32x16_bf16 v[50:65], v[168:171], v[232:235], v[50:65]
	v_mfma_f32_32x32x16_bf16 v[82:97], v[142:145], v[236:239], v[82:97]
	v_mfma_f32_32x32x16_bf16 v[50:65], v[172:175], v[236:239], v[50:65]
	s_barrier
	v_add3_u32 v186, v166, v161, s10
	v_add3_u32 v187, v166, v163, s10
	ds_read_b128 v[130:133], v186 offset:16384
	ds_read_b128 v[134:137], v187 offset:16384
	ds_read_b128 v[146:149], v186 offset:20480
	ds_read_b128 v[150:153], v187 offset:20480
	v_add3_u32 v186, v166, v164, s10
	v_add3_u32 v187, v166, v165, s10
	ds_read_b128 v[138:141], v186 offset:16384
	ds_read_b128 v[142:145], v187 offset:16384
	ds_read_b128 v[168:171], v186 offset:20480
	ds_read_b128 v[172:175], v187 offset:20480
	s_barrier
	s_waitcnt lgkmcnt(0)
	v_mfma_f32_32x32x16_bf16 v[66:81], v[130:133], v[176:179], v[66:81]
	v_mfma_f32_32x32x16_bf16 v[34:49], v[146:149], v[176:179], v[34:49]
	v_mfma_f32_32x32x16_bf16 v[66:81], v[134:137], v[180:183], v[66:81]
	v_mfma_f32_32x32x16_bf16 v[34:49], v[150:153], v[180:183], v[34:49]
	v_mfma_f32_32x32x16_bf16 v[66:81], v[138:141], v[192:195], v[66:81]
	v_mfma_f32_32x32x16_bf16 v[34:49], v[168:171], v[192:195], v[34:49]
	v_mfma_f32_32x32x16_bf16 v[66:81], v[142:145], v[196:199], v[66:81]
	v_mfma_f32_32x32x16_bf16 v[34:49], v[172:175], v[196:199], v[34:49]
	v_mfma_f32_32x32x16_bf16 v[18:33], v[130:133], v[200:203], v[18:33]
	v_mfma_f32_32x32x16_bf16 v[2:17], v[146:149], v[200:203], v[2:17]
	v_mfma_f32_32x32x16_bf16 v[18:33], v[134:137], v[228:231], v[18:33]
	v_mfma_f32_32x32x16_bf16 v[2:17], v[150:153], v[228:231], v[2:17]
	v_mfma_f32_32x32x16_bf16 v[18:33], v[138:141], v[232:235], v[18:33]
	v_mfma_f32_32x32x16_bf16 v[2:17], v[168:171], v[232:235], v[2:17]
	v_mfma_f32_32x32x16_bf16 v[18:33], v[142:145], v[236:239], v[18:33]
	v_mfma_f32_32x32x16_bf16 v[2:17], v[172:175], v[236:239], v[2:17]
	s_barrier
	s_cmp_eq_u32 s101, 0
	s_cbranch_scc0 .Lg8_ib_p1
	s_barrier
